# combined: IEEE f32 division sequences -> v_rcp_f32+v_mul (162 sites), dilcomb loads hoisted, phase-C balance k=5, nsa cmp K loads batched, phase-A GEMM via LDS-DMA
# speedup vs baseline: 1.0249x; 1.0220x over previous
; DI float lo16(unsigned w) { return __uint_as_float(w << 16); }
; DI float hi16(unsigned w) { return __uint_as_float(w & 0xffff0000u); }
; #define GLOAD(dst, kt_) _Pragma("unroll") for (int i = 0; i < NCH; ++i) { dst[i] = (i < NCHW) ? ldw(i, tid >> 3, (kt_) * 64 + (tid & 7) * 8) : ldx(i - NCHW, tid >> 3, (kt_) * 64 + (tid & 7) * 8); }
; #define LSTORE(src, base) _Pragma("unroll") for (int i = 0; i < NCH; ++i) { const int c = tid + 256 * i; *(u32x4*)((base) + (c >> 3) * 144 + (c & 7) * 16) = src[i]; }
; template <int WGN, int INS, int IMS, bool DB, class LdW, class LdX>
; DI void gemm_core(f32x16 (&acc)[INS][IMS], const int KT, LdW ldw, LdX ldx, char* lds, const int tid) {
;     ...
;     u32x4 pre[NCH];
;     GLOAD(pre, 0)
;     for (int kt = 0; kt < KT; ++kt) {
;       __syncthreads();
;       LSTORE(pre, lds)
;       __syncthreads();
;       if (kt + 1 < KT) { GLOAD(pre, kt + 1) }
;       if (INS >= 4) COMPUTE_FLAT(lds) else COMPUTE_PIPE(lds)
;     }
; DI void cmp_item(const Params& p, int l, int it, char* lds) {
;     ...
;   gemm_core<4, 2, 1, false>(acc, 32, [&](int i, int r0, int k) -> u32x4 { return *(const u32x4*)((W1 + i * 65536) + (unsigned)(r0 * 2048 + k)); },
;    [&](int i, int row, int k) -> u32x4 {
;     const int rr = mt * 32 + row, b = rr >> 7; int n = rr & 127; if (n > 126) n = 126;
;     const int l32 = k >> 6, d = k & 63;
;     const u32x4 raw = *(const u32x4*)(proj + ((size_t)b * S_ + 16 * n + l32) * NP + kvcol + d);
;     const f32x4 e0 = *(const f32x4*)(pe + l32 * 64 + d), e1 = *(const f32x4*)(pe + l32 * 64 + d + 4);
;     u32x4 o;
;     o[0] = pk2(lo16(raw[0]) + e0[0], hi16(raw[0]) + e0[1]); o[1] = pk2(lo16(raw[1]) + e0[2], hi16(raw[1]) + e0[3]);
;     o[2] = pk2(lo16(raw[2]) + e1[0], hi16(raw[2]) + e1[1]); o[3] = pk2(lo16(raw[3]) + e1[2], hi16(raw[3]) + e1[3]);
;     return o; }, lds, tid);
.LBB0_287:
	s_barrier
	ds_write_b128 v84, v[32:35]
	ds_write_b128 v85, v[36:39]
	ds_write_b128 v86, v[40:43]
	ds_write_b128 v87, v[44:47]
	s_waitcnt vmcnt(3)
	ds_write_b128 v88, v[48:51]
	s_waitcnt vmcnt(2)
	ds_write_b128 v89, v[52:55]
	s_waitcnt vmcnt(1)
	ds_write_b128 v90, v[56:59]
	s_waitcnt vmcnt(0)
	ds_write_b128 v91, v[60:63]
	ds_write_b128 v92, v[64:67]
	s_waitcnt lgkmcnt(0)
	s_barrier
	ds_read_b128 v[32:35], v83
	ds_read_b128 v[36:39], v82 offset:36864
	ds_read_b128 v[40:43], v83 offset:32
	ds_read_b128 v[44:47], v82 offset:36896
	s_waitcnt lgkmcnt(2)
	v_mfma_f32_32x32x16_bf16 v[16:31], v[32:35], v[36:39], v[16:31]
	ds_read_b128 v[32:35], v83 offset:4608
	ds_read_b128 v[48:51], v83 offset:4640
	v_add_u32_e32 v178, s20, v68
	v_lshlrev_b64 v[60:61], 1, v[178:179]
	v_lshl_add_u64 v[62:63], s[16:17], 0, v[60:61]
	s_mov_b64 s[22:23], 0x1a00
	s_add_i32 s20, s20, 64
	s_cmpk_lg_i32 s20, 0x800
	s_waitcnt lgkmcnt(1)
	v_mfma_f32_32x32x16_bf16 v[0:15], v[32:35], v[36:39], v[0:15]
	ds_read_b128 v[32:35], v83 offset:64
	v_lshl_add_u64 v[36:37], s[4:5], 0, v[60:61]
	v_lshl_add_u64 v[38:39], s[6:7], 0, v[60:61]
	v_mfma_f32_32x32x16_bf16 v[16:31], v[40:43], v[44:47], v[16:31]
	v_lshl_add_u64 v[40:41], s[8:9], 0, v[60:61]
	s_waitcnt lgkmcnt(1)
	v_mfma_f32_32x32x16_bf16 v[0:15], v[48:51], v[44:47], v[0:15]
	ds_read_b128 v[48:51], v82 offset:36928
	ds_read_b128 v[52:55], v83 offset:4672
	ds_read_b128 v[56:59], v83 offset:96
	ds_read_b128 v[64:67], v82 offset:36960
	v_lshl_add_u64 v[44:45], s[10:11], 0, v[60:61]
	s_waitcnt lgkmcnt(3)
	v_mfma_f32_32x32x16_bf16 v[16:31], v[32:35], v[48:51], v[16:31]
	global_load_dwordx4 v[32:35], v[36:37], off
	s_nop 0
	global_load_dwordx4 v[36:39], v[38:39], off
	s_nop 0
	global_load_dwordx4 v[94:97], v[70:71], off
	s_nop 0
	global_load_dwordx4 v[40:43], v[40:41], off
	s_nop 0
	global_load_dwordx4 v[44:47], v[44:45], off
	ds_read_b128 v[98:101], v83 offset:4704
	global_load_dwordx4 v[102:105], v[72:73], off offset:16
	global_load_dwordx4 v[106:109], v[72:73], off
	v_lshl_add_u64 v[70:71], v[70:71], 0, s[22:23]
	s_mov_b64 s[22:23], 0x100
	v_lshl_add_u64 v[72:73], v[72:73], 0, s[22:23]
	s_waitcnt lgkmcnt(3)
	v_mfma_f32_32x32x16_bf16 v[0:15], v[52:55], v[48:51], v[0:15]
	v_lshl_add_u64 v[48:49], s[12:13], 0, v[60:61]
	v_lshl_add_u64 v[52:53], s[14:15], 0, v[60:61]
	v_lshl_add_u64 v[60:61], s[18:19], 0, v[60:61]
	global_load_dwordx4 v[48:51], v[48:49], off
	s_nop 0
	global_load_dwordx4 v[52:55], v[52:53], off
	s_waitcnt lgkmcnt(1)
	v_mfma_f32_32x32x16_bf16 v[16:31], v[56:59], v[64:67], v[16:31]
	global_load_dwordx4 v[56:59], v[62:63], off
	s_nop 0
	global_load_dwordx4 v[60:63], v[60:61], off
	s_waitcnt lgkmcnt(0)
	v_mfma_f32_32x32x16_bf16 v[0:15], v[98:101], v[64:67], v[0:15]
	s_waitcnt vmcnt(8)
	v_lshlrev_b32_e32 v64, 16, v94
	v_and_b32_e32 v65, 0xffff0000, v94
	v_lshlrev_b32_e32 v66, 16, v95
	v_and_b32_e32 v67, 0xffff0000, v95
	v_lshlrev_b32_e32 v94, 16, v96
	v_and_b32_e32 v95, 0xffff0000, v96
	v_lshlrev_b32_e32 v96, 16, v97
	v_and_b32_e32 v97, 0xffff0000, v97
	s_waitcnt vmcnt(4)
	v_pk_add_f32 v[64:65], v[106:107], v[64:65]
	v_pk_add_f32 v[66:67], v[108:109], v[66:67]
	v_pk_add_f32 v[94:95], v[102:103], v[94:95]
	v_pk_add_f32 v[96:97], v[104:105], v[96:97]
	v_cvt_pk_bf16_f32 v64, v64, v65
	v_cvt_pk_bf16_f32 v65, v66, v67
	v_cvt_pk_bf16_f32 v66, v94, v95
	v_cvt_pk_bf16_f32 v67, v96, v97
	s_cbranch_scc1 .LBB0_287
	s_barrier
	ds_write_b128 v84, v[32:35]
	ds_write_b128 v85, v[36:39]
	ds_write_b128 v86, v[40:43]
	ds_write_b128 v87, v[44:47]
	s_waitcnt vmcnt(3)
	ds_write_b128 v88, v[48:51]
	s_waitcnt vmcnt(2)
	ds_write_b128 v89, v[52:55]
	s_waitcnt vmcnt(1)
	ds_write_b128 v90, v[56:59]
	s_waitcnt vmcnt(0)
	ds_write_b128 v91, v[60:63]
	ds_write_b128 v92, v[64:67]
	s_waitcnt lgkmcnt(0)
	s_barrier
	ds_read_b128 v[32:35], v83 offset:4608
	ds_read_b128 v[36:39], v83
	ds_read_b128 v[40:43], v83 offset:32
	ds_read_b128 v[44:47], v83 offset:4640
	ds_read_b128 v[48:51], v82 offset:36864
	ds_read_b128 v[52:55], v82 offset:36896
	s_waitcnt lgkmcnt(1)
	v_mfma_f32_32x32x16_bf16 v[16:31], v[36:39], v[48:51], v[16:31]
	s_lshl_b64 s[2:3], s[2:3], 15
	s_add_u32 s2, s0, s2
	s_addc_u32 s3, s1, s3
	v_bfe_u32 v56, v74, 5, 1
	v_lshlrev_b32_e32 v178, 3, v56
	s_waitcnt lgkmcnt(0)
	v_mfma_f32_32x32x16_bf16 v[16:31], v[40:43], v[52:55], v[16:31]
	v_mfma_f32_32x32x16_bf16 v[0:15], v[32:35], v[48:51], v[0:15]
	ds_read_b128 v[32:35], v83 offset:64
	ds_read_b128 v[36:39], v83 offset:4672
	ds_read_b128 v[48:51], v82 offset:36928
	s_waitcnt lgkmcnt(0)
	v_mfma_f32_32x32x16_bf16 v[16:31], v[32:35], v[48:51], v[16:31]
	v_mfma_f32_32x32x16_bf16 v[0:15], v[44:47], v[52:55], v[0:15]
	ds_read_b128 v[40:43], v83 offset:96
	ds_read_b128 v[44:47], v83 offset:4704
	ds_read_b128 v[52:55], v82 offset:36960
	s_waitcnt lgkmcnt(0)
; DI void cmp_item(const Params& p, int l, int it, char* lds) {
;     ...
;   const int lane = tid & 63, wid = tid >> 6, l31 = lane & 31, hi = lane >> 5;
; #pragma unroll
;   for (int a = 0; a < 2; ++a)
; #pragma unroll
;     for (int r = 0; r < 16; ++r) {
;       const float x = acc[a][0][r]; const float u = 0.7978845608028654f * (x + 0.044715f * x * x * x);
;       acc[a][0][r] = x / (1.f + __expf(-2.f * u));
;     }
	v_mfma_f32_32x32x16_bf16 v[16:31], v[40:43], v[52:55], v[16:31]
	v_mfma_f32_32x32x16_bf16 v[0:15], v[36:39], v[48:51], v[0:15]
	s_nop 10
	v_mul_f32_e32 v32, 0x3d372713, v16
	v_mul_f32_e32 v33, 0x3d372713, v17
	v_mul_f32_e32 v32, v16, v32
	v_mul_f32_e32 v33, v17, v33
	v_fma_f32 v32, v16, v32, v16
	v_fma_f32 v33, v17, v33, v17
	v_mul_f32_e32 v32, 0x3f4c422a, v32
	v_mul_f32_e32 v33, 0x3f4c422a, v33
	v_mul_f32_e32 v32, -2.0, v32
	v_mul_f32_e32 v33, -2.0, v33
	v_mul_f32_e32 v32, 0x3fb8aa3b, v32
	v_mul_f32_e32 v33, 0x3fb8aa3b, v33
	v_exp_f32_e32 v32, v32
	v_exp_f32_e32 v33, v33
	v_mfma_f32_32x32x16_bf16 v[0:15], v[44:47], v[52:55], v[0:15]
	v_add_f32_e64 v32, v32, 1.0
	v_add_f32_e64 v33, v33, 1.0
	s_nop 0
	v_rcp_f32_e32 v34, v33
	s_nop 0
	v_mul_f32_e32 v17, v17, v34
	s_nop 0
	v_rcp_f32_e32 v33, v32
	s_nop 0
	v_mul_f32_e32 v16, v16, v33
	v_mul_f32_e32 v32, 0x3d372713, v18
	v_mul_f32_e32 v33, 0x3d372713, v19
	v_mul_f32_e32 v32, v18, v32
	v_mul_f32_e32 v33, v19, v33
	v_fma_f32 v32, v18, v32, v18
	v_fma_f32 v33, v19, v33, v19
	v_mul_f32_e32 v32, 0x3f4c422a, v32
	v_mul_f32_e32 v33, 0x3f4c422a, v33
	v_mul_f32_e32 v32, -2.0, v32
	v_mul_f32_e32 v33, -2.0, v33
	v_mul_f32_e32 v32, 0x3fb8aa3b, v32
	v_mul_f32_e32 v33, 0x3fb8aa3b, v33
	v_exp_f32_e32 v32, v32
	v_exp_f32_e32 v33, v33
	s_nop 0
	v_pk_add_f32 v[32:33], v[32:33], 1.0 op_sel_hi:[1,0]
	s_nop 0
	s_nop 0
	v_rcp_f32_e32 v34, v33
	s_nop 0
	v_mul_f32_e32 v19, v19, v34
	s_nop 0
	v_rcp_f32_e32 v33, v32
	s_nop 0
	v_mul_f32_e32 v18, v18, v33
	v_mul_f32_e32 v32, 0x3d372713, v20
	v_mul_f32_e32 v33, 0x3d372713, v21
	v_mul_f32_e32 v32, v20, v32
	v_mul_f32_e32 v33, v21, v33
	v_fma_f32 v32, v20, v32, v20
	v_fma_f32 v33, v21, v33, v21
	v_mul_f32_e32 v32, 0x3f4c422a, v32
	v_mul_f32_e32 v33, 0x3f4c422a, v33
	v_mul_f32_e32 v32, -2.0, v32
	v_mul_f32_e32 v33, -2.0, v33
	v_mul_f32_e32 v32, 0x3fb8aa3b, v32
	v_mul_f32_e32 v33, 0x3fb8aa3b, v33
	v_exp_f32_e32 v32, v32
	v_exp_f32_e32 v33, v33
	s_nop 0
	v_pk_add_f32 v[32:33], v[32:33], 1.0 op_sel_hi:[1,0]
	s_nop 0
	s_nop 0
	v_rcp_f32_e32 v34, v33
	s_nop 0
	v_mul_f32_e32 v21, v21, v34
	s_nop 0
	v_rcp_f32_e32 v33, v32
	s_nop 0
	v_mul_f32_e32 v20, v20, v33
	v_mul_f32_e32 v32, 0x3d372713, v22
	v_mul_f32_e32 v33, 0x3d372713, v23
	v_mul_f32_e32 v32, v22, v32
	v_mul_f32_e32 v33, v23, v33
	v_fma_f32 v32, v22, v32, v22
	v_fma_f32 v33, v23, v33, v23
	v_mul_f32_e32 v32, 0x3f4c422a, v32
	v_mul_f32_e32 v33, 0x3f4c422a, v33
	v_mul_f32_e32 v32, -2.0, v32
	v_mul_f32_e32 v33, -2.0, v33
	v_mul_f32_e32 v32, 0x3fb8aa3b, v32
	v_mul_f32_e32 v33, 0x3fb8aa3b, v33
	v_exp_f32_e32 v32, v32
	v_exp_f32_e32 v33, v33
	s_nop 0
	v_pk_add_f32 v[32:33], v[32:33], 1.0 op_sel_hi:[1,0]
	s_nop 0
	s_nop 0
	v_rcp_f32_e32 v34, v33
	s_nop 0
	v_mul_f32_e32 v23, v23, v34
	s_nop 0
	v_rcp_f32_e32 v33, v32
	s_nop 0
	v_mul_f32_e32 v22, v22, v33
	v_mul_f32_e32 v32, 0x3d372713, v24
	v_mul_f32_e32 v33, 0x3d372713, v25
	v_mul_f32_e32 v32, v24, v32
	v_mul_f32_e32 v33, v25, v33
	v_fma_f32 v32, v24, v32, v24
	v_fma_f32 v33, v25, v33, v25
	v_mul_f32_e32 v32, 0x3f4c422a, v32
	v_mul_f32_e32 v33, 0x3f4c422a, v33
	v_mul_f32_e32 v32, -2.0, v32
	v_mul_f32_e32 v33, -2.0, v33
	v_mul_f32_e32 v32, 0x3fb8aa3b, v32
	v_mul_f32_e32 v33, 0x3fb8aa3b, v33
	v_exp_f32_e32 v32, v32
	v_exp_f32_e32 v33, v33
	s_nop 0
	v_pk_add_f32 v[34:35], v[32:33], 1.0 op_sel_hi:[1,0]
	s_nop 0
	s_nop 0
	v_rcp_f32_e32 v32, v35
	s_nop 0
	v_mul_f32_e32 v32, v25, v32
	s_nop 0
	v_rcp_f32_e32 v33, v34
	s_nop 0
	v_mul_f32_e32 v33, v24, v33
	v_mul_f32_e32 v24, 0x3d372713, v26
	v_mul_f32_e32 v25, 0x3d372713, v27
	v_mul_f32_e32 v24, v26, v24
	v_mul_f32_e32 v25, v27, v25
	v_fma_f32 v24, v26, v24, v26
	v_fma_f32 v25, v27, v25, v27
	v_mul_f32_e32 v24, 0x3f4c422a, v24
	v_mul_f32_e32 v25, 0x3f4c422a, v25
	v_mul_f32_e32 v24, -2.0, v24
	v_mul_f32_e32 v25, -2.0, v25
	v_mul_f32_e32 v24, 0x3fb8aa3b, v24
	v_mul_f32_e32 v25, 0x3fb8aa3b, v25
	v_exp_f32_e32 v24, v24
	v_exp_f32_e32 v25, v25
	v_cvt_pk_bf16_f32 v32, v33, v32
	v_pk_add_f32 v[24:25], v[24:25], 1.0 op_sel_hi:[1,0]
	s_nop 0
	s_nop 0
	v_rcp_f32_e32 v34, v25
	s_nop 0
	v_mul_f32_e32 v34, v27, v34
	s_nop 0
	v_rcp_f32_e32 v35, v24
	s_nop 0
	v_mul_f32_e32 v35, v26, v35
	v_mul_f32_e32 v24, 0x3d372713, v28
	v_mul_f32_e32 v25, 0x3d372713, v29
	v_mul_f32_e32 v24, v28, v24
	v_mul_f32_e32 v25, v29, v25
	v_fma_f32 v24, v28, v24, v28
	v_fma_f32 v25, v29, v25, v29
	v_mul_f32_e32 v24, 0x3f4c422a, v24
	v_mul_f32_e32 v25, 0x3f4c422a, v25
	v_mul_f32_e32 v24, -2.0, v24
	v_mul_f32_e32 v25, -2.0, v25
	v_mul_f32_e32 v24, 0x3fb8aa3b, v24
	v_mul_f32_e32 v25, 0x3fb8aa3b, v25
	v_exp_f32_e32 v24, v24
	v_exp_f32_e32 v25, v25
	v_cvt_pk_bf16_f32 v33, v35, v34
	v_pk_add_f32 v[24:25], v[24:25], 1.0 op_sel_hi:[1,0]
	s_nop 0
	s_nop 0
	v_rcp_f32_e32 v38, v25
	s_nop 0
	v_mul_f32_e32 v38, v29, v38
	s_nop 0
	v_rcp_f32_e32 v39, v24
	s_nop 0
	v_mul_f32_e32 v39, v28, v39
	v_mul_f32_e32 v24, 0x3d372713, v30
	v_mul_f32_e32 v25, 0x3d372713, v31
	v_mul_f32_e32 v24, v30, v24
	v_mul_f32_e32 v25, v31, v25
	v_fma_f32 v24, v30, v24, v30
	v_fma_f32 v25, v31, v25, v31
	v_mul_f32_e32 v24, 0x3f4c422a, v24
	v_mul_f32_e32 v25, 0x3f4c422a, v25
	v_mul_f32_e32 v24, -2.0, v24
	v_mul_f32_e32 v25, -2.0, v25
	v_mul_f32_e32 v24, 0x3fb8aa3b, v24
	v_mul_f32_e32 v25, 0x3fb8aa3b, v25
	v_exp_f32_e32 v24, v24
	v_exp_f32_e32 v25, v25
	v_cvt_pk_bf16_f32 v34, v39, v38
	v_pk_add_f32 v[24:25], v[24:25], 1.0 op_sel_hi:[1,0]
	s_nop 0
	s_nop 0
	v_rcp_f32_e32 v40, v25
	s_nop 0
	v_mul_f32_e32 v40, v31, v40
	s_nop 0
	v_rcp_f32_e32 v42, v24
	s_nop 0
	v_mul_f32_e32 v42, v30, v42
	v_mul_f32_e32 v24, 0x3d372713, v0
	v_mul_f32_e32 v25, 0x3d372713, v1
	v_mul_f32_e32 v24, v0, v24
	v_mul_f32_e32 v25, v1, v25
; #define MFMA(a, b, c) __builtin_amdgcn_mfma_f32_32x32x16_bf16((a), (b), (c), 0, 0, 0)
; DI void cmp_item(const Params& p, int l, int it, char* lds) {
;     ...
;       const float x = acc[a][0][r]; const float u = 0.7978845608028654f * (x + 0.044715f * x * x * x);
;       acc[a][0][r] = x / (1.f + __expf(-2.f * u));
;     }
;   f32x16 c2[2];
; #pragma unroll
;   for (int r = 0; r < 16; ++r) { c2[0][r] = 0.f; c2[1][r] = 0.f; }
; #pragma unroll
;   for (int in = 0; in < 2; ++in)
; #pragma unroll
;     for (int s2 = 0; s2 < 2; ++s2) {
;       const bf16x8 h0 = pack8(acc[in][0], s2);
; #pragma unroll
;       for (int dt = 0; dt < 2; ++dt) {
;         const u16* wp = W2 + (size_t)(dt * 32 + l31) * 256 + wid * 64 + in * 32 + 16 * s2 + 4 * hi;
;         const s16x4 lo = *(const s16x4*)wp, hh = *(const s16x4*)(wp + 8);
;         const bf16x8 wf = {lo[0], lo[1], lo[2], lo[3], hh[0], hh[1], hh[2], hh[3]};
;         c2[dt] = MFMA(wf, h0, c2[dt]);
	v_fma_f32 v24, v0, v24, v0
	v_fma_f32 v25, v1, v25, v1
	v_mul_f32_e32 v24, 0x3f4c422a, v24
	v_mul_f32_e32 v25, 0x3f4c422a, v25
	v_mul_f32_e32 v24, -2.0, v24
	v_mul_f32_e32 v25, -2.0, v25
	v_mul_f32_e32 v24, 0x3fb8aa3b, v24
	v_mul_f32_e32 v25, 0x3fb8aa3b, v25
	v_exp_f32_e32 v24, v24
	v_exp_f32_e32 v25, v25
	v_cvt_pk_bf16_f32 v35, v42, v40
	v_pk_add_f32 v[24:25], v[24:25], 1.0 op_sel_hi:[1,0]
	s_nop 0
	s_nop 0
	v_rcp_f32_e32 v41, v25
	s_nop 0
	v_mul_f32_e32 v41, v1, v41
	s_nop 0
	v_rcp_f32_e32 v43, v24
	s_nop 0
	v_mul_f32_e32 v43, v0, v43
	v_mul_f32_e32 v0, 0x3d372713, v2
	v_mul_f32_e32 v1, 0x3d372713, v3
	v_mul_f32_e32 v0, v2, v0
	v_mul_f32_e32 v1, v3, v1
	v_fma_f32 v0, v2, v0, v2
	v_fma_f32 v1, v3, v1, v3
	v_mul_f32_e32 v0, 0x3f4c422a, v0
	v_mul_f32_e32 v1, 0x3f4c422a, v1
	v_mul_f32_e32 v0, -2.0, v0
	v_mul_f32_e32 v1, -2.0, v1
	v_mul_f32_e32 v0, 0x3fb8aa3b, v0
	v_mul_f32_e32 v1, 0x3fb8aa3b, v1
	v_exp_f32_e32 v0, v0
	v_exp_f32_e32 v1, v1
	s_nop 0
	v_pk_add_f32 v[0:1], v[0:1], 1.0 op_sel_hi:[1,0]
	s_nop 0
	s_nop 0
	v_rcp_f32_e32 v44, v1
	s_nop 0
	v_mul_f32_e32 v44, v3, v44
	s_nop 0
	v_rcp_f32_e32 v45, v0
	s_nop 0
	v_mul_f32_e32 v45, v2, v45
	v_mul_f32_e32 v0, 0x3d372713, v4
	v_mul_f32_e32 v1, 0x3d372713, v5
	v_mul_f32_e32 v0, v4, v0
	v_mul_f32_e32 v1, v5, v1
	v_fma_f32 v0, v4, v0, v4
	v_fma_f32 v1, v5, v1, v5
	v_mul_f32_e32 v0, 0x3f4c422a, v0
	v_mul_f32_e32 v1, 0x3f4c422a, v1
	v_mul_f32_e32 v0, -2.0, v0
	v_mul_f32_e32 v1, -2.0, v1
	v_mul_f32_e32 v0, 0x3fb8aa3b, v0
	v_mul_f32_e32 v1, 0x3fb8aa3b, v1
	v_exp_f32_e32 v0, v0
	v_exp_f32_e32 v1, v1
	s_nop 0
	v_pk_add_f32 v[0:1], v[0:1], 1.0 op_sel_hi:[1,0]
	s_nop 0
	s_nop 0
	v_rcp_f32_e32 v46, v1
	s_nop 0
	v_mul_f32_e32 v46, v5, v46
	s_nop 0
	v_rcp_f32_e32 v47, v0
	s_nop 0
	v_mul_f32_e32 v47, v4, v47
	v_mul_f32_e32 v0, 0x3d372713, v6
	v_mul_f32_e32 v1, 0x3d372713, v7
	v_mul_f32_e32 v0, v6, v0
	v_mul_f32_e32 v1, v7, v1
	v_fma_f32 v0, v6, v0, v6
	v_fma_f32 v1, v7, v1, v7
	v_mul_f32_e32 v0, 0x3f4c422a, v0
	v_mul_f32_e32 v1, 0x3f4c422a, v1
	v_mul_f32_e32 v0, -2.0, v0
	v_mul_f32_e32 v1, -2.0, v1
	v_mul_f32_e32 v0, 0x3fb8aa3b, v0
	v_mul_f32_e32 v1, 0x3fb8aa3b, v1
	v_exp_f32_e32 v0, v0
	v_exp_f32_e32 v1, v1
	s_nop 0
	v_pk_add_f32 v[0:1], v[0:1], 1.0 op_sel_hi:[1,0]
	s_nop 0
	s_nop 0
	v_rcp_f32_e32 v48, v1
	s_nop 0
	v_mul_f32_e32 v48, v7, v48
	s_nop 0
	v_rcp_f32_e32 v50, v0
	s_nop 0
	v_mul_f32_e32 v50, v6, v50
	v_mul_f32_e32 v0, 0x3d372713, v8
	v_mul_f32_e32 v1, 0x3d372713, v9
	v_mul_f32_e32 v0, v8, v0
	v_mul_f32_e32 v1, v9, v1
	v_fma_f32 v0, v8, v0, v8
	v_fma_f32 v1, v9, v1, v9
	v_mul_f32_e32 v0, 0x3f4c422a, v0
	v_mul_f32_e32 v1, 0x3f4c422a, v1
	v_mul_f32_e32 v0, -2.0, v0
	v_mul_f32_e32 v1, -2.0, v1
	v_mul_f32_e32 v0, 0x3fb8aa3b, v0
	v_mul_f32_e32 v1, 0x3fb8aa3b, v1
	v_exp_f32_e32 v0, v0
	v_exp_f32_e32 v1, v1
	s_nop 0
	v_pk_add_f32 v[0:1], v[0:1], 1.0 op_sel_hi:[1,0]
	s_nop 0
	s_nop 0
	v_rcp_f32_e32 v49, v1
	s_nop 0
	v_mul_f32_e32 v49, v9, v49
	s_nop 0
	v_rcp_f32_e32 v51, v0
	s_nop 0
	v_mul_f32_e32 v51, v8, v51
	v_mul_f32_e32 v0, 0x3d372713, v10
	v_mul_f32_e32 v1, 0x3d372713, v11
	v_mul_f32_e32 v0, v10, v0
	v_mul_f32_e32 v1, v11, v1
	v_fma_f32 v0, v10, v0, v10
	v_fma_f32 v1, v11, v1, v11
	v_mul_f32_e32 v0, 0x3f4c422a, v0
	v_mul_f32_e32 v1, 0x3f4c422a, v1
	v_mul_f32_e32 v0, -2.0, v0
	v_mul_f32_e32 v1, -2.0, v1
	v_mul_f32_e32 v0, 0x3fb8aa3b, v0
	v_mul_f32_e32 v1, 0x3fb8aa3b, v1
	v_exp_f32_e32 v0, v0
	v_exp_f32_e32 v1, v1
	s_nop 0
	v_pk_add_f32 v[0:1], v[0:1], 1.0 op_sel_hi:[1,0]
	s_nop 0
	s_nop 0
	v_rcp_f32_e32 v52, v1
	s_nop 0
	v_mul_f32_e32 v52, v11, v52
	s_nop 0
	v_rcp_f32_e32 v53, v0
	s_nop 0
	v_mul_f32_e32 v53, v10, v53
	v_mul_f32_e32 v0, 0x3d372713, v12
	v_mul_f32_e32 v1, 0x3d372713, v13
	v_mul_f32_e32 v0, v12, v0
	v_mul_f32_e32 v1, v13, v1
	v_fma_f32 v0, v12, v0, v12
	v_fma_f32 v1, v13, v1, v13
	v_mul_f32_e32 v0, 0x3f4c422a, v0
	v_mul_f32_e32 v1, 0x3f4c422a, v1
	v_mul_f32_e32 v0, -2.0, v0
	v_mul_f32_e32 v1, -2.0, v1
	v_mul_f32_e32 v0, 0x3fb8aa3b, v0
	v_mul_f32_e32 v1, 0x3fb8aa3b, v1
	v_exp_f32_e32 v0, v0
	v_exp_f32_e32 v1, v1
	s_nop 0
	v_pk_add_f32 v[0:1], v[0:1], 1.0 op_sel_hi:[1,0]
	s_nop 0
	s_nop 0
	v_rcp_f32_e32 v54, v1
	s_nop 0
	v_mul_f32_e32 v54, v13, v54
	s_nop 0
	v_rcp_f32_e32 v55, v0
	s_nop 0
	v_mul_f32_e32 v55, v12, v55
	v_mul_f32_e32 v0, 0x3d372713, v14
	v_mul_f32_e32 v1, 0x3d372713, v15
	v_mul_f32_e32 v0, v14, v0
	v_mul_f32_e32 v1, v15, v1
	v_fma_f32 v0, v14, v0, v14
	v_fma_f32 v1, v15, v1, v15
	v_mul_f32_e32 v0, 0x3f4c422a, v0
	v_mul_f32_e32 v1, 0x3f4c422a, v1
	v_mul_f32_e32 v0, -2.0, v0
	v_mul_f32_e32 v1, -2.0, v1
	v_mul_f32_e32 v0, 0x3fb8aa3b, v0
	v_mul_f32_e32 v1, 0x3fb8aa3b, v1
	v_exp_f32_e32 v0, v0
	v_exp_f32_e32 v1, v1
	s_nop 0
	v_pk_add_f32 v[0:1], v[0:1], 1.0 op_sel_hi:[1,0]
	s_nop 0
	s_nop 0
	v_rcp_f32_e32 v57, v1
	s_nop 0
	v_mul_f32_e32 v57, v15, v57
	s_nop 0
	v_rcp_f32_e32 v64, v0
	s_nop 0
	v_mul_f32_e32 v64, v14, v64
	v_and_b32_e32 v0, 0xffffffc0, v74
	v_ashrrev_i32_e32 v1, 31, v0
	v_lshl_add_u64 v[0:1], v[0:1], 1, s[2:3]
	v_lshl_add_u64 v[0:1], v[0:1], 0, v[178:179]
	s_mov_b64 s[2:3], 0x2a00000
	v_lshl_add_u64 v[8:9], v[0:1], 0, s[2:3]
	v_lshlrev_b32_e32 v178, 9, v77
	v_lshl_add_u64 v[62:63], v[8:9], 0, v[178:179]
	global_load_dwordx2 v[4:5], v[62:63], off
	global_load_dwordx2 v[6:7], v[62:63], off offset:16
	v_or_b32_e32 v178, 0x4000, v178
	v_cvt_pk_bf16_f32 v0, v16, v17
	v_cvt_pk_bf16_f32 v1, v18, v19
	v_cvt_pk_bf16_f32 v2, v20, v21
	v_cvt_pk_bf16_f32 v3, v22, v23
	v_lshl_add_u64 v[36:37], v[8:9], 0, v[178:179]
	v_cmp_gt_u32_e32 vcc, 64, v74
	s_waitcnt vmcnt(0)
; #define MFMA(a, b, c) __builtin_amdgcn_mfma_f32_32x32x16_bf16((a), (b), (c), 0, 0, 0)
; DI int crow(int r, int hi) { return (r & 3) + 8 * (r >> 2) + 4 * hi; }
; DI void cmp_item(const Params& p, int l, int it, char* lds) {
;     ...
; #pragma unroll
;   for (int in = 0; in < 2; ++in)
; #pragma unroll
;     for (int s2 = 0; s2 < 2; ++s2) {
;       const bf16x8 h0 = pack8(acc[in][0], s2);
; #pragma unroll
;       for (int dt = 0; dt < 2; ++dt) {
;         const u16* wp = W2 + (size_t)(dt * 32 + l31) * 256 + wid * 64 + in * 32 + 16 * s2 + 4 * hi;
;         const s16x4 lo = *(const s16x4*)wp, hh = *(const s16x4*)(wp + 8);
;         const bf16x8 wf = {lo[0], lo[1], lo[2], lo[3], hh[0], hh[1], hh[2], hh[3]};
;         c2[dt] = MFMA(wf, h0, c2[dt]);
;       }
;     }
;   float* red = (float*)lds;
;   __syncthreads();
;   for (int w = 0; w < 4; ++w) {
;     if (wid == w) {
; #pragma unroll
;       for (int dt = 0; dt < 2; ++dt)
; #pragma unroll
;         for (int r = 0; r < 16; ++r) {
;           float* q = red + (dt * 32 + crow(r, hi)) * 32 + l31;
;           if (w == 0) *q = c2[dt][r]; else *q += c2[dt][r];
;         }
	v_mfma_f32_32x32x16_bf16 v[16:31], v[4:7], v[0:3], 0
	global_load_dwordx2 v[4:5], v[36:37], off
	global_load_dwordx2 v[6:7], v[36:37], off offset:16
	global_load_dwordx2 v[58:59], v[62:63], off offset:32
	global_load_dwordx2 v[60:61], v[62:63], off offset:48
	s_waitcnt vmcnt(0)
	v_mfma_f32_32x32x16_bf16 v[16:31], v[58:61], v[32:35], v[16:31]
	global_load_dwordx2 v[58:59], v[36:37], off offset:32
	global_load_dwordx2 v[60:61], v[36:37], off offset:48
	v_mfma_f32_32x32x16_bf16 v[0:15], v[4:7], v[0:3], 0
	s_waitcnt vmcnt(0)
	v_mfma_f32_32x32x16_bf16 v[0:15], v[58:61], v[32:35], v[0:15]
	v_cvt_pk_bf16_f32 v32, v43, v41
	global_load_dwordx2 v[38:39], v[62:63], off offset:64
	global_load_dwordx2 v[40:41], v[62:63], off offset:80
	v_cvt_pk_bf16_f32 v33, v45, v44
	v_cvt_pk_bf16_f32 v34, v47, v46
	v_cvt_pk_bf16_f32 v35, v50, v48
	s_waitcnt vmcnt(0)
	s_nop 0
	v_mfma_f32_32x32x16_bf16 v[16:31], v[38:41], v[32:35], v[16:31]
	global_load_dwordx2 v[38:39], v[36:37], off offset:64
	global_load_dwordx2 v[40:41], v[36:37], off offset:80
	s_waitcnt vmcnt(0)
	v_mfma_f32_32x32x16_bf16 v[0:15], v[38:41], v[32:35], v[0:15]
	global_load_dwordx2 v[38:39], v[62:63], off offset:96
	global_load_dwordx2 v[40:41], v[62:63], off offset:112
	v_cvt_pk_bf16_f32 v32, v51, v49
	v_cvt_pk_bf16_f32 v33, v53, v52
	v_cvt_pk_bf16_f32 v34, v55, v54
	v_cvt_pk_bf16_f32 v35, v64, v57
	s_waitcnt vmcnt(0)
	s_nop 0
	v_mfma_f32_32x32x16_bf16 v[16:31], v[38:41], v[32:35], v[16:31]
	global_load_dwordx2 v[38:39], v[36:37], off offset:96
	global_load_dwordx2 v[40:41], v[36:37], off offset:112
	s_barrier
	s_waitcnt vmcnt(0)
	v_mfma_f32_32x32x16_bf16 v[0:15], v[38:41], v[32:35], v[0:15]
	v_lshlrev_b32_e32 v32, 9, v56
	v_lshl_or_b32 v40, v77, 2, v32
	v_add_u32_e32 v39, 0x400, v40
	v_add_u32_e32 v38, 0x800, v40
	v_add_u32_e32 v37, 0xc00, v40
	v_add_u32_e32 v36, 0x1000, v40
	v_add_u32_e32 v35, 0x1400, v40
	v_add_u32_e32 v34, 0x1800, v40
	v_add_u32_e32 v33, 0x1c00, v40
	s_and_saveexec_b64 s[2:3], vcc
	s_cbranch_execz .LBB0_290
	ds_write2_b32 v40, v16, v17 offset1:32
	ds_write2_b32 v40, v18, v19 offset0:64 offset1:96
	ds_write2_b32 v39, v20, v21 offset1:32
	ds_write2_b32 v39, v22, v23 offset0:64 offset1:96
	ds_write2_b32 v38, v24, v25 offset1:32
	ds_write2_b32 v38, v26, v27 offset0:64 offset1:96
	ds_write2_b32 v37, v28, v29 offset1:32
	ds_write2_b32 v37, v30, v31 offset0:64 offset1:96
	ds_write2_b32 v36, v0, v1 offset1:32
	ds_write2_b32 v36, v2, v3 offset0:64 offset1:96
	ds_write2_b32 v35, v4, v5 offset1:32
	ds_write2_b32 v35, v6, v7 offset0:64 offset1:96
	ds_write2_b32 v34, v8, v9 offset1:32
	ds_write2_b32 v34, v10, v11 offset0:64 offset1:96
	ds_write2_b32 v33, v12, v13 offset1:32
	ds_write2_b32 v33, v14, v15 offset0:64 offset1:96

; #define MFMA(a, b, c) __builtin_amdgcn_mfma_f32_32x32x16_bf16((a), (b), (c), 0, 0, 0)
; DI int tidx() { int t = threadIdx.x; asm volatile("" : "+v"(t)); return t; }
; DI float bf2f(u16 v) { return __uint_as_float((unsigned)v << 16); }
; DI float sigmoidf_(float x) { return 1.f / (1.f + __expf(-x)); }
; DI void nsa_item(const Params& p, int it, char* lds) {
;     ...
;   const int b = it & 7, qt = 63 - (it >> 3), q0 = qt * 32;
;   const int tid = tidx(), lane = tid & 63, h = tid >> 6, l31 = lane & 31, hi = lane >> 5;
;   const u16* proj = (const u16*)(ws_ + OFF_PROJ);
;   const int t = q0 + l31; const size_t tok = (size_t)b * S_ + t;
;   bf16x8 qr[4];
; #pragma unroll
;   for (int s = 0; s < 4; ++s) qr[s] = *(const bf16x8*)(proj + tok * NP + C_AQ + h * 64 + 16 * s + 8 * hi);
;   char* ldsK = lds; char* ldsV = lds + 9216;
;   float* impS = (float*)(lds + 36864);
;   float* vals = (float*)(lds + 36864 + 16384);
;   unsigned* selm = (unsigned*)(lds + 73728 - 256);
;   int* jlist = (int*)(lds + 73728 - 128);
;   float* yst = (float*)(lds + 36864);
;   __syncthreads();
;   if (tid < 32) selm[tid] = 0u;
;   const float g0 = sigmoidf_(bf2f(proj[tok * NP + C_AG + 0 + h])), g1 = sigmoidf_(bf2f(proj[tok * NP + C_AG + 4 + h])), g2 = sigmoidf_(bf2f(proj[tok * NP + C_AG + 8 + h]));
;   f32x16 ya[2];
;   {
;     const u16* kc = (const u16*)(ws_ + OFF_KC); const u16* vct = (const u16*)(ws_ + OFF_VCT);
;     f32x16 sc[4];
;     const int nkb = (((q0 + 31 - 31) >> 4) >> 5) + 1;
; #pragma unroll
;     for (int kb = 0; kb < 4; ++kb) {
; #pragma unroll
;       for (int r = 0; r < 16; ++r) sc[kb][r] = 0.f;
;       if (kb < nkb) {
; #pragma unroll
;         for (int s = 0; s < 4; ++s) {
;           const bf16x8 kf = *(const bf16x8*)(kc + ((size_t)(b * 128 + kb * 32 + l31)) * 64 + 16 * s + 8 * hi);
;           sc[kb] = MFMA(kf, qr[s], sc[kb]);
;         }
;       }
;     }
.LBB0_346:
	s_mov_b64 s[0:1], 0
	s_add_u32 s10, s90, s0
	s_addc_u32 s11, s91, s1
	s_lshl_b32 s0, s13, 2
	s_andn2_b32 s0, s0, 31
	s_and_b32 s6, s13, 7
	s_sub_i32 s9, 0x7e0, s0
	v_mov_b32_e32 v159, v176
	s_add_u32 s14, s10, 0x4a50000
	v_and_b32_e32 v160, 31, v159
	s_addc_u32 s15, s11, 0
	v_or_b32_e32 v147, s9, v160
	s_lshl_b32 s80, s6, 11
	v_add_u32_e32 v146, s80, v147
	v_mov_b64_e32 v[0:1], s[14:15]
	v_and_b32_e32 v148, 0xffffffc0, v159
	v_bfe_u32 v152, v159, 5, 1
	v_mad_u64_u32 v[144:145], s[0:1], v146, s33, v[0:1]
	v_ashrrev_i32_e32 v149, 31, v148
	v_lshl_add_u64 v[0:1], v[148:149], 1, v[144:145]
	v_lshlrev_b32_e32 v178, 4, v152
	v_lshl_add_u64 v[0:1], v[0:1], 0, v[178:179]
	global_load_dwordx4 v[64:67], v[0:1], off
	global_load_dwordx4 v[68:71], v[0:1], off offset:32
	global_load_dwordx4 v[72:75], v[0:1], off offset:64
	global_load_dwordx4 v[76:79], v[0:1], off offset:96
	v_cmp_gt_i32_e64 s[16:17], 32, v159
	s_barrier
	s_and_saveexec_b64 s[0:1], s[16:17]
	v_lshl_add_u32 v0, v159, 2, v198
	ds_write_b32 v0, v179
	s_or_b64 exec, exec, s[0:1]
	v_ashrrev_i32_e32 v150, 6, v159
	v_ashrrev_i32_e32 v151, 31, v150
	v_lshl_add_u64 v[0:1], v[150:151], 1, v[144:145]
	v_add_co_u32_e32 v0, vcc, 0x1000, v0
	v_lshlrev_b32_e32 v80, 3, v152
	s_nop 0
	v_addc_co_u32_e32 v1, vcc, 0, v1, vcc
	global_load_ushort v151, v[0:1], off offset:2304
	global_load_ushort v154, v[0:1], off offset:2312
	global_load_ushort v155, v[0:1], off offset:2320
	v_lshlrev_b32_e32 v0, 1, v80
	v_mov_b32_e32 v1, v179
	v_lshlrev_b32_e32 v153, 7, v160
	v_lshl_add_u64 v[0:1], s[10:11], 0, v[0:1]
	v_lshl_or_b32 v2, s6, 14, v153
	v_mov_b32_e32 v3, v179
	v_lshl_add_u64 v[0:1], v[0:1], 0, v[2:3]
	s_mov_b64 s[0:1], 0xb350000
	v_lshl_add_u64 v[82:83], v[0:1], 0, s[0:1]
	global_load_dwordx4 v[88:91], v[82:83], off
	global_load_dwordx4 v[92:95], v[82:83], off offset:32
	global_load_dwordx4 v[96:99], v[82:83], off offset:64
	global_load_dwordx4 v[100:103], v[82:83], off offset:96
	s_cmpk_gt_u32 s9, 0x1ff
	s_cselect_b64 s[4:5], -1, 0
	s_cmpk_gt_u32 s9, 0x3ff
	s_cselect_b64 s[2:3], -1, 0
	s_cmpk_lt_u32 s9, 0x200
	s_cbranch_scc1 .Lnsa_ld_done
	v_add_co_u32_e32 v6, vcc, 0x1000, v82
	s_nop 1
	v_addc_co_u32_e32 v7, vcc, 0, v83, vcc
	global_load_dwordx4 v[104:107], v[6:7], off
	global_load_dwordx4 v[108:111], v[6:7], off offset:32
	global_load_dwordx4 v[112:115], v[6:7], off offset:64
	global_load_dwordx4 v[116:119], v[6:7], off offset:96
	s_cmpk_lt_u32 s9, 0x400
	s_cbranch_scc1 .Lnsa_ld_done
	v_add_co_u32_e32 v8, vcc, 0x2000, v82
	s_nop 1
	v_addc_co_u32_e32 v9, vcc, 0, v83, vcc
	global_load_dwordx4 v[120:123], v[8:9], off
	global_load_dwordx4 v[124:127], v[8:9], off offset:32
	global_load_dwordx4 v[128:131], v[8:9], off offset:64
	global_load_dwordx4 v[132:135], v[8:9], off offset:96
	s_cmpk_lt_u32 s9, 0x600
	s_cbranch_scc1 .Lnsa_ld_done
	v_add_co_u32_e32 v10, vcc, 0x3000, v82
	s_nop 1
	v_addc_co_u32_e32 v11, vcc, 0, v83, vcc
	global_load_dwordx4 v[136:139], v[10:11], off
	global_load_dwordx4 v[140:143], v[10:11], off offset:32
	global_load_dwordx4 v[202:205], v[10:11], off offset:64
	global_load_dwordx4 v[206:209], v[10:11], off offset:96
.Lnsa_ld_done:
	s_cmpk_gt_u32 s9, 0x5ff
	s_cselect_b64 s[0:1], -1, 0
	v_mov_b32_e32 v0, 0
	v_mov_b32_e32 v1, 0
	v_mov_b32_e32 v2, 0
	v_mov_b32_e32 v3, 0
	v_mov_b32_e32 v4, 0
	v_mov_b32_e32 v5, 0
	v_mov_b32_e32 v6, 0
	v_mov_b32_e32 v7, 0
	v_mov_b32_e32 v8, 0
	v_mov_b32_e32 v9, 0
	v_mov_b32_e32 v10, 0
	v_mov_b32_e32 v11, 0
	v_mov_b32_e32 v12, 0
	v_mov_b32_e32 v13, 0
	v_mov_b32_e32 v14, 0
	v_mov_b32_e32 v15, 0
	v_mov_b32_e32 v16, 0
	v_mov_b32_e32 v17, 0
	v_mov_b32_e32 v18, 0
	v_mov_b32_e32 v19, 0
	v_mov_b32_e32 v20, 0
	v_mov_b32_e32 v21, 0
	v_mov_b32_e32 v22, 0
	v_mov_b32_e32 v23, 0
	v_mov_b32_e32 v24, 0
	v_mov_b32_e32 v25, 0
	v_mov_b32_e32 v26, 0
	v_mov_b32_e32 v27, 0
	v_mov_b32_e32 v28, 0
	v_mov_b32_e32 v29, 0
	v_mov_b32_e32 v30, 0
	v_mov_b32_e32 v31, 0
	v_mov_b32_e32 v32, 0
	v_mov_b32_e32 v33, 0
	v_mov_b32_e32 v34, 0
	v_mov_b32_e32 v35, 0
	v_mov_b32_e32 v36, 0
	v_mov_b32_e32 v37, 0
	v_mov_b32_e32 v38, 0
	v_mov_b32_e32 v39, 0
	v_mov_b32_e32 v40, 0
	v_mov_b32_e32 v41, 0
	v_mov_b32_e32 v42, 0
	v_mov_b32_e32 v43, 0
	v_mov_b32_e32 v44, 0
	v_mov_b32_e32 v45, 0
	v_mov_b32_e32 v46, 0
	v_mov_b32_e32 v47, 0
	s_waitcnt vmcnt(0)
	v_mfma_f32_32x32x16_bf16 v[48:63], v[88:91], v[64:67], 0
	v_mfma_f32_32x32x16_bf16 v[48:63], v[92:95], v[68:71], v[48:63]
	v_mfma_f32_32x32x16_bf16 v[48:63], v[96:99], v[72:75], v[48:63]
	v_mfma_f32_32x32x16_bf16 v[48:63], v[100:103], v[76:79], v[48:63]
	s_cmpk_lt_u32 s9, 0x200
	s_cbranch_scc1 .LBB0_354
	v_mfma_f32_32x32x16_bf16 v[32:47], v[104:107], v[64:67], 0
	v_mfma_f32_32x32x16_bf16 v[32:47], v[108:111], v[68:71], v[32:47]
	v_mfma_f32_32x32x16_bf16 v[32:47], v[112:115], v[72:75], v[32:47]
	v_mfma_f32_32x32x16_bf16 v[32:47], v[116:119], v[76:79], v[32:47]
	s_cmpk_lt_u32 s9, 0x400
	s_cbranch_scc1 .LBB0_354
	v_mfma_f32_32x32x16_bf16 v[16:31], v[120:123], v[64:67], 0
	v_mfma_f32_32x32x16_bf16 v[16:31], v[124:127], v[68:71], v[16:31]
	v_mfma_f32_32x32x16_bf16 v[16:31], v[128:131], v[72:75], v[16:31]
	v_mfma_f32_32x32x16_bf16 v[16:31], v[132:135], v[76:79], v[16:31]
	s_cmpk_lt_u32 s9, 0x600
	s_cbranch_scc1 .LBB0_354
	v_mfma_f32_32x32x16_bf16 v[0:15], v[136:139], v[64:67], 0
	v_mfma_f32_32x32x16_bf16 v[0:15], v[140:143], v[68:71], v[0:15]
	v_mfma_f32_32x32x16_bf16 v[0:15], v[202:205], v[72:75], v[0:15]
	v_mfma_f32_32x32x16_bf16 v[0:15], v[206:209], v[76:79], v[0:15]

; DI int crow(int r, int hi) { return (r & 3) + 8 * (r >> 2) + 4 * hi; }
; DI void nsa_item(const Params& p, int it, char* lds) {
;     ...
;     const int nv = (t >= 31) ? ((t - 31) >> 4) : -1;
;     float mx = NEGB;
; #pragma unroll
;     for (int kb = 0; kb < 4; ++kb)
; #pragma unroll
;       for (int r = 0; r < 16; ++r) { const int n = 32 * kb + crow(r, hi); const float v = (n <= nv) ? sc[kb][r] * C2 : NEGB; sc[kb][r] = v; mx = fmaxf(mx, v); }
;     mx = fmaxf(mx, __shfl_xor(mx, 32, 64));
.LBB0_380:
	v_subrev_u32_e32 v149, 31, v147
	v_lshrrev_b32_e32 v149, 4, v149
	v_cmp_lt_i32_e32 vcc, 30, v147
	v_mul_f32_e32 v48, 0x3e38aa3b, v48
	v_mul_f32_e32 v49, 0x3e38aa3b, v49
	v_cndmask_b32_e32 v158, -1, v149, vcc
	v_sub_u32_e32 v149, v158, v156
	v_cmp_gt_i32_e64 s[48:49], 0, v149
	v_cmp_gt_i32_e64 s[50:51], 1, v149
	s_mov_b32 s0, 0xf149f2ca
	v_cndmask_b32_e64 v48, v48, v194, s[48:49]
	v_cndmask_b32_e64 v49, v49, v194, s[50:51]
	v_mul_f32_e32 v50, 0x3e38aa3b, v50
	v_cmp_gt_i32_e64 s[36:37], 2, v149
	v_mul_f32_e32 v51, 0x3e38aa3b, v51
	v_cmp_gt_i32_e64 s[34:35], 3, v149
	v_max3_f32 v157, v48, s0, v49
	v_cndmask_b32_e64 v50, v50, v194, s[36:37]
	v_cndmask_b32_e64 v51, v51, v194, s[34:35]
	v_mul_f32_e32 v52, 0x3e38aa3b, v52
	v_cmp_gt_i32_e64 s[42:43], 8, v149
	v_mul_f32_e32 v53, 0x3e38aa3b, v53
	v_cmp_gt_i32_e64 s[38:39], 9, v149
	v_max3_f32 v157, v157, v50, v51
	v_cndmask_b32_e64 v52, v52, v194, s[42:43]
	v_cndmask_b32_e64 v53, v53, v194, s[38:39]
	v_mul_f32_e32 v54, 0x3e38aa3b, v54
	v_cmp_gt_i32_e64 s[30:31], 10, v149
	v_mul_f32_e32 v55, 0x3e38aa3b, v55
	v_cmp_gt_i32_e64 s[44:45], 11, v149
	v_max3_f32 v157, v157, v52, v53
	v_cndmask_b32_e64 v54, v54, v194, s[30:31]
	v_cndmask_b32_e64 v55, v55, v194, s[44:45]
	v_mul_f32_e32 v56, 0x3e38aa3b, v56
	v_cmp_gt_i32_e64 s[26:27], 16, v149
	v_mul_f32_e32 v57, 0x3e38aa3b, v57
	v_cmp_gt_i32_e64 s[28:29], 17, v149
	v_max3_f32 v157, v157, v54, v55
	v_cndmask_b32_e64 v56, v56, v194, s[26:27]
	v_cndmask_b32_e64 v57, v57, v194, s[28:29]
	v_mul_f32_e32 v58, 0x3e38aa3b, v58
	v_cmp_gt_i32_e64 s[22:23], 18, v149
	v_mul_f32_e32 v59, 0x3e38aa3b, v59
	v_cmp_gt_i32_e64 s[24:25], 19, v149
	v_max3_f32 v157, v157, v56, v57
	v_cndmask_b32_e64 v58, v58, v194, s[22:23]
	v_cndmask_b32_e64 v59, v59, v194, s[24:25]
	v_mul_f32_e32 v60, 0x3e38aa3b, v60
	v_cmp_gt_i32_e64 s[16:17], 24, v149
	v_mul_f32_e32 v61, 0x3e38aa3b, v61
	v_cmp_gt_i32_e64 s[18:19], 25, v149
	v_max3_f32 v157, v157, v58, v59
	v_cndmask_b32_e64 v60, v60, v194, s[16:17]
	v_cndmask_b32_e64 v61, v61, v194, s[18:19]
	v_mul_f32_e32 v62, 0x3e38aa3b, v62
	v_cmp_gt_i32_e64 s[10:11], 26, v149
	v_mul_f32_e32 v63, 0x3e38aa3b, v63
	v_cmp_gt_i32_e64 s[12:13], 27, v149
	v_max3_f32 v157, v157, v60, v61
	v_cndmask_b32_e64 v62, v62, v194, s[10:11]
	v_cndmask_b32_e64 v63, v63, v194, s[12:13]
	v_max3_f32 v149, v157, v62, v63
	v_or_b32_e32 v157, 32, v156
	v_sub_u32_e32 v161, v158, v157
	v_mul_f32_e32 v34, 0x3e38aa3b, v34
	v_cmp_gt_i32_e64 s[74:75], 2, v161
	v_cmp_gt_i32_e64 s[96:97], 3, v161
	v_cmp_gt_i32_e64 s[94:95], 8, v161
	v_cndmask_b32_e64 v163, v34, v194, s[74:75]
	v_mul_f32_e32 v34, 0x3e38aa3b, v35
	v_cndmask_b32_e64 v164, v34, v194, s[96:97]
	v_mul_f32_e32 v34, 0x3e38aa3b, v36
	v_cndmask_b32_e64 v165, v34, v194, s[94:95]
	v_mul_f32_e32 v34, 0x3e38aa3b, v37
	v_cmp_gt_i32_e64 s[92:93], 9, v161
	v_cmp_gt_i32_e64 s[0:1], 10, v161
	v_cmp_gt_i32_e64 s[2:3], 25, v161
	v_cndmask_b32_e64 v166, v34, v194, s[92:93]
	v_mul_f32_e32 v34, 0x3e38aa3b, v38
	v_writelane_b32 v234, s0, 51
	v_mul_f32_e32 v16, 0x3e38aa3b, v16
	v_cmp_gt_i32_e64 s[6:7], 0, v161
	v_writelane_b32 v234, s1, 52
	v_cndmask_b32_e64 v167, v34, v194, s[0:1]
	v_cmp_gt_i32_e64 s[0:1], 11, v161
	v_mul_f32_e32 v34, 0x3e38aa3b, v39
	v_cmp_gt_i32_e64 s[72:73], 1, v161
	v_writelane_b32 v234, s0, 53
	v_mul_f32_e32 v32, 0x3e38aa3b, v32
	v_mul_f32_e32 v33, 0x3e38aa3b, v33
	v_writelane_b32 v234, s1, 54
	v_cndmask_b32_e64 v39, v34, v194, s[0:1]
	v_cmp_gt_i32_e64 s[0:1], 16, v161
	v_mul_f32_e32 v34, 0x3e38aa3b, v40
	v_cndmask_b32_e64 v32, v32, v194, s[6:7]
	v_writelane_b32 v234, s0, 55
	v_cndmask_b32_e64 v162, v33, v194, s[72:73]
	v_max3_f32 v33, v149, v32, v162
	v_writelane_b32 v234, s1, 56
	v_cndmask_b32_e64 v40, v34, v194, s[0:1]
	v_cmp_gt_i32_e64 s[0:1], 17, v161
	v_mul_f32_e32 v34, 0x3e38aa3b, v41
	v_max3_f32 v33, v33, v163, v164
	v_writelane_b32 v234, s0, 57
	v_max3_f32 v33, v33, v165, v166
	v_max3_f32 v33, v33, v167, v39
	v_writelane_b32 v234, s1, 58
	v_cndmask_b32_e64 v41, v34, v194, s[0:1]
	v_cmp_gt_i32_e64 s[0:1], 18, v161
	v_mul_f32_e32 v34, 0x3e38aa3b, v42
	v_max3_f32 v33, v33, v40, v41
	v_writelane_b32 v234, s0, 59
	v_mul_f32_e32 v0, 0x3e38aa3b, v0
	s_nop 0
	v_writelane_b32 v234, s1, 60
	v_cndmask_b32_e64 v42, v34, v194, s[0:1]
	v_cmp_gt_i32_e64 s[0:1], 19, v161
	v_mul_f32_e32 v34, 0x3e38aa3b, v43
	s_nop 0
	v_writelane_b32 v234, s0, 61
	s_nop 1
	v_writelane_b32 v234, s1, 62
	v_cndmask_b32_e64 v168, v34, v194, s[0:1]
	v_cmp_gt_i32_e64 s[0:1], 24, v161
	v_mul_f32_e32 v34, 0x3e38aa3b, v44
	v_max3_f32 v33, v33, v42, v168
	v_writelane_b32 v234, s0, 63
	s_nop 1
	v_writelane_b32 v233, s1, 0
	v_cndmask_b32_e64 v169, v34, v194, s[0:1]
	v_mul_f32_e32 v34, 0x3e38aa3b, v45
	v_cmp_gt_i32_e64 s[0:1], 26, v161
	v_cndmask_b32_e64 v45, v34, v194, s[2:3]
	v_mul_f32_e32 v34, 0x3e38aa3b, v46
	v_writelane_b32 v233, s0, 1
	v_max3_f32 v33, v33, v169, v45
	s_nop 0
	v_writelane_b32 v233, s1, 2
	v_cndmask_b32_e64 v46, v34, v194, s[0:1]
	v_mul_f32_e32 v34, 0x3e38aa3b, v47
	v_cmp_gt_i32_e64 s[0:1], 27, v161
	s_nop 1
	v_writelane_b32 v233, s0, 3
	s_nop 1
	v_cndmask_b32_e64 v47, v34, v194, s[0:1]
	v_or_b32_e32 v34, 64, v156
	v_sub_u32_e32 v34, v158, v34
	v_writelane_b32 v233, s1, 4
	v_cmp_gt_i32_e64 s[0:1], 0, v34
	v_max3_f32 v33, v33, v46, v47
	s_nop 0
	v_writelane_b32 v233, s0, 5
	s_nop 1
	v_writelane_b32 v233, s1, 6
	v_cndmask_b32_e64 v161, v16, v194, s[0:1]
	v_cmp_gt_i32_e64 s[0:1], 1, v34
	v_mul_f32_e32 v16, 0x3e38aa3b, v17
	v_mul_f32_e32 v17, 0x3e38aa3b, v18
	v_writelane_b32 v233, s0, 7
	v_xor_b32_e32 v18, 32, v195
	s_nop 0
	v_writelane_b32 v233, s1, 8
	v_cndmask_b32_e64 v170, v16, v194, s[0:1]
	v_cmp_gt_i32_e64 s[0:1], 2, v34
; DI int crow(int r, int hi) { return (r & 3) + 8 * (r >> 2) + 4 * hi; }
; DI void nsa_item(const Params& p, int it, char* lds) {
;     ...
;     for (int kb = 0; kb < 4; ++kb)
; #pragma unroll
;       for (int r = 0; r < 16; ++r) { const int n = 32 * kb + crow(r, hi); const float v = (n <= nv) ? sc[kb][r] * C2 : NEGB; sc[kb][r] = v; mx = fmaxf(mx, v); }
;     mx = fmaxf(mx, __shfl_xor(mx, 32, 64));
	v_max3_f32 v16, v33, v161, v170
	s_nop 0
	v_writelane_b32 v233, s0, 9
	s_nop 1
	v_writelane_b32 v233, s1, 10
	v_cndmask_b32_e64 v171, v17, v194, s[0:1]
	v_cmp_gt_i32_e64 s[0:1], 3, v34
	v_mul_f32_e32 v17, 0x3e38aa3b, v19
	s_nop 0
	v_writelane_b32 v233, s0, 11
	s_nop 1
	v_writelane_b32 v233, s1, 12
	v_cndmask_b32_e64 v19, v17, v194, s[0:1]
	v_cmp_gt_i32_e64 s[0:1], 8, v34
	v_mul_f32_e32 v17, 0x3e38aa3b, v20
	v_max3_f32 v16, v16, v171, v19
	v_writelane_b32 v233, s0, 13
	s_nop 1
	v_writelane_b32 v233, s1, 14
	v_cndmask_b32_e64 v20, v17, v194, s[0:1]
	v_cmp_gt_i32_e64 s[0:1], 9, v34
	v_mul_f32_e32 v17, 0x3e38aa3b, v21
	s_nop 0
	v_writelane_b32 v233, s0, 15
	s_nop 1
	v_writelane_b32 v233, s1, 16
	v_cndmask_b32_e64 v21, v17, v194, s[0:1]
	v_cmp_gt_i32_e64 s[0:1], 10, v34
	v_mul_f32_e32 v17, 0x3e38aa3b, v22
	v_max3_f32 v16, v16, v20, v21
	v_writelane_b32 v233, s0, 17
	s_nop 1
	v_writelane_b32 v233, s1, 18
	v_cndmask_b32_e64 v22, v17, v194, s[0:1]
	v_cmp_gt_i32_e64 s[0:1], 11, v34
	v_mul_f32_e32 v17, 0x3e38aa3b, v23
	s_nop 0
	v_writelane_b32 v233, s0, 19
	s_nop 1
	v_writelane_b32 v233, s1, 20
	v_cndmask_b32_e64 v23, v17, v194, s[0:1]
	v_cmp_gt_i32_e64 s[0:1], 16, v34
	v_mul_f32_e32 v17, 0x3e38aa3b, v24
	v_max3_f32 v16, v16, v22, v23
	v_writelane_b32 v233, s0, 21
	s_nop 1
	v_writelane_b32 v233, s1, 22
	v_cndmask_b32_e64 v24, v17, v194, s[0:1]
	v_cmp_gt_i32_e64 s[0:1], 17, v34
	v_mul_f32_e32 v17, 0x3e38aa3b, v25
	s_nop 0
	v_writelane_b32 v233, s0, 23
	s_nop 1
	v_writelane_b32 v233, s1, 24
	v_cndmask_b32_e64 v25, v17, v194, s[0:1]
	v_cmp_gt_i32_e64 s[0:1], 18, v34
	v_mul_f32_e32 v17, 0x3e38aa3b, v26
	v_max3_f32 v16, v16, v24, v25
	v_writelane_b32 v233, s0, 25
	s_nop 1
	v_writelane_b32 v233, s1, 26
	v_cndmask_b32_e64 v26, v17, v194, s[0:1]
	v_cmp_gt_i32_e64 s[0:1], 19, v34
	v_mul_f32_e32 v17, 0x3e38aa3b, v27
	s_nop 0
	v_writelane_b32 v233, s0, 27
	s_nop 1
	v_writelane_b32 v233, s1, 28
	v_cndmask_b32_e64 v27, v17, v194, s[0:1]
	v_cmp_gt_i32_e64 s[0:1], 24, v34
	v_mul_f32_e32 v17, 0x3e38aa3b, v28
	v_max3_f32 v16, v16, v26, v27
	v_writelane_b32 v233, s0, 29
	s_nop 1
	v_writelane_b32 v233, s1, 30
	v_cndmask_b32_e64 v28, v17, v194, s[0:1]
	v_mul_f32_e32 v17, 0x3e38aa3b, v29
	v_cmp_gt_i32_e64 s[0:1], 25, v34
	s_nop 1
	v_writelane_b32 v233, s0, 31
	s_nop 1
	v_cndmask_b32_e64 v29, v17, v194, s[0:1]
	v_mul_f32_e32 v17, 0x3e38aa3b, v30
	v_and_b32_e32 v30, 64, v195
	v_add_u32_e32 v149, 64, v30
	v_writelane_b32 v233, s1, 32
	v_cmp_lt_i32_e32 vcc, v18, v149
	v_cmp_gt_i32_e64 s[0:1], 26, v34
	v_max3_f32 v16, v16, v28, v29
	v_cndmask_b32_e32 v18, v195, v18, vcc
	v_cndmask_b32_e64 v30, v17, v194, s[0:1]
	v_mul_f32_e32 v17, 0x3e38aa3b, v31
	v_cmp_gt_i32_e32 vcc, 27, v34
	s_nop 1
	v_cndmask_b32_e32 v31, v17, v194, vcc
	v_or_b32_e32 v17, 0x60, v156
	v_sub_u32_e32 v17, v158, v17
	v_cmp_gt_i32_e64 s[8:9], 0, v17
	v_cmp_gt_i32_e64 s[20:21], 2, v17
	v_cmp_gt_i32_e64 s[14:15], 3, v17
	v_cndmask_b32_e64 v172, v0, v194, s[8:9]
	v_mul_f32_e32 v0, 0x3e38aa3b, v1
	v_mul_f32_e32 v1, 0x3e38aa3b, v2
	v_cndmask_b32_e64 v174, v1, v194, s[20:21]
	v_mul_f32_e32 v1, 0x3e38aa3b, v3
	v_cndmask_b32_e64 v175, v1, v194, s[14:15]
	v_mul_f32_e32 v1, 0x3e38aa3b, v4
	v_cmp_gt_i32_e64 s[46:47], 8, v17
	v_cmp_gt_i32_e64 s[40:41], 9, v17
	v_cmp_gt_i32_e64 s[54:55], 10, v17
	v_cndmask_b32_e64 v181, v1, v194, s[46:47]
	v_mul_f32_e32 v1, 0x3e38aa3b, v5
	v_cndmask_b32_e64 v183, v1, v194, s[40:41]
	v_mul_f32_e32 v1, 0x3e38aa3b, v6
	v_cndmask_b32_e64 v6, v1, v194, s[54:55]
	v_mul_f32_e32 v1, 0x3e38aa3b, v7
	v_cmp_gt_i32_e64 s[52:53], 11, v17
	v_cmp_gt_i32_e64 s[4:5], 1, v17
	v_cmp_gt_i32_e64 s[58:59], 16, v17
	v_cndmask_b32_e64 v7, v1, v194, s[52:53]
	v_mul_f32_e32 v1, 0x3e38aa3b, v8
	v_max3_f32 v16, v16, v30, v31
	v_cndmask_b32_e64 v173, v0, v194, s[4:5]
	v_cndmask_b32_e64 v8, v1, v194, s[58:59]
	v_mul_f32_e32 v1, 0x3e38aa3b, v9
	v_cmp_gt_i32_e64 s[56:57], 17, v17
	v_max3_f32 v0, v16, v172, v173
	v_cmp_gt_i32_e64 s[62:63], 18, v17
	v_cndmask_b32_e64 v9, v1, v194, s[56:57]
	v_mul_f32_e32 v1, 0x3e38aa3b, v10
	v_max3_f32 v0, v0, v174, v175
	v_cndmask_b32_e64 v10, v1, v194, s[62:63]
	v_mul_f32_e32 v1, 0x3e38aa3b, v11
	v_cmp_gt_i32_e64 s[60:61], 19, v17
	v_max3_f32 v0, v0, v181, v183
	v_cmp_gt_i32_e64 s[66:67], 24, v17
	v_cndmask_b32_e64 v11, v1, v194, s[60:61]
	v_mul_f32_e32 v1, 0x3e38aa3b, v12
	v_max3_f32 v0, v0, v6, v7
	v_cndmask_b32_e64 v12, v1, v194, s[66:67]
	v_mul_f32_e32 v1, 0x3e38aa3b, v13
	v_cmp_gt_i32_e64 s[64:65], 25, v17
	v_max3_f32 v0, v0, v8, v9
	v_cmp_gt_i32_e64 s[70:71], 26, v17
	v_cndmask_b32_e64 v13, v1, v194, s[64:65]
	v_mul_f32_e32 v1, 0x3e38aa3b, v14
	v_max3_f32 v0, v0, v10, v11
	v_cndmask_b32_e64 v14, v1, v194, s[70:71]
	v_mul_f32_e32 v1, 0x3e38aa3b, v15
	v_cmp_gt_i32_e64 s[68:69], 27, v17
	v_max3_f32 v0, v0, v12, v13
	v_lshlrev_b32_e32 v158, 2, v18
	v_cndmask_b32_e64 v15, v1, v194, s[68:69]
	v_max3_f32 v0, v0, v14, v15
	ds_bpermute_b32 v1, v158, v0
	s_waitcnt lgkmcnt(0)
; DI int crow(int r, int hi) { return (r & 3) + 8 * (r >> 2) + 4 * hi; }
; DI float ex2(float x) { return __builtin_amdgcn_exp2f(x); }
; DI void nsa_item(const Params& p, int it, char* lds) {
;     ...
;     mx = fmaxf(mx, __shfl_xor(mx, 32, 64));
;     float sum = 0.f;
; #pragma unroll
;     for (int kb = 0; kb < 4; ++kb)
; #pragma unroll
;       for (int r = 0; r < 16; ++r) { const int n = 32 * kb + crow(r, hi); const float e = (n <= nv) ? ex2(sc[kb][r] - mx) : 0.f; sc[kb][r] = e; sum += e; }
	v_max_f32_e32 v1, v1, v1
	v_max_f32_e32 v185, v0, v1
	v_sub_f32_e32 v1, v49, v185
	v_exp_f32_e32 v1, v1
	v_sub_f32_e32 v0, v48, v185
	v_exp_f32_e32 v0, v0
	v_sub_f32_e32 v4, v53, v185
	v_cndmask_b32_e64 v186, v1, 0, s[50:51]
	v_sub_f32_e32 v1, v50, v185
	v_exp_f32_e32 v4, v4
	v_exp_f32_e32 v1, v1
	v_sub_f32_e32 v2, v51, v185
	v_exp_f32_e32 v2, v2
	v_sub_f32_e32 v3, v52, v185
	v_cndmask_b32_e64 v0, v0, 0, s[48:49]
	v_exp_f32_e32 v3, v3
	v_sub_f32_e32 v17, v57, v185
	v_cndmask_b32_e64 v187, v4, 0, s[38:39]
	v_sub_f32_e32 v4, v54, v185
	v_exp_f32_e32 v17, v17
	v_add_f32_e32 v36, 0, v0
	v_cndmask_b32_e64 v1, v1, 0, s[36:37]
	v_exp_f32_e32 v4, v4
	v_sub_f32_e32 v5, v55, v185
	v_add_f32_e32 v36, v186, v36
	v_cndmask_b32_e64 v2, v2, 0, s[34:35]
	v_exp_f32_e32 v5, v5
	v_sub_f32_e32 v16, v56, v185
	v_add_f32_e32 v36, v1, v36
	v_cndmask_b32_e64 v3, v3, 0, s[42:43]
	v_exp_f32_e32 v16, v16
	v_sub_f32_e32 v34, v61, v185
	v_add_f32_e32 v36, v2, v36
	v_cndmask_b32_e64 v202, v17, 0, s[28:29]
	v_sub_f32_e32 v17, v58, v185
	v_exp_f32_e32 v34, v34
	v_add_f32_e32 v36, v3, v36
	v_cndmask_b32_e64 v4, v4, 0, s[30:31]
	v_exp_f32_e32 v17, v17
	v_sub_f32_e32 v18, v59, v185
	v_add_f32_e32 v36, v187, v36
	v_cndmask_b32_e64 v5, v5, 0, s[44:45]
	v_exp_f32_e32 v18, v18
	v_sub_f32_e32 v33, v60, v185
	v_add_f32_e32 v36, v4, v36
	v_cndmask_b32_e64 v16, v16, 0, s[26:27]
	v_exp_f32_e32 v33, v33
	v_add_f32_e32 v36, v5, v36
	v_sub_f32_e32 v37, v162, v185
	v_cndmask_b32_e64 v203, v34, 0, s[18:19]
	v_sub_f32_e32 v34, v62, v185
	v_add_f32_e32 v36, v16, v36
	v_exp_f32_e32 v37, v37
	v_cndmask_b32_e64 v17, v17, 0, s[22:23]
	v_exp_f32_e32 v34, v34
	v_sub_f32_e32 v35, v63, v185
	v_add_f32_e32 v36, v202, v36
	v_cndmask_b32_e64 v18, v18, 0, s[24:25]
	v_exp_f32_e32 v35, v35
	v_sub_f32_e32 v32, v32, v185
	v_add_f32_e32 v36, v17, v36
	v_cndmask_b32_e64 v33, v33, 0, s[16:17]
	v_exp_f32_e32 v32, v32
	v_add_f32_e32 v36, v18, v36
	v_add_f32_e32 v36, v33, v36
	v_cndmask_b32_e64 v204, v37, 0, s[72:73]
	v_sub_f32_e32 v37, v163, v185
	v_sub_f32_e32 v38, v164, v185
	v_cndmask_b32_e64 v34, v34, 0, s[10:11]
	v_add_f32_e32 v36, v203, v36
	v_exp_f32_e32 v37, v37
	v_exp_f32_e32 v38, v38
	v_cndmask_b32_e64 v35, v35, 0, s[12:13]
	v_add_f32_e32 v36, v34, v36
	v_sub_f32_e32 v44, v166, v185
	v_cndmask_b32_e64 v32, v32, 0, s[6:7]
	v_add_f32_e32 v36, v35, v36
	v_exp_f32_e32 v44, v44
	v_add_f32_e32 v36, v32, v36
	v_add_f32_e32 v43, v204, v36
	v_cndmask_b32_e64 v36, v37, 0, s[74:75]
	v_cndmask_b32_e64 v37, v38, 0, s[96:97]
	v_sub_f32_e32 v38, v165, v185
	v_exp_f32_e32 v38, v38
	v_cndmask_b32_e64 v205, v44, 0, s[92:93]
	v_sub_f32_e32 v44, v167, v185
	v_exp_f32_e32 v44, v44
	v_add_f32_e32 v43, v36, v43
	v_sub_f32_e32 v39, v39, v185
	v_add_f32_e32 v43, v37, v43
	v_cndmask_b32_e64 v38, v38, 0, s[94:95]
	v_exp_f32_e32 v39, v39
	v_readlane_b32 s6, v234, 51
	v_add_f32_e32 v43, v38, v43
	v_readlane_b32 s7, v234, 52
	v_add_f32_e32 v48, v205, v43
	v_sub_f32_e32 v45, v45, v185
	v_cndmask_b32_e64 v43, v44, 0, s[6:7]
	v_readlane_b32 s6, v234, 53
	v_readlane_b32 s7, v234, 54
	v_exp_f32_e32 v49, v45
	v_add_f32_e32 v48, v43, v48
	v_cndmask_b32_e64 v44, v39, 0, s[6:7]
	v_sub_f32_e32 v39, v40, v185
	v_exp_f32_e32 v39, v39
	v_sub_f32_e32 v40, v41, v185
	v_exp_f32_e32 v40, v40
	v_readlane_b32 s6, v234, 55
	v_readlane_b32 s7, v234, 56
	v_sub_f32_e32 v46, v46, v185
	v_add_f32_e32 v41, v44, v48
	v_cndmask_b32_e64 v39, v39, 0, s[6:7]
	v_readlane_b32 s6, v234, 57
	v_readlane_b32 s7, v234, 58
	v_sub_f32_e32 v48, v169, v185
	v_exp_f32_e32 v46, v46
	v_cndmask_b32_e64 v206, v40, 0, s[6:7]
	v_sub_f32_e32 v40, v42, v185
	v_exp_f32_e32 v40, v40
	v_sub_f32_e32 v42, v168, v185
	v_exp_f32_e32 v42, v42
	v_readlane_b32 s6, v234, 59
	v_readlane_b32 s7, v234, 60
	v_exp_f32_e32 v48, v48
	v_sub_f32_e32 v47, v47, v185
	v_cndmask_b32_e64 v40, v40, 0, s[6:7]
	v_readlane_b32 s6, v234, 61
	v_add_f32_e32 v41, v39, v41
	v_readlane_b32 s7, v234, 62
	v_cndmask_b32_e64 v168, v49, 0, s[2:3]
	v_exp_f32_e32 v47, v47
	v_readlane_b32 s2, v233, 1
	v_add_f32_e32 v41, v206, v41
	v_cndmask_b32_e64 v42, v42, 0, s[6:7]
	v_readlane_b32 s6, v234, 63
	v_readlane_b32 s3, v233, 2
	v_add_f32_e32 v41, v40, v41
	v_readlane_b32 s7, v233, 0
	v_cndmask_b32_e64 v49, v46, 0, s[2:3]
	v_readlane_b32 s2, v233, 3
	v_sub_f32_e32 v46, v161, v185
	v_add_f32_e32 v41, v42, v41
	v_cndmask_b32_e64 v45, v48, 0, s[6:7]
	v_readlane_b32 s3, v233, 4
	v_exp_f32_e32 v46, v46
	v_add_f32_e32 v41, v45, v41
	v_cndmask_b32_e64 v50, v47, 0, s[2:3]
	v_sub_f32_e32 v47, v170, v185
	v_add_f32_e32 v41, v168, v41
	v_exp_f32_e32 v47, v47
	v_readlane_b32 s2, v233, 5
	v_add_f32_e32 v41, v49, v41
	v_readlane_b32 s3, v233, 6
	v_add_f32_e32 v48, v50, v41
	v_sub_f32_e32 v19, v19, v185
	v_cndmask_b32_e64 v41, v46, 0, s[2:3]
	v_readlane_b32 s2, v233, 7
	v_readlane_b32 s3, v233, 8
	v_exp_f32_e32 v19, v19
	v_add_f32_e32 v46, v41, v48
	v_cndmask_b32_e64 v169, v47, 0, s[2:3]
	v_sub_f32_e32 v47, v171, v185
	v_exp_f32_e32 v47, v47
	v_readlane_b32 s2, v233, 9
	v_readlane_b32 s3, v233, 10
	v_add_f32_e32 v48, v169, v46
	v_sub_f32_e32 v7, v7, v185
	v_cndmask_b32_e64 v46, v47, 0, s[2:3]
	v_readlane_b32 s2, v233, 11
	v_readlane_b32 s3, v233, 12
	v_add_f32_e32 v48, v46, v48
	v_exp_f32_e32 v7, v7
	v_cndmask_b32_e64 v47, v19, 0, s[2:3]
	v_sub_f32_e32 v19, v20, v185
	v_exp_f32_e32 v19, v19
	v_readlane_b32 s2, v233, 13
	v_sub_f32_e32 v20, v21, v185
	v_readlane_b32 s3, v233, 14
	v_exp_f32_e32 v20, v20
	v_add_f32_e32 v21, v47, v48
	v_cndmask_b32_e64 v51, v19, 0, s[2:3]
	v_add_f32_e32 v19, v51, v21
	v_sub_f32_e32 v21, v22, v185
	v_readlane_b32 s2, v233, 15
	v_exp_f32_e32 v21, v21
	v_readlane_b32 s3, v233, 16
	v_sub_f32_e32 v22, v23, v185
; DI void nsa_item(const Params& p, int it, char* lds) {
;     ...
;     sum += __shfl_xor(sum, 32, 64);
;     const float inv = sum > 0.f ? 1.f / sum : 0.f;
; #pragma unroll
;     for (int kb = 0; kb < 4; ++kb)
; #pragma unroll
;       for (int r = 0; r < 16; ++r) sc[kb][r] *= inv;
;     float* myimp = impS + (h * 32 + l31) * 32;
; #pragma unroll
;     for (int kb = 0; kb < 4; ++kb)
; #pragma unroll
;       for (int g = 0; g < 4; ++g) myimp[8 * kb + 2 * g + hi] = ((sc[kb][4 * g] + sc[kb][4 * g + 1]) + sc[kb][4 * g + 2]) + sc[kb][4 * g + 3];
;     __syncthreads();
	v_exp_f32_e32 v22, v22
	v_cndmask_b32_e64 v20, v20, 0, s[2:3]
	v_readlane_b32 s2, v233, 17
	v_readlane_b32 s3, v233, 18
	v_sub_f32_e32 v23, v27, v185
	v_exp_f32_e32 v23, v23
	v_cndmask_b32_e64 v55, v21, 0, s[2:3]
	v_readlane_b32 s2, v233, 19
	v_sub_f32_e32 v21, v24, v185
	v_readlane_b32 s3, v233, 20
	v_exp_f32_e32 v21, v21
	v_sub_f32_e32 v24, v31, v185
	v_cndmask_b32_e64 v56, v22, 0, s[2:3]
	v_sub_f32_e32 v22, v25, v185
	v_exp_f32_e32 v22, v22
	v_readlane_b32 s2, v233, 21
	v_readlane_b32 s3, v233, 22
	v_exp_f32_e32 v24, v24
	v_add_f32_e32 v19, v20, v19
	v_cndmask_b32_e64 v48, v21, 0, s[2:3]
	v_readlane_b32 s2, v233, 23
	v_readlane_b32 s3, v233, 24
	v_cndmask_b32_e64 v162, v24, 0, vcc
	v_sub_f32_e32 v24, v173, v185
	v_cndmask_b32_e64 v21, v22, 0, s[2:3]
	v_sub_f32_e32 v22, v26, v185
	v_exp_f32_e32 v22, v22
	v_readlane_b32 s2, v233, 25
	v_readlane_b32 s3, v233, 26
	v_exp_f32_e32 v24, v24
	v_add_f32_e32 v19, v55, v19
	v_cndmask_b32_e64 v52, v22, 0, s[2:3]
	v_readlane_b32 s2, v233, 27
	v_sub_f32_e32 v22, v28, v185
	v_readlane_b32 s3, v233, 28
	v_exp_f32_e32 v22, v22
	v_add_f32_e32 v19, v56, v19
	v_cndmask_b32_e64 v54, v23, 0, s[2:3]
	v_sub_f32_e32 v23, v29, v185
	v_exp_f32_e32 v23, v23
	v_readlane_b32 s2, v233, 29
	v_readlane_b32 s3, v233, 30
	v_add_f32_e32 v19, v48, v19
	v_add_f32_e32 v19, v21, v19
	v_cndmask_b32_e64 v59, v22, 0, s[2:3]
	v_readlane_b32 s2, v233, 31
	v_readlane_b32 s3, v233, 32
	v_cndmask_b32_e64 v165, v7, 0, s[52:53]
	v_sub_f32_e32 v7, v8, v185
	v_cndmask_b32_e64 v22, v23, 0, s[2:3]
	v_sub_f32_e32 v23, v30, v185
	v_exp_f32_e32 v23, v23
	v_add_f32_e32 v19, v52, v19
	v_sub_f32_e32 v25, v175, v185
	v_exp_f32_e32 v7, v7
	v_cndmask_b32_e64 v161, v23, 0, s[0:1]
	v_sub_f32_e32 v23, v172, v185
	v_exp_f32_e32 v23, v23
	v_add_f32_e32 v19, v54, v19
	v_exp_f32_e32 v25, v25
	v_add_f32_e32 v19, v59, v19
	v_cndmask_b32_e64 v53, v23, 0, s[8:9]
	v_cndmask_b32_e64 v23, v24, 0, s[4:5]
	v_sub_f32_e32 v24, v174, v185
	v_exp_f32_e32 v24, v24
	v_add_f32_e32 v19, v22, v19
	v_add_f32_e32 v19, v161, v19
	v_cndmask_b32_e64 v57, v7, 0, s[58:59]
	v_cndmask_b32_e64 v58, v24, 0, s[20:21]
	v_sub_f32_e32 v24, v181, v185
	v_sub_f32_e32 v7, v10, v185
	v_add_f32_e32 v19, v162, v19
	v_cndmask_b32_e64 v60, v25, 0, s[14:15]
	v_exp_f32_e32 v24, v24
	v_sub_f32_e32 v25, v183, v185
	v_exp_f32_e32 v7, v7
	v_add_f32_e32 v19, v53, v19
	v_exp_f32_e32 v25, v25
	v_sub_f32_e32 v6, v6, v185
	v_add_f32_e32 v19, v23, v19
	v_exp_f32_e32 v6, v6
	v_add_f32_e32 v19, v58, v19
	v_sub_f32_e32 v8, v9, v185
	v_sub_f32_e32 v9, v11, v185
	v_add_f32_e32 v19, v60, v19
	v_cndmask_b32_e64 v63, v24, 0, s[46:47]
	v_exp_f32_e32 v9, v9
	v_cndmask_b32_e64 v61, v7, 0, s[62:63]
	v_sub_f32_e32 v7, v12, v185
	v_add_f32_e32 v19, v63, v19
	v_cndmask_b32_e64 v24, v25, 0, s[40:41]
	v_exp_f32_e32 v8, v8
	v_exp_f32_e32 v7, v7
	v_add_f32_e32 v19, v24, v19
	v_cndmask_b32_e64 v164, v6, 0, s[54:55]
	v_add_f32_e32 v6, v164, v19
	v_add_f32_e32 v6, v165, v6
	v_cndmask_b32_e64 v62, v9, 0, s[60:61]
	v_sub_f32_e32 v9, v13, v185
	v_add_f32_e32 v6, v57, v6
	v_cndmask_b32_e64 v8, v8, 0, s[56:57]
	v_exp_f32_e32 v9, v9
	v_cndmask_b32_e64 v163, v7, 0, s[66:67]
	v_sub_f32_e32 v7, v14, v185
	v_add_f32_e32 v6, v8, v6
	v_exp_f32_e32 v7, v7
	v_sub_f32_e32 v10, v15, v185
	v_add_f32_e32 v6, v61, v6
	v_exp_f32_e32 v10, v10
	v_add_f32_e32 v6, v62, v6
	v_add_f32_e32 v6, v163, v6
	v_cndmask_b32_e64 v9, v9, 0, s[64:65]
	v_add_f32_e32 v6, v9, v6
	v_cndmask_b32_e64 v166, v7, 0, s[70:71]
	v_add_f32_e32 v6, v166, v6
	v_cndmask_b32_e64 v12, v10, 0, s[68:69]
	v_add_f32_e32 v6, v12, v6
	ds_bpermute_b32 v7, v158, v6
	s_waitcnt lgkmcnt(0)
	v_add_f32_e32 v6, v6, v7
	s_nop 0
	v_rcp_f32_e32 v7, v6
	s_nop 0
	v_cmp_lt_f32_e32 vcc, 0, v6
	s_nop 1
	v_cndmask_b32_e32 v167, 0, v7, vcc
	v_mul_f32_e32 v7, v186, v167
	v_mul_f32_e32 v6, v187, v167
	v_mul_f32_e32 v175, v169, v167
	v_mul_f32_e32 v169, v8, v167
	v_lshl_or_b32 v8, v150, 12, v153
	v_fma_f32 v10, v0, v167, v7
	v_fma_f32 v11, v3, v167, v6
	v_mul_f32_e32 v181, v168, v167
	v_mul_f32_e32 v168, v9, v167
	v_lshl_add_u32 v9, v152, 2, v8
	v_fmac_f32_e32 v10, v1, v167
	v_fmac_f32_e32 v11, v4, v167
	v_mul_f32_e32 v202, v202, v167
	v_mul_f32_e32 v187, v203, v167
	v_fmac_f32_e32 v10, v2, v167
	v_fmac_f32_e32 v11, v5, v167
	v_add_u32_e32 v19, 0x9000, v9
	ds_write2_b32 v19, v10, v11 offset1:2
	v_fma_f32 v10, v16, v167, v202
	v_fma_f32 v11, v33, v167, v187
	v_fmac_f32_e32 v10, v17, v167
	v_fmac_f32_e32 v11, v34, v167
	v_mul_f32_e32 v186, v204, v167
	v_mul_f32_e32 v185, v205, v167
	v_fmac_f32_e32 v10, v18, v167
	v_fmac_f32_e32 v11, v35, v167
	ds_write2_b32 v19, v10, v11 offset0:4 offset1:6
	v_fma_f32 v10, v32, v167, v186
	v_fma_f32 v11, v38, v167, v185
	v_fmac_f32_e32 v10, v36, v167
	v_fmac_f32_e32 v11, v43, v167
	v_mul_f32_e32 v183, v206, v167
	v_fmac_f32_e32 v10, v37, v167
	v_fmac_f32_e32 v11, v44, v167
	ds_write2_b32 v19, v10, v11 offset0:8 offset1:10
	v_fma_f32 v10, v39, v167, v183
	v_fma_f32 v11, v45, v167, v181
	v_fmac_f32_e32 v10, v40, v167
	v_fmac_f32_e32 v11, v49, v167
	v_mul_f32_e32 v174, v20, v167
	v_fmac_f32_e32 v10, v42, v167
	v_fmac_f32_e32 v11, v50, v167
	ds_write2_b32 v19, v10, v11 offset0:12 offset1:14
	v_fma_f32 v10, v41, v167, v175
	v_fma_f32 v11, v51, v167, v174
	v_fmac_f32_e32 v10, v46, v167
	v_fmac_f32_e32 v11, v55, v167
	v_mul_f32_e32 v173, v21, v167
	v_mul_f32_e32 v172, v22, v167
	v_fmac_f32_e32 v10, v47, v167
	v_fmac_f32_e32 v11, v56, v167
	ds_write2_b32 v19, v10, v11 offset0:16 offset1:18
	v_fma_f32 v10, v48, v167, v173
	v_fma_f32 v11, v59, v167, v172
	v_fmac_f32_e32 v10, v52, v167
	v_fmac_f32_e32 v11, v161, v167
	v_mul_f32_e32 v171, v23, v167
	v_mul_f32_e32 v170, v24, v167
	v_fmac_f32_e32 v10, v54, v167
	v_fmac_f32_e32 v11, v162, v167
	ds_write2_b32 v19, v10, v11 offset0:20 offset1:22
	v_fma_f32 v10, v53, v167, v171
	v_fma_f32 v11, v63, v167, v170
	v_fmac_f32_e32 v10, v58, v167
	v_fmac_f32_e32 v11, v164, v167
	v_fmac_f32_e32 v10, v60, v167
	v_fmac_f32_e32 v11, v165, v167
	ds_write2_b32 v19, v10, v11 offset0:24 offset1:26
	v_fma_f32 v10, v57, v167, v169
	v_fma_f32 v11, v163, v167, v168
	v_fmac_f32_e32 v10, v61, v167
	v_fmac_f32_e32 v11, v166, v167
	v_fmac_f32_e32 v10, v62, v167
	v_fmac_f32_e32 v11, v12, v167
	ds_write2_b32 v19, v10, v11 offset0:28 offset1:30
	s_waitcnt lgkmcnt(0)
	s_barrier
; DI void nsa_item(const Params& p, int it, char* lds) {
;     ...
;     __syncthreads();
; #pragma unroll
;     for (int kb = 0; kb < 4; ++kb)
; #pragma unroll
;       for (int g = 0; g < 4; ++g) { const int j1 = 8 * kb + 2 * g + hi + 1; if (j1 < 32) myimp[j1] += sc[kb][4 * g + 3]; }
	ds_read2_b32 v[10:11], v19 offset0:1 offset1:3
	v_mul_f32_e32 v150, v12, v167
	ds_read2_b32 v[12:13], v19 offset0:5 offset1:7
	ds_read2_b32 v[14:15], v19 offset0:9 offset1:11
	ds_read2_b32 v[20:21], v19 offset0:13 offset1:15
	v_cmp_eq_u32_e32 vcc, 0, v152
	s_waitcnt lgkmcnt(3)
	v_fma_f32 v10, v2, v167, v10
	v_fmac_f32_e32 v11, v5, v167
	ds_write2_b32 v19, v10, v11 offset0:1 offset1:3
	s_waitcnt lgkmcnt(3)
	v_fma_f32 v10, v18, v167, v12
	v_fmac_f32_e32 v13, v35, v167
	ds_write2_b32 v19, v10, v13 offset0:5 offset1:7
	s_waitcnt lgkmcnt(3)
	v_fma_f32 v10, v37, v167, v14
	v_fmac_f32_e32 v15, v44, v167
	ds_write2_b32 v19, v10, v15 offset0:9 offset1:11
	ds_read2_b32 v[10:11], v19 offset0:17 offset1:19
	s_waitcnt lgkmcnt(4)
	v_fma_f32 v12, v42, v167, v20
	v_fmac_f32_e32 v21, v50, v167
	ds_write2_b32 v19, v12, v21 offset0:13 offset1:15
	ds_read2_b32 v[12:13], v19 offset0:21 offset1:23
	s_waitcnt lgkmcnt(2)
	v_fma_f32 v10, v47, v167, v10
	v_fmac_f32_e32 v11, v56, v167
	ds_write2_b32 v19, v10, v11 offset0:17 offset1:19
	ds_read2_b32 v[10:11], v19 offset0:25 offset1:27
	ds_read_b32 v14, v9 offset:36980
	s_waitcnt lgkmcnt(3)
	v_fma_f32 v12, v54, v167, v12
	v_fmac_f32_e32 v13, v162, v167
	ds_write2_b32 v19, v12, v13 offset0:21 offset1:23
	s_waitcnt lgkmcnt(2)
	v_fma_f32 v10, v60, v167, v10
	v_fmac_f32_e32 v11, v165, v167
	s_waitcnt lgkmcnt(1)
	v_fmac_f32_e32 v14, v62, v167
	ds_write2_b32 v19, v10, v11 offset0:25 offset1:27
	ds_write_b32 v9, v14 offset:36980
	s_and_saveexec_b64 s[0:1], vcc
	s_cbranch_execz .LBB0_382
	ds_read_b32 v9, v8 offset:36988
	s_waitcnt lgkmcnt(0)
	v_add_f32_e32 v9, v150, v9
	ds_write_b32 v8, v9 offset:36988

; template <class RowF>
; DI void kv_load(const int tid, u32x4 (&pre)[4], RowF rowtok, const u16* proj, int kcol, int vcol) {
; #pragma unroll
;   for (int i = 0; i < 2; ++i) {
;     const int c = tid + 256 * i, row = c >> 3, ch = c & 7;
;     const u16* p = proj + (size_t)rowtok(row) * NP + ch * 8;
; DI void nsa_item(const Params& p, int it, char* lds) {
;     ...
;     for (int r = 0; r < 16; ++r) { ya[0][r] = oc[0][r] * g0; ya[1][r] = oc[1][r] * g0; }
;   }
;   __syncthreads();
;   const int cur = q0 >> 6;
;   {
;     const int q = tid >> 3, sub = tid & 7;
; #pragma unroll
;     for (int jj = 0; jj < 4; ++jj) {
;       const int j = sub * 4 + jj;
;       float v = ((impS[(0 * 32 + q) * 32 + j] + impS[(1 * 32 + q) * 32 + j]) + impS[(2 * 32 + q) * 32 + j]) + impS[(3 * 32 + q) * 32 + j];
;       const bool forced = (j == 0) || (j == cur) || (j == cur - 1);
;       v = forced ? 1e4f : ((j <= cur) ? v : -1e4f);
;       vals[q * 32 + j] = v;
;     }
;     __syncthreads();
;     f32x4 vv[8];
; #pragma unroll
;     for (int i = 0; i < 8; ++i) vv[i] = *(const f32x4*)(vals + q * 32 + i * 4);
;     unsigned bits = 0u;
; #pragma unroll
;     for (int jj = 0; jj < 4; ++jj) {
;       const int j = sub * 4 + jj; const float v = vals[q * 32 + j];
;       int cnt = 0;
; #pragma unroll
;       for (int j2 = 0; j2 < 32; ++j2) { const float w = vv[j2 >> 2][j2 & 3]; cnt += ((w > v) || (w == v && j2 < j)) ? 1 : 0; }
;       if (cnt < 16 && j <= cur) bits |= 1u << j;
;     }
;     if (bits) atomicOr(&selm[q], bits);
;   }
;   __syncthreads();
;   const unsigned mymask = selm[l31];
;   unsigned anym = mymask, allm = mymask;
; #pragma unroll
;   for (int o = 16; o >= 1; o >>= 1) { anym |= (unsigned)__shfl_xor((int)anym, o, 64); allm &= (unsigned)__shfl_xor((int)allm, o, 64); }
;   anym = __builtin_amdgcn_readfirstlane(anym);
;   allm = __builtin_amdgcn_readfirstlane(allm);
;   if (tid < 32) { if ((anym >> tid) & 1u) jlist[__builtin_popcount(anym & ((1u << tid) - 1u))] = tid; }
;   f32x16 o[2];
; #pragma unroll
;   for (int r = 0; r < 16; ++r) { o[0][r] = 0.f; o[1][r] = 0.f; }
;   float m = M_INIT, lsum = 0.f;
; #pragma unroll
;   for (int r = 0; r < 16; ++r) { yst[r * 256 + tid] = ya[0][r]; yst[(16 + r) * 256 + tid] = ya[1][r]; }
;   __syncthreads();
;   attn_stream(tid, proj, C_KSLC, C_VSLC, __builtin_popcount(anym),
.LBB0_401:
	s_or_b64 exec, exec, s[0:1]
	v_lshlrev_b32_e32 v32, 16, v151
	v_mul_f32_e32 v32, 0xbfb8aa3b, v32
	v_exp_f32_e32 v32, v32
	s_cmp_lg_u32 s3, 0
	v_add_u32_e32 v162, 0x10000, v161
	v_add_u32_e32 v163, 0x10400, v161
	v_add_f32_e32 v32, 1.0, v32
	v_add_u32_e32 v164, 0x10800, v161
	v_rcp_f32_e32 v32, v32
	s_nop 0
	v_mul_f32_e32 v0, v32, v0
	v_mul_f32_e32 v1, v32, v1
	v_mul_f32_e32 v16, v32, v16
	v_mul_f32_e32 v17, v32, v17
	v_mul_f32_e32 v2, v32, v2
	v_mul_f32_e32 v18, v32, v18
	v_mul_f32_e32 v3, v32, v3
	v_mul_f32_e32 v19, v32, v19
	v_mul_f32_e32 v4, v32, v4
	v_mul_f32_e32 v20, v32, v20
	v_mul_f32_e32 v5, v32, v5
	v_mul_f32_e32 v21, v32, v21
	v_mul_f32_e32 v6, v32, v6
	v_mul_f32_e32 v22, v32, v22
	v_mul_f32_e32 v7, v32, v7
	v_mul_f32_e32 v23, v32, v23
	v_mul_f32_e32 v8, v32, v8
	v_mul_f32_e32 v24, v32, v24
	v_mul_f32_e32 v9, v32, v9
	v_mul_f32_e32 v25, v32, v25
	v_mul_f32_e32 v10, v32, v10
	v_mul_f32_e32 v26, v32, v26
	v_mul_f32_e32 v11, v32, v11
	v_mul_f32_e32 v27, v32, v27
	ds_write2st64_b32 v161, v0, v1 offset0:144 offset1:148
	ds_write2st64_b32 v161, v16, v17 offset0:208 offset1:212
	ds_write2st64_b32 v161, v2, v3 offset0:152 offset1:156
	ds_write2st64_b32 v161, v18, v19 offset0:216 offset1:220
	ds_write2st64_b32 v161, v4, v5 offset0:160 offset1:164
	ds_write2st64_b32 v161, v20, v21 offset0:224 offset1:228
	ds_write2st64_b32 v161, v6, v7 offset0:168 offset1:172
	ds_write2st64_b32 v161, v22, v23 offset0:232 offset1:236
	ds_write2st64_b32 v161, v8, v9 offset0:176 offset1:180
	ds_write2st64_b32 v161, v24, v25 offset0:240 offset1:244
	ds_write2st64_b32 v161, v10, v11 offset0:184 offset1:188
	ds_write2st64_b32 v161, v26, v27 offset0:248 offset1:252
	v_lshlrev_b32_e32 v0, 4, v159
	v_add_u32_e32 v1, 0x100, v159
	v_mul_f32_e32 v28, v32, v28
	v_mul_f32_e32 v29, v32, v29
	v_mul_f32_e32 v30, v32, v30
	v_mul_f32_e32 v31, v32, v31
	v_add_u32_e32 v165, 0x10c00, v161
	s_cselect_b64 s[0:1], -1, 0
	s_cmp_eq_u32 s3, 0
	v_and_b32_e32 v0, 0x70, v0
	v_ashrrev_i32_e32 v167, 3, v1
	v_mul_f32_e32 v12, v32, v12
	v_mul_f32_e32 v13, v32, v13
	v_mul_f32_e32 v14, v32, v14
	v_mul_f32_e32 v15, v32, v15
	ds_write_b32 v162, v28
	ds_write2st64_b32 v161, v12, v13 offset0:192 offset1:196
	ds_write_b32 v163, v29
	ds_write_b32 v164, v30
	ds_write2st64_b32 v161, v14, v15 offset0:200 offset1:204
	ds_write_b32 v165, v31
	s_waitcnt lgkmcnt(0)
	s_barrier
	s_cbranch_scc1 .LBB0_467
	ds_read_b32 v4, v189
	v_mov_b32_e32 v1, v179
	v_lshl_add_u64 v[2:3], s[38:39], 0, v[0:1]
	s_waitcnt lgkmcnt(0)
	v_lshlrev_b32_e32 v1, 6, v4
	v_add_u32_e32 v1, s80, v1
	v_add_u32_e32 v4, v1, v150
	v_add_u32_e32 v1, v1, v167
	v_mad_i64_i32 v[4:5], s[4:5], v4, s33, v[2:3]
	v_mad_i64_i32 v[2:3], s[4:5], v1, s33, v[2:3]
	global_load_dwordx4 v[80:83], v[4:5], off offset:768
	global_load_dwordx4 v[84:87], v[4:5], off offset:896
	global_load_dwordx4 v[88:91], v[2:3], off offset:768
	global_load_dwordx4 v[92:95], v[2:3], off offset:896
	s_bcnt1_i32_b32 s3, s3
	s_cmp_lt_u32 s3, 2
	s_cbranch_scc1 .LBB0_468

; DI float lo16(unsigned w) { return __uint_as_float(w << 16); }
; DI float hi16(unsigned w) { return __uint_as_float(w & 0xffff0000u); }
; DI float siluf_(float x) { return x / (1.f + __expf(-x)); }
; DI void nsa_item(const Params& p, int it, char* lds) {
;     ...
; #pragma unroll
;   for (int r = 0; r < 16; ++r) { ya[0][r] = yst[r * 256 + tid]; ya[1][r] = yst[(16 + r) * 256 + tid]; }
;   lsum += __shfl_xor(lsum, 32, 64);
;   const float il = g1 / lsum;
;   const u16* ow = (const u16*)(ws_ + OFF_OWIN);
;   u16* y = (u16*)(ws_ + OFF_XB);
; #pragma unroll
;   for (int db = 0; db < 2; ++db)
; #pragma unroll
;     for (int g = 0; g < 4; ++g) {
;       const int col = h * 64 + 32 * db + 8 * g + 4 * hi;
;       const u32x2 w = *(const u32x2*)(ow + tok * 256 + col), az = *(const u32x2*)(proj + tok * NP + C_AZ + col);
;       const float v0 = (ya[db][4 * g] + o[db][4 * g] * il + g2 * lo16(w[0])) * siluf_(lo16(az[0]));
;       const float v1 = (ya[db][4 * g + 1] + o[db][4 * g + 1] * il + g2 * hi16(w[0])) * siluf_(hi16(az[0]));
;       const float v2 = (ya[db][4 * g + 2] + o[db][4 * g + 2] * il + g2 * lo16(w[1])) * siluf_(lo16(az[1]));
;       const float v3 = (ya[db][4 * g + 3] + o[db][4 * g + 3] * il + g2 * hi16(w[1])) * siluf_(hi16(az[1]));
;       u32x2 v; v[0] = pk2(v0, v1); v[1] = pk2(v2, v3);
;       *(u32x2*)(y + tok * 1024 + col) = v;
;     }
.LBB0_405:
	v_lshlrev_b32_e32 v32, 16, v155
	v_mul_f32_e32 v32, 0xbfb8aa3b, v32
	v_exp_f32_e32 v32, v32
	ds_bpermute_b32 v181, v158, v151
	v_mov_b32_e32 v147, v179
	v_lshlrev_b64 v[72:73], 11, v[146:147]
	v_add_f32_e32 v32, 1.0, v32
	v_readlane_b32 s13, v234, 36
	v_readlane_b32 s12, v234, 33
	v_readlane_b32 s14, v234, 37
	v_rcp_f32_e32 v32, v32
	s_nop 0
	v_lshlrev_b32_e32 v33, 16, v154
	v_mul_f32_e32 v33, 0xbfb8aa3b, v33
	v_exp_f32_e32 v150, v33
	ds_read2st64_b32 v[70:71], v161 offset0:144 offset1:148
	ds_read2st64_b32 v[54:55], v161 offset0:208 offset1:212
	ds_read2st64_b32 v[68:69], v161 offset0:152 offset1:156
	ds_read2st64_b32 v[52:53], v161 offset0:216 offset1:220
	ds_read2st64_b32 v[66:67], v161 offset0:160 offset1:164
	ds_read2st64_b32 v[50:51], v161 offset0:224 offset1:228
	ds_read2st64_b32 v[64:65], v161 offset0:168 offset1:172
	ds_read2st64_b32 v[48:49], v161 offset0:232 offset1:236
	ds_read2st64_b32 v[62:63], v161 offset0:176 offset1:180
	ds_read2st64_b32 v[46:47], v161 offset0:240 offset1:244
	ds_read2st64_b32 v[60:61], v161 offset0:184 offset1:188
	ds_read2st64_b32 v[44:45], v161 offset0:248 offset1:252
	ds_read2st64_b32 v[58:59], v161 offset0:192 offset1:196
	ds_read_b32 v38, v162
	ds_read_b32 v39, v163
	ds_read2st64_b32 v[56:57], v161 offset0:200 offset1:204
	ds_read_b32 v34, v164
	ds_read_b32 v35, v165
	s_waitcnt lgkmcnt(14)
	v_pk_add_f32 v[36:37], v[150:151], v[180:181]
	s_nop 0
	s_nop 0
	v_rcp_f32_e32 v33, v36
	s_nop 0
	v_readlane_b32 s0, v234, 38
	v_readlane_b32 s1, v234, 39
	v_or_b32_e32 v40, v156, v148
	v_lshlrev_b64 v[42:43], 9, v[146:147]
	v_ashrrev_i32_e32 v41, 31, v40
	v_lshl_add_u64 v[42:43], s[0:1], 0, v[42:43]
	v_lshlrev_b64 v[74:75], 1, v[40:41]
	v_lshl_add_u64 v[72:73], s[0:1], 0, v[72:73]
	v_lshl_add_u64 v[40:41], v[42:43], 0, v[74:75]
	s_mov_b64 s[0:1], 0xb390000
	v_lshl_add_u64 v[42:43], v[40:41], 0, s[0:1]
	s_mov_b32 s0, 0xb390000
	v_add_co_u32_e32 v40, vcc, s0, v40
	v_rcp_f32_e32 v36, v37
	s_nop 0
	v_mul_f32_e32 v36, v33, v36
	s_nop 0
	v_addc_co_u32_e32 v41, vcc, 0, v41, vcc
	global_load_dwordx2 v[76:77], v[40:41], off
	v_lshl_add_u64 v[40:41], v[144:145], 0, v[74:75]
	global_load_dwordx2 v[78:79], v[40:41], off offset:1280
	s_waitcnt vmcnt(0)
	v_and_b32_e32 v37, 0xffff0000, v78
	v_lshlrev_b32_e32 v33, 16, v78
	v_pk_fma_f32 v[16:17], v[16:17], v[36:37], v[70:71] op_sel_hi:[1,0,1]
	v_lshlrev_b32_e32 v70, 16, v76
	v_and_b32_e32 v71, 0xffff0000, v76
	v_mul_f32_e32 v78, 0xbfb8aa3b, v33
	v_pk_fma_f32 v[16:17], v[32:33], v[70:71], v[16:17] op_sel_hi:[0,1,1]
	v_mul_f32_e32 v70, 0xbfb8aa3b, v37
	v_exp_f32_e32 v80, v78
	v_exp_f32_e32 v81, v70
	s_nop 0
	v_pk_add_f32 v[70:71], v[80:81], 1.0 op_sel_hi:[1,0]
	s_nop 0
	s_nop 0
	v_rcp_f32_e32 v71, v71
	s_nop 0
	v_mul_f32_e32 v71, v37, v71
	s_nop 0
	v_rcp_f32_e32 v70, v70
	s_nop 0
	v_mul_f32_e32 v70, v33, v70
	v_and_b32_e32 v37, 0xffff0000, v79
	v_lshlrev_b32_e32 v33, 16, v79
	v_pk_fma_f32 v[18:19], v[18:19], v[36:37], v[68:69] op_sel_hi:[1,0,1]
	v_lshlrev_b32_e32 v68, 16, v77
	v_and_b32_e32 v69, 0xffff0000, v77
	v_pk_mul_f32 v[16:17], v[16:17], v[70:71]
	v_mul_f32_e32 v70, 0xbfb8aa3b, v33
	v_pk_fma_f32 v[18:19], v[32:33], v[68:69], v[18:19] op_sel_hi:[0,1,1]
	v_mul_f32_e32 v68, 0xbfb8aa3b, v37
	v_exp_f32_e32 v70, v70
	v_exp_f32_e32 v71, v68
	s_nop 0
	v_pk_add_f32 v[68:69], v[70:71], 1.0 op_sel_hi:[1,0]
	s_nop 0
	s_nop 0
	v_rcp_f32_e32 v69, v69
	s_nop 0
	v_mul_f32_e32 v69, v37, v69
	s_mov_b64 s[0:1], 0x2a40000
	v_rcp_f32_e32 v68, v68
	s_nop 0
	v_mul_f32_e32 v68, v33, v68
	v_pk_mul_f32 v[18:19], v[18:19], v[68:69]
	v_cvt_pk_bf16_f32 v68, v16, v17
	v_cvt_pk_bf16_f32 v69, v18, v19
	v_lshl_add_u64 v[18:19], v[72:73], 0, v[74:75]
	v_lshl_add_u64 v[16:17], v[18:19], 0, s[0:1]
	v_add_co_u32_e32 v18, vcc, s74, v18
	s_nop 1
	v_addc_co_u32_e32 v19, vcc, 0, v19, vcc
	global_store_dwordx2 v[18:19], v[68:69], off
	global_load_dwordx2 v[18:19], v[42:43], off offset:16
	s_nop 0
	global_load_dwordx2 v[68:69], v[40:41], off offset:1296
	s_waitcnt vmcnt(0)
	v_lshlrev_b32_e32 v33, 16, v68
	v_and_b32_e32 v37, 0xffff0000, v68
	v_mul_f32_e32 v68, 0xbfb8aa3b, v33
	s_waitcnt lgkmcnt(13)
	v_pk_fma_f32 v[20:21], v[20:21], v[36:37], v[66:67] op_sel_hi:[1,0,1]
	v_lshlrev_b32_e32 v66, 16, v18
	v_and_b32_e32 v67, 0xffff0000, v18
	v_mul_f32_e32 v18, 0xbfb8aa3b, v37
	v_exp_f32_e32 v70, v68
	v_exp_f32_e32 v71, v18
	v_pk_fma_f32 v[20:21], v[32:33], v[66:67], v[20:21] op_sel_hi:[0,1,1]
	v_pk_add_f32 v[66:67], v[70:71], 1.0 op_sel_hi:[1,0]
	s_nop 0
	s_nop 0
	v_rcp_f32_e32 v67, v67
	s_nop 0
	v_mul_f32_e32 v67, v37, v67
	s_nop 0
	v_rcp_f32_e32 v66, v66
	s_nop 0
	v_mul_f32_e32 v66, v33, v66
	v_lshlrev_b32_e32 v33, 16, v69
	v_and_b32_e32 v37, 0xffff0000, v69
	v_mul_f32_e32 v18, 0xbfb8aa3b, v33
	s_waitcnt lgkmcnt(11)
	v_pk_fma_f32 v[22:23], v[22:23], v[36:37], v[64:65] op_sel_hi:[1,0,1]
	v_lshlrev_b32_e32 v64, 16, v19
	v_and_b32_e32 v65, 0xffff0000, v19
	v_mul_f32_e32 v19, 0xbfb8aa3b, v37
	v_exp_f32_e32 v18, v18
	v_exp_f32_e32 v19, v19
	v_pk_fma_f32 v[22:23], v[32:33], v[64:65], v[22:23] op_sel_hi:[0,1,1]
	v_pk_mul_f32 v[20:21], v[20:21], v[66:67]
	v_pk_add_f32 v[18:19], v[18:19], 1.0 op_sel_hi:[1,0]
	s_nop 0
	v_cvt_pk_bf16_f32 v20, v20, v21
	v_rcp_f32_e32 v19, v19
	s_nop 0
	v_mul_f32_e32 v19, v37, v19
	v_div_scale_f32 v37, s[0:1], v18, v18, v33
	v_rcp_f32_e32 v64, v37
	s_nop 0
	v_fma_f32 v65, -v37, v64, 1.0
	v_fmac_f32_e32 v64, v65, v64
	v_div_scale_f32 v65, vcc, v33, v18, v33
	v_mul_f32_e32 v66, v65, v64
	v_fma_f32 v67, -v37, v66, v65
	v_fmac_f32_e32 v66, v67, v64
	v_fma_f32 v37, -v37, v66, v65
	v_div_fmas_f32 v37, v37, v64, v66
	v_div_fixup_f32 v18, v37, v18, v33
	v_pk_mul_f32 v[18:19], v[22:23], v[18:19]
	s_waitcnt lgkmcnt(9)
; DI float lo16(unsigned w) { return __uint_as_float(w << 16); }
; DI float hi16(unsigned w) { return __uint_as_float(w & 0xffff0000u); }
; DI float siluf_(float x) { return x / (1.f + __expf(-x)); }
; DI void nsa_item(const Params& p, int it, char* lds) {
;     ...
; #pragma unroll
;   for (int db = 0; db < 2; ++db)
; #pragma unroll
;     for (int g = 0; g < 4; ++g) {
;       const int col = h * 64 + 32 * db + 8 * g + 4 * hi;
;       const u32x2 w = *(const u32x2*)(ow + tok * 256 + col), az = *(const u32x2*)(proj + tok * NP + C_AZ + col);
;       const float v0 = (ya[db][4 * g] + o[db][4 * g] * il + g2 * lo16(w[0])) * siluf_(lo16(az[0]));
;       const float v1 = (ya[db][4 * g + 1] + o[db][4 * g + 1] * il + g2 * hi16(w[0])) * siluf_(hi16(az[0]));
;       const float v2 = (ya[db][4 * g + 2] + o[db][4 * g + 2] * il + g2 * lo16(w[1])) * siluf_(lo16(az[1]));
;       const float v3 = (ya[db][4 * g + 3] + o[db][4 * g + 3] * il + g2 * hi16(w[1])) * siluf_(hi16(az[1]));
;       u32x2 v; v[0] = pk2(v0, v1); v[1] = pk2(v2, v3);
;       *(u32x2*)(y + tok * 1024 + col) = v;
;     }
	v_pk_fma_f32 v[24:25], v[24:25], v[36:37], v[62:63] op_sel_hi:[1,0,1]
	v_cvt_pk_bf16_f32 v21, v18, v19
	global_store_dwordx2 v[16:17], v[20:21], off offset:16
	global_load_dwordx2 v[18:19], v[42:43], off offset:32
	s_nop 0
	global_load_dwordx2 v[20:21], v[40:41], off offset:1312
	s_waitcnt vmcnt(1)
	v_lshlrev_b32_e32 v62, 16, v18
	s_waitcnt vmcnt(0)
	v_lshlrev_b32_e32 v33, 16, v20
	v_and_b32_e32 v20, 0xffff0000, v20
	v_mul_f32_e32 v22, 0xbfb8aa3b, v33
	v_and_b32_e32 v63, 0xffff0000, v18
	v_mul_f32_e32 v18, 0xbfb8aa3b, v20
	v_exp_f32_e32 v22, v22
	v_exp_f32_e32 v23, v18
	v_pk_fma_f32 v[24:25], v[32:33], v[62:63], v[24:25] op_sel_hi:[0,1,1]
	v_pk_add_f32 v[22:23], v[22:23], 1.0 op_sel_hi:[1,0]
	s_nop 0
	s_nop 0
	v_rcp_f32_e32 v23, v23
	s_nop 0
	v_mul_f32_e32 v23, v20, v23
	s_nop 0
	v_rcp_f32_e32 v22, v22
	s_nop 0
	v_mul_f32_e32 v22, v33, v22
	v_lshlrev_b32_e32 v33, 16, v21
	v_and_b32_e32 v37, 0xffff0000, v21
	v_pk_mul_f32 v[22:23], v[24:25], v[22:23]
	v_mul_f32_e32 v18, 0xbfb8aa3b, v33
	v_lshlrev_b32_e32 v24, 16, v19
	v_and_b32_e32 v25, 0xffff0000, v19
	v_mul_f32_e32 v19, 0xbfb8aa3b, v37
	v_exp_f32_e32 v18, v18
	v_exp_f32_e32 v19, v19
	s_waitcnt lgkmcnt(7)
	v_pk_fma_f32 v[20:21], v[26:27], v[36:37], v[60:61] op_sel_hi:[1,0,1]
	v_pk_add_f32 v[18:19], v[18:19], 1.0 op_sel_hi:[1,0]
	v_pk_fma_f32 v[20:21], v[32:33], v[24:25], v[20:21] op_sel_hi:[0,1,1]
	s_nop 0
	v_rcp_f32_e32 v19, v19
	s_nop 0
	v_mul_f32_e32 v19, v37, v19
	v_div_scale_f32 v24, s[0:1], v18, v18, v33
	v_rcp_f32_e32 v25, v24
	s_nop 0
	v_fma_f32 v26, -v24, v25, 1.0
	v_fmac_f32_e32 v25, v26, v25
	v_div_scale_f32 v26, vcc, v33, v18, v33
	v_mul_f32_e32 v27, v26, v25
	v_fma_f32 v37, -v24, v27, v26
	v_fmac_f32_e32 v27, v37, v25
	v_fma_f32 v24, -v24, v27, v26
	v_div_fmas_f32 v24, v24, v25, v27
	v_div_fixup_f32 v18, v24, v18, v33
	v_pk_mul_f32 v[18:19], v[20:21], v[18:19]
	v_cvt_pk_bf16_f32 v20, v22, v23
	v_cvt_pk_bf16_f32 v21, v18, v19
	global_store_dwordx2 v[16:17], v[20:21], off offset:32
	global_load_dwordx2 v[18:19], v[42:43], off offset:48
	s_nop 0
	global_load_dwordx2 v[20:21], v[40:41], off offset:1328
	s_waitcnt lgkmcnt(5)
	v_pk_fma_f32 v[24:25], v[28:29], v[36:37], v[58:59] op_sel_hi:[1,0,1]
	v_pk_fma_f32 v[0:1], v[0:1], v[36:37], v[54:55] op_sel_hi:[1,0,1]
	v_pk_fma_f32 v[2:3], v[2:3], v[36:37], v[52:53] op_sel_hi:[1,0,1]
	v_pk_fma_f32 v[4:5], v[4:5], v[36:37], v[50:51] op_sel_hi:[1,0,1]
	s_waitcnt vmcnt(1)
	v_lshlrev_b32_e32 v26, 16, v18
	s_waitcnt vmcnt(0)
	v_lshlrev_b32_e32 v33, 16, v20
	v_and_b32_e32 v20, 0xffff0000, v20
	v_mul_f32_e32 v22, 0xbfb8aa3b, v33
	v_and_b32_e32 v27, 0xffff0000, v18
	v_mul_f32_e32 v18, 0xbfb8aa3b, v20
	v_exp_f32_e32 v22, v22
	v_exp_f32_e32 v23, v18
	v_pk_fma_f32 v[24:25], v[32:33], v[26:27], v[24:25] op_sel_hi:[0,1,1]
	v_pk_add_f32 v[22:23], v[22:23], 1.0 op_sel_hi:[1,0]
	s_nop 0
	s_nop 0
	v_rcp_f32_e32 v23, v23
	s_nop 0
	v_mul_f32_e32 v23, v20, v23
	s_nop 0
	v_rcp_f32_e32 v22, v22
	s_nop 0
	v_mul_f32_e32 v22, v33, v22
	v_lshlrev_b32_e32 v26, 16, v21
	v_and_b32_e32 v27, 0xffff0000, v21
	v_pk_mul_f32 v[22:23], v[24:25], v[22:23]
	v_mul_f32_e32 v18, 0xbfb8aa3b, v26
	v_lshlrev_b32_e32 v24, 16, v19
	v_and_b32_e32 v25, 0xffff0000, v19
	v_mul_f32_e32 v19, 0xbfb8aa3b, v27
	v_exp_f32_e32 v18, v18
	v_exp_f32_e32 v19, v19
	s_waitcnt lgkmcnt(2)
	v_pk_fma_f32 v[20:21], v[30:31], v[36:37], v[56:57] op_sel_hi:[1,0,1]
	v_pk_add_f32 v[18:19], v[18:19], 1.0 op_sel_hi:[1,0]
	v_pk_fma_f32 v[20:21], v[32:33], v[24:25], v[20:21] op_sel_hi:[0,1,1]
	s_nop 0
	v_rcp_f32_e32 v19, v19
	s_nop 0
	v_mul_f32_e32 v19, v27, v19
	s_nop 0
	v_rcp_f32_e32 v18, v18
	s_nop 0
	v_mul_f32_e32 v18, v26, v18
	v_pk_mul_f32 v[18:19], v[20:21], v[18:19]
	v_cvt_pk_bf16_f32 v20, v22, v23
	v_cvt_pk_bf16_f32 v21, v18, v19
	global_store_dwordx2 v[16:17], v[20:21], off offset:48
	global_load_dwordx2 v[18:19], v[42:43], off offset:64
	s_nop 0
	global_load_dwordx2 v[20:21], v[40:41], off offset:1344
	s_waitcnt vmcnt(1)
	v_lshlrev_b32_e32 v24, 16, v18
	s_waitcnt vmcnt(0)
	v_lshlrev_b32_e32 v26, 16, v20
	v_and_b32_e32 v20, 0xffff0000, v20
	v_mul_f32_e32 v22, 0xbfb8aa3b, v26
	v_and_b32_e32 v25, 0xffff0000, v18
	v_mul_f32_e32 v18, 0xbfb8aa3b, v20
	v_exp_f32_e32 v22, v22
	v_exp_f32_e32 v23, v18
	v_pk_fma_f32 v[0:1], v[32:33], v[24:25], v[0:1] op_sel_hi:[0,1,1]
	v_pk_add_f32 v[22:23], v[22:23], 1.0 op_sel_hi:[1,0]
	s_nop 0
	s_nop 0
	v_rcp_f32_e32 v23, v23
	s_nop 0
	v_mul_f32_e32 v23, v20, v23
	s_nop 0
	v_rcp_f32_e32 v22, v22
	s_nop 0
	v_mul_f32_e32 v22, v26, v22
	v_pk_mul_f32 v[0:1], v[0:1], v[22:23]
	v_lshlrev_b32_e32 v22, 16, v21
	v_and_b32_e32 v23, 0xffff0000, v21
	v_mul_f32_e32 v18, 0xbfb8aa3b, v22
	v_lshlrev_b32_e32 v20, 16, v19
	v_and_b32_e32 v21, 0xffff0000, v19
	v_mul_f32_e32 v19, 0xbfb8aa3b, v23
	v_exp_f32_e32 v18, v18
	v_exp_f32_e32 v19, v19
	v_pk_fma_f32 v[2:3], v[32:33], v[20:21], v[2:3] op_sel_hi:[0,1,1]
	v_cvt_pk_bf16_f32 v0, v0, v1
	v_pk_add_f32 v[18:19], v[18:19], 1.0 op_sel_hi:[1,0]
	s_nop 0
	s_nop 0
	v_rcp_f32_e32 v19, v19
	s_nop 0
	v_mul_f32_e32 v19, v23, v19
	s_nop 0
	v_rcp_f32_e32 v18, v18
	s_nop 0
	v_mul_f32_e32 v18, v22, v18
	v_pk_mul_f32 v[2:3], v[2:3], v[18:19]
	s_nop 0
	v_cvt_pk_bf16_f32 v1, v2, v3
	global_store_dwordx2 v[16:17], v[0:1], off offset:64
	global_load_dwordx2 v[0:1], v[42:43], off offset:80
	s_nop 0
	global_load_dwordx2 v[2:3], v[40:41], off offset:1360
	s_waitcnt vmcnt(1)
; DI float lo16(unsigned w) { return __uint_as_float(w << 16); }
; DI float hi16(unsigned w) { return __uint_as_float(w & 0xffff0000u); }
; DI float siluf_(float x) { return x / (1.f + __expf(-x)); }
; DI void nsa_item(const Params& p, int it, char* lds) {
;     ...
; #pragma unroll
;   for (int db = 0; db < 2; ++db)
; #pragma unroll
;     for (int g = 0; g < 4; ++g) {
;       const int col = h * 64 + 32 * db + 8 * g + 4 * hi;
;       const u32x2 w = *(const u32x2*)(ow + tok * 256 + col), az = *(const u32x2*)(proj + tok * NP + C_AZ + col);
;       const float v0 = (ya[db][4 * g] + o[db][4 * g] * il + g2 * lo16(w[0])) * siluf_(lo16(az[0]));
;       const float v1 = (ya[db][4 * g + 1] + o[db][4 * g + 1] * il + g2 * hi16(w[0])) * siluf_(hi16(az[0]));
;       const float v2 = (ya[db][4 * g + 2] + o[db][4 * g + 2] * il + g2 * lo16(w[1])) * siluf_(lo16(az[1]));
;       const float v3 = (ya[db][4 * g + 3] + o[db][4 * g + 3] * il + g2 * hi16(w[1])) * siluf_(hi16(az[1]));
;       u32x2 v; v[0] = pk2(v0, v1); v[1] = pk2(v2, v3);
;       *(u32x2*)(y + tok * 1024 + col) = v;
;     }
; __global__ void __launch_bounds__(256, 2) hybrid_megakernel(Params p) {
;     ...
;       const int gi = vb >> 4;
;       int start = 0, mine = 0;
;       for (int g2 = 0; g2 <= gi; ++g2) {
;         const int n = 32 - g2;
;         const int d = (n <= 10) ? 2 : (n <= 22) ? 1 : 0;
;         if (g2 < gi) start += 2 * d; else mine = d;
;       }
;       start += ((vb >> 3) & 1) * mine;
;       const int x = vb & 7;
;       for (int k = 0; k < mine; ++k) { const int slot = start + k; sgu_item(p, l, slot * 8 + x, lds); pool_item(p, l, slot * 8 + x, lds); dilcomb_item(p, x * 64 + slot); }
	v_lshlrev_b32_e32 v20, 16, v0
	s_waitcnt vmcnt(0)
	v_lshlrev_b32_e32 v22, 16, v2
	v_and_b32_e32 v2, 0xffff0000, v2
	v_mul_f32_e32 v18, 0xbfb8aa3b, v22
	v_and_b32_e32 v21, 0xffff0000, v0
	v_mul_f32_e32 v0, 0xbfb8aa3b, v2
	v_exp_f32_e32 v18, v18
	v_exp_f32_e32 v19, v0
	v_pk_fma_f32 v[4:5], v[32:33], v[20:21], v[4:5] op_sel_hi:[0,1,1]
	v_pk_add_f32 v[18:19], v[18:19], 1.0 op_sel_hi:[1,0]
	s_nop 0
	s_nop 0
	v_rcp_f32_e32 v19, v19
	s_nop 0
	v_mul_f32_e32 v19, v2, v19
	s_nop 0
	v_rcp_f32_e32 v18, v18
	s_nop 0
	v_mul_f32_e32 v18, v22, v18
	v_pk_mul_f32 v[4:5], v[4:5], v[18:19]
	v_lshlrev_b32_e32 v18, 16, v3
	v_and_b32_e32 v19, 0xffff0000, v3
	v_mul_f32_e32 v0, 0xbfb8aa3b, v18
	v_pk_fma_f32 v[2:3], v[6:7], v[36:37], v[48:49] op_sel_hi:[1,0,1]
	v_lshlrev_b32_e32 v6, 16, v1
	v_and_b32_e32 v7, 0xffff0000, v1
	v_mul_f32_e32 v1, 0xbfb8aa3b, v19
	v_exp_f32_e32 v0, v0
	v_exp_f32_e32 v1, v1
	v_pk_fma_f32 v[2:3], v[32:33], v[6:7], v[2:3] op_sel_hi:[0,1,1]
	v_pk_add_f32 v[0:1], v[0:1], 1.0 op_sel_hi:[1,0]
	s_nop 0
	s_nop 0
	v_rcp_f32_e32 v1, v1
	s_nop 0
	v_mul_f32_e32 v1, v19, v1
	s_nop 0
	v_rcp_f32_e32 v0, v0
	s_nop 0
	v_mul_f32_e32 v0, v18, v0
	v_pk_mul_f32 v[0:1], v[2:3], v[0:1]
	v_cvt_pk_bf16_f32 v2, v4, v5
	v_cvt_pk_bf16_f32 v3, v0, v1
	global_store_dwordx2 v[16:17], v[2:3], off offset:80
	global_load_dwordx2 v[0:1], v[42:43], off offset:96
	s_nop 0
	global_load_dwordx2 v[2:3], v[40:41], off offset:1376
	v_pk_fma_f32 v[6:7], v[8:9], v[36:37], v[46:47] op_sel_hi:[1,0,1]
	s_waitcnt vmcnt(1)
	v_lshlrev_b32_e32 v8, 16, v0
	s_waitcnt vmcnt(0)
	v_lshlrev_b32_e32 v18, 16, v2
	v_and_b32_e32 v2, 0xffff0000, v2
	v_mul_f32_e32 v4, 0xbfb8aa3b, v18
	v_and_b32_e32 v9, 0xffff0000, v0
	v_mul_f32_e32 v0, 0xbfb8aa3b, v2
	v_exp_f32_e32 v4, v4
	v_exp_f32_e32 v5, v0
	v_pk_fma_f32 v[6:7], v[32:33], v[8:9], v[6:7] op_sel_hi:[0,1,1]
	v_pk_add_f32 v[4:5], v[4:5], 1.0 op_sel_hi:[1,0]
	s_nop 0
	s_nop 0
	v_rcp_f32_e32 v5, v5
	s_nop 0
	v_mul_f32_e32 v5, v2, v5
	s_nop 0
	v_rcp_f32_e32 v4, v4
	s_nop 0
	v_mul_f32_e32 v4, v18, v4
	v_lshlrev_b32_e32 v8, 16, v3
	v_and_b32_e32 v9, 0xffff0000, v3
	v_pk_mul_f32 v[4:5], v[6:7], v[4:5]
	v_mul_f32_e32 v0, 0xbfb8aa3b, v8
	v_lshlrev_b32_e32 v6, 16, v1
	v_and_b32_e32 v7, 0xffff0000, v1
	v_mul_f32_e32 v1, 0xbfb8aa3b, v9
	v_exp_f32_e32 v0, v0
	v_exp_f32_e32 v1, v1
	v_pk_fma_f32 v[2:3], v[10:11], v[36:37], v[44:45] op_sel_hi:[1,0,1]
	v_pk_add_f32 v[0:1], v[0:1], 1.0 op_sel_hi:[1,0]
	v_pk_fma_f32 v[2:3], v[32:33], v[6:7], v[2:3] op_sel_hi:[0,1,1]
	s_nop 0
	v_rcp_f32_e32 v1, v1
	s_nop 0
	v_mul_f32_e32 v1, v9, v1
	s_nop 0
	v_rcp_f32_e32 v0, v0
	s_nop 0
	v_mul_f32_e32 v0, v8, v0
	v_pk_mul_f32 v[0:1], v[2:3], v[0:1]
	v_cvt_pk_bf16_f32 v2, v4, v5
	v_cvt_pk_bf16_f32 v3, v0, v1
	global_store_dwordx2 v[16:17], v[2:3], off offset:96
	global_load_dwordx2 v[0:1], v[42:43], off offset:112
	s_nop 0
	global_load_dwordx2 v[2:3], v[40:41], off offset:1392
	v_pk_fma_f32 v[6:7], v[12:13], v[36:37], v[38:39] op_sel_hi:[1,0,1]
	s_waitcnt vmcnt(1)
	v_lshlrev_b32_e32 v8, 16, v0
	s_waitcnt vmcnt(0)
	v_lshlrev_b32_e32 v10, 16, v2
	v_and_b32_e32 v2, 0xffff0000, v2
	v_mul_f32_e32 v4, 0xbfb8aa3b, v10
	v_and_b32_e32 v9, 0xffff0000, v0
	v_mul_f32_e32 v0, 0xbfb8aa3b, v2
	v_exp_f32_e32 v4, v4
	v_exp_f32_e32 v5, v0
	v_pk_fma_f32 v[6:7], v[32:33], v[8:9], v[6:7] op_sel_hi:[0,1,1]
	v_pk_add_f32 v[4:5], v[4:5], 1.0 op_sel_hi:[1,0]
	s_nop 0
	s_nop 0
	v_rcp_f32_e32 v5, v5
	s_nop 0
	v_mul_f32_e32 v5, v2, v5
	s_nop 0
	v_rcp_f32_e32 v4, v4
	s_nop 0
	v_mul_f32_e32 v4, v10, v4
	v_lshlrev_b32_e32 v8, 16, v3
	v_and_b32_e32 v9, 0xffff0000, v3
	v_pk_mul_f32 v[4:5], v[6:7], v[4:5]
	v_mul_f32_e32 v0, 0xbfb8aa3b, v8
	v_lshlrev_b32_e32 v6, 16, v1
	v_and_b32_e32 v7, 0xffff0000, v1
	v_mul_f32_e32 v1, 0xbfb8aa3b, v9
	v_exp_f32_e32 v0, v0
	v_exp_f32_e32 v1, v1
	s_waitcnt lgkmcnt(0)
	v_pk_fma_f32 v[2:3], v[14:15], v[36:37], v[34:35] op_sel_hi:[1,0,1]
	v_pk_add_f32 v[0:1], v[0:1], 1.0 op_sel_hi:[1,0]
	v_pk_fma_f32 v[2:3], v[32:33], v[6:7], v[2:3] op_sel_hi:[0,1,1]
	s_nop 0
	v_rcp_f32_e32 v1, v1
	s_nop 0
	v_mul_f32_e32 v1, v9, v1
	s_ashr_i32 s0, s13, 4
	s_cmp_lt_i32 s0, 0
	v_rcp_f32_e32 v0, v0
	s_nop 0
	v_mul_f32_e32 v0, v8, v0
	v_pk_mul_f32 v[0:1], v[2:3], v[0:1]
	v_cvt_pk_bf16_f32 v2, v4, v5
	v_cvt_pk_bf16_f32 v3, v0, v1
	global_store_dwordx2 v[16:17], v[2:3], off offset:112
	s_cbranch_scc1 .LBB0_409
	s_add_i32 s1, s0, 1
	s_mov_b32 s2, 0
	v_mov_b32_e32 v116, 0
	v_mov_b32_e32 v0, 0

; DI float lo16(unsigned w) { return __uint_as_float(w << 16); }
; DI float hi16(unsigned w) { return __uint_as_float(w & 0xffff0000u); }
; DI float siluf_(float x) { return x / (1.f + __expf(-x)); }
; DI void sgu_item(const Params& p, int l, int it, char* lds) {
;     ...
;   const size_t tok = (size_t)b * S_ + t0 + i;
;   const float bs = p.b_sp[(l * 4 + g) * 128 + i];
;   u16* y = (u16*)(ws_ + OFF_XB);
; #pragma unroll
;   for (int ct = 0; ct < 2; ++ct)
; #pragma unroll
;     for (int g4 = 0; g4 < 4; ++g4) {
;       const int col = g * 64 + ct * 32 + 8 * g4 + 4 * hi;
;       const u32x2 u = *(const u32x2*)(proj + tok * NP + C_DU + col), z = *(const u32x2*)(proj + tok * NP + C_DZ + col);
;       u32x2 v;
;       v[0] = pk2(lo16(u[0]) * (acc[ct][4 * g4] + bs) * siluf_(lo16(z[0])), hi16(u[0]) * (acc[ct][4 * g4 + 1] + bs) * siluf_(hi16(z[0])));
;       v[1] = pk2(lo16(u[1]) * (acc[ct][4 * g4 + 2] + bs) * siluf_(lo16(z[1])), hi16(u[1]) * (acc[ct][4 * g4 + 3] + bs) * siluf_(hi16(z[1])));
;       *(u32x2*)(y + tok * 1024 + 768 + col) = v;
;     }
.LBB0_445:
	v_mov_b32_e32 v95, v179
	v_lshl_add_u64 v[32:33], v[96:97], 0, v[94:95]
	v_lshl_add_u32 v34, v99, 7, v96
	v_mov_b64_e32 v[36:37], s[2:3]
	v_ashrrev_i32_e32 v35, 31, v34
	v_mad_i64_i32 v[36:37], s[2:3], v32, s33, v[36:37]
	v_lshl_add_u64 v[34:35], v[34:35], 2, s[82:83]
	s_mov_b64 s[2:3], 0x1300
	global_load_dword v34, v[34:35], off
	v_lshl_add_u64 v[38:39], v[36:37], 0, s[2:3]
	s_mov_b64 s[2:3], 0x1700
	v_lshlrev_b32_e32 v35, 7, v93
	v_lshl_add_u64 v[36:37], v[36:37], 0, s[2:3]
	v_lshl_or_b32 v178, v98, 3, v35
	v_lshl_add_u64 v[40:41], v[38:39], 0, v[178:179]
	v_lshl_add_u64 v[42:43], v[36:37], 0, v[178:179]
	global_load_dwordx2 v[40:41], v[40:41], off
	v_lshlrev_b64 v[32:33], 11, v[32:33]
	global_load_dwordx2 v[42:43], v[42:43], off
	v_lshl_add_u64 v[32:33], s[0:1], 0, v[32:33]
	s_mov_b64 s[0:1], 0x2a40600
	v_lshl_add_u64 v[32:33], v[32:33], 0, s[0:1]
	v_mov_b32_e32 v121, v176
	s_waitcnt vmcnt(1)
	v_lshlrev_b32_e32 v46, 16, v40
	v_and_b32_e32 v47, 0xffff0000, v40
	s_waitcnt vmcnt(0)
	v_lshlrev_b32_e32 v35, 16, v42
	v_and_b32_e32 v42, 0xffff0000, v42
	v_mul_f32_e32 v44, 0xbfb8aa3b, v35
	v_mul_f32_e32 v40, 0xbfb8aa3b, v42
	v_exp_f32_e32 v44, v44
	v_exp_f32_e32 v45, v40
	v_pk_add_f32 v[0:1], v[34:35], v[0:1] op_sel_hi:[0,1]
	v_pk_mul_f32 v[0:1], v[0:1], v[46:47]
	v_pk_add_f32 v[44:45], v[44:45], 1.0 op_sel_hi:[1,0]
	s_nop 0
	s_nop 0
	v_rcp_f32_e32 v45, v45
	s_nop 0
	v_mul_f32_e32 v45, v42, v45
	s_nop 0
	v_rcp_f32_e32 v44, v44
	s_nop 0
	v_mul_f32_e32 v44, v35, v44
	v_pk_mul_f32 v[0:1], v[0:1], v[44:45]
	v_and_b32_e32 v35, 0xffff0000, v43
	v_cvt_pk_bf16_f32 v0, v0, v1
	v_lshlrev_b32_e32 v1, 16, v43
	v_mul_f32_e32 v40, 0xbfb8aa3b, v1
	v_lshlrev_b32_e32 v42, 16, v41
	v_and_b32_e32 v43, 0xffff0000, v41
	v_mul_f32_e32 v41, 0xbfb8aa3b, v35
	v_exp_f32_e32 v40, v40
	v_exp_f32_e32 v41, v41
	v_pk_add_f32 v[2:3], v[34:35], v[2:3] op_sel_hi:[0,1]
	v_pk_mul_f32 v[2:3], v[2:3], v[42:43]
	v_pk_add_f32 v[40:41], v[40:41], 1.0 op_sel_hi:[1,0]
	s_nop 0
	s_nop 0
	v_rcp_f32_e32 v41, v41
	s_nop 0
	v_mul_f32_e32 v41, v35, v41
	s_nop 0
	v_rcp_f32_e32 v40, v40
	s_nop 0
	v_mul_f32_e32 v40, v1, v40
	v_pk_mul_f32 v[2:3], v[2:3], v[40:41]
	s_nop 0
	v_cvt_pk_bf16_f32 v1, v2, v3
	v_lshl_add_u64 v[2:3], v[32:33], 0, v[178:179]
	global_store_dwordx2 v[2:3], v[0:1], off
	v_or_b32_e32 v0, 16, v178
	v_mov_b32_e32 v1, v179
	v_lshl_add_u64 v[2:3], v[38:39], 0, v[0:1]
	v_lshl_add_u64 v[40:41], v[36:37], 0, v[0:1]
	global_load_dwordx2 v[2:3], v[2:3], off
	v_lshl_add_u64 v[0:1], v[32:33], 0, v[0:1]
	global_load_dwordx2 v[40:41], v[40:41], off
	s_waitcnt vmcnt(1)
	v_lshlrev_b32_e32 v44, 16, v2
	v_and_b32_e32 v45, 0xffff0000, v2
	s_waitcnt vmcnt(0)
	v_lshlrev_b32_e32 v35, 16, v40
	v_and_b32_e32 v40, 0xffff0000, v40
	v_mul_f32_e32 v42, 0xbfb8aa3b, v35
	v_mul_f32_e32 v2, 0xbfb8aa3b, v40
	v_exp_f32_e32 v42, v42
	v_exp_f32_e32 v43, v2
	v_pk_add_f32 v[4:5], v[34:35], v[4:5] op_sel_hi:[0,1]
	v_pk_mul_f32 v[4:5], v[4:5], v[44:45]
	v_pk_add_f32 v[42:43], v[42:43], 1.0 op_sel_hi:[1,0]
	s_nop 0
	s_nop 0
	v_rcp_f32_e32 v43, v43
	s_nop 0
	v_mul_f32_e32 v43, v40, v43
	s_nop 0
	v_rcp_f32_e32 v42, v42
	s_nop 0
	v_mul_f32_e32 v42, v35, v42
	v_pk_mul_f32 v[4:5], v[4:5], v[42:43]
	v_lshlrev_b32_e32 v35, 16, v41
	v_and_b32_e32 v42, 0xffff0000, v41
	v_cvt_pk_bf16_f32 v2, v4, v5
	v_mul_f32_e32 v4, 0xbfb8aa3b, v35
	v_lshlrev_b32_e32 v40, 16, v3
	v_and_b32_e32 v41, 0xffff0000, v3
	v_mul_f32_e32 v3, 0xbfb8aa3b, v42
	v_exp_f32_e32 v4, v4
	v_exp_f32_e32 v5, v3
	v_pk_add_f32 v[6:7], v[34:35], v[6:7] op_sel_hi:[0,1]
	v_pk_mul_f32 v[6:7], v[6:7], v[40:41]
	v_pk_add_f32 v[4:5], v[4:5], 1.0 op_sel_hi:[1,0]
	s_nop 0
	s_nop 0
	v_rcp_f32_e32 v5, v5
	s_nop 0
	v_mul_f32_e32 v5, v42, v5
	s_nop 0
	v_rcp_f32_e32 v4, v4
	s_nop 0
	v_mul_f32_e32 v4, v35, v4
	v_pk_mul_f32 v[4:5], v[6:7], v[4:5]
	s_nop 0
	v_cvt_pk_bf16_f32 v3, v4, v5
	global_store_dwordx2 v[0:1], v[2:3], off
	v_or_b32_e32 v0, 32, v178
	v_mov_b32_e32 v1, v179
	v_lshl_add_u64 v[2:3], v[38:39], 0, v[0:1]
	v_lshl_add_u64 v[4:5], v[36:37], 0, v[0:1]
	global_load_dwordx2 v[2:3], v[2:3], off
	v_lshl_add_u64 v[0:1], v[32:33], 0, v[0:1]
	global_load_dwordx2 v[4:5], v[4:5], off
	s_waitcnt vmcnt(1)
	v_lshlrev_b32_e32 v40, 16, v2
	v_and_b32_e32 v41, 0xffff0000, v2
	s_waitcnt vmcnt(0)
	v_lshlrev_b32_e32 v35, 16, v4
	v_and_b32_e32 v4, 0xffff0000, v4
	v_mul_f32_e32 v6, 0xbfb8aa3b, v35
	v_mul_f32_e32 v2, 0xbfb8aa3b, v4
	v_exp_f32_e32 v6, v6
	v_exp_f32_e32 v7, v2
	v_pk_add_f32 v[8:9], v[34:35], v[8:9] op_sel_hi:[0,1]
	v_pk_mul_f32 v[8:9], v[8:9], v[40:41]
	v_pk_add_f32 v[6:7], v[6:7], 1.0 op_sel_hi:[1,0]
	s_nop 0
	s_nop 0
	v_rcp_f32_e32 v7, v7
	s_nop 0
	v_mul_f32_e32 v7, v4, v7
	s_nop 0
	v_rcp_f32_e32 v6, v6
	s_nop 0
	v_mul_f32_e32 v6, v35, v6
	v_pk_mul_f32 v[6:7], v[8:9], v[6:7]
	v_lshlrev_b32_e32 v35, 16, v5
	v_and_b32_e32 v40, 0xffff0000, v5
	v_cvt_pk_bf16_f32 v2, v6, v7
	v_mul_f32_e32 v4, 0xbfb8aa3b, v35
	v_lshlrev_b32_e32 v6, 16, v3
	v_and_b32_e32 v7, 0xffff0000, v3
	v_mul_f32_e32 v3, 0xbfb8aa3b, v40
	v_exp_f32_e32 v4, v4
	v_exp_f32_e32 v5, v3
	v_pk_add_f32 v[8:9], v[34:35], v[10:11] op_sel_hi:[0,1]
	v_pk_mul_f32 v[6:7], v[8:9], v[6:7]
	v_pk_add_f32 v[4:5], v[4:5], 1.0 op_sel_hi:[1,0]
	s_nop 0
	s_nop 0
	v_rcp_f32_e32 v5, v5
	s_nop 0
	v_mul_f32_e32 v5, v40, v5
	s_nop 0
	v_rcp_f32_e32 v4, v4
	s_nop 0
	v_mul_f32_e32 v4, v35, v4
	v_pk_mul_f32 v[4:5], v[6:7], v[4:5]
	s_nop 0
	v_cvt_pk_bf16_f32 v3, v4, v5
	global_store_dwordx2 v[0:1], v[2:3], off
	v_or_b32_e32 v0, 48, v178
	v_mov_b32_e32 v1, v179
	v_lshl_add_u64 v[2:3], v[38:39], 0, v[0:1]
	v_lshl_add_u64 v[4:5], v[36:37], 0, v[0:1]
	global_load_dwordx2 v[2:3], v[2:3], off
	v_lshl_add_u64 v[0:1], v[32:33], 0, v[0:1]
	global_load_dwordx2 v[4:5], v[4:5], off
	s_waitcnt vmcnt(1)
; DI float lo16(unsigned w) { return __uint_as_float(w << 16); }
; DI float hi16(unsigned w) { return __uint_as_float(w & 0xffff0000u); }
; DI float siluf_(float x) { return x / (1.f + __expf(-x)); }
; DI void sgu_item(const Params& p, int l, int it, char* lds) {
;     ...
;   const size_t tok = (size_t)b * S_ + t0 + i;
;   const float bs = p.b_sp[(l * 4 + g) * 128 + i];
;   u16* y = (u16*)(ws_ + OFF_XB);
; #pragma unroll
;   for (int ct = 0; ct < 2; ++ct)
; #pragma unroll
;     for (int g4 = 0; g4 < 4; ++g4) {
;       const int col = g * 64 + ct * 32 + 8 * g4 + 4 * hi;
;       const u32x2 u = *(const u32x2*)(proj + tok * NP + C_DU + col), z = *(const u32x2*)(proj + tok * NP + C_DZ + col);
;       u32x2 v;
;       v[0] = pk2(lo16(u[0]) * (acc[ct][4 * g4] + bs) * siluf_(lo16(z[0])), hi16(u[0]) * (acc[ct][4 * g4 + 1] + bs) * siluf_(hi16(z[0])));
;       v[1] = pk2(lo16(u[1]) * (acc[ct][4 * g4 + 2] + bs) * siluf_(lo16(z[1])), hi16(u[1]) * (acc[ct][4 * g4 + 3] + bs) * siluf_(hi16(z[1])));
;       *(u32x2*)(y + tok * 1024 + 768 + col) = v;
;     }
	v_lshlrev_b32_e32 v8, 16, v2
	v_and_b32_e32 v9, 0xffff0000, v2
	s_waitcnt vmcnt(0)
	v_lshlrev_b32_e32 v35, 16, v4
	v_and_b32_e32 v4, 0xffff0000, v4
	v_mul_f32_e32 v6, 0xbfb8aa3b, v35
	v_mul_f32_e32 v2, 0xbfb8aa3b, v4
	v_exp_f32_e32 v6, v6
	v_exp_f32_e32 v7, v2
	v_pk_add_f32 v[10:11], v[34:35], v[12:13] op_sel_hi:[0,1]
	v_pk_mul_f32 v[8:9], v[10:11], v[8:9]
	v_pk_add_f32 v[6:7], v[6:7], 1.0 op_sel_hi:[1,0]
	s_nop 0
	s_nop 0
	v_rcp_f32_e32 v7, v7
	s_nop 0
	v_mul_f32_e32 v7, v4, v7
	s_nop 0
	v_rcp_f32_e32 v6, v6
	s_nop 0
	v_mul_f32_e32 v6, v35, v6
	v_pk_mul_f32 v[6:7], v[8:9], v[6:7]
	v_lshlrev_b32_e32 v10, 16, v5
	v_and_b32_e32 v11, 0xffff0000, v5
	v_cvt_pk_bf16_f32 v2, v6, v7
	v_mul_f32_e32 v4, 0xbfb8aa3b, v10
	v_lshlrev_b32_e32 v6, 16, v3
	v_and_b32_e32 v7, 0xffff0000, v3
	v_mul_f32_e32 v3, 0xbfb8aa3b, v11
	v_exp_f32_e32 v4, v4
	v_exp_f32_e32 v5, v3
	v_pk_add_f32 v[8:9], v[34:35], v[14:15] op_sel_hi:[0,1]
	v_pk_mul_f32 v[6:7], v[8:9], v[6:7]
	v_mov_b32_e32 v15, 0
	v_pk_add_f32 v[4:5], v[4:5], 1.0 op_sel_hi:[1,0]
	s_nop 0
	s_nop 0
	v_rcp_f32_e32 v5, v5
	s_nop 0
	v_mul_f32_e32 v5, v11, v5
	s_nop 0
	v_rcp_f32_e32 v4, v4
	s_nop 0
	v_mul_f32_e32 v4, v10, v4
	v_pk_mul_f32 v[4:5], v[6:7], v[4:5]
	v_pk_add_f32 v[10:11], v[34:35], v[16:17] op_sel_hi:[0,1]
	v_cvt_pk_bf16_f32 v3, v4, v5
	global_store_dwordx2 v[0:1], v[2:3], off
	v_or_b32_e32 v0, 64, v178
	v_mov_b32_e32 v1, v179
	v_lshl_add_u64 v[2:3], v[38:39], 0, v[0:1]
	v_lshl_add_u64 v[4:5], v[36:37], 0, v[0:1]
	global_load_dwordx2 v[2:3], v[2:3], off
	v_lshl_add_u64 v[0:1], v[32:33], 0, v[0:1]
	global_load_dwordx2 v[4:5], v[4:5], off
	s_waitcnt vmcnt(1)
	v_lshlrev_b32_e32 v8, 16, v2
	v_and_b32_e32 v9, 0xffff0000, v2
	s_waitcnt vmcnt(0)
	v_lshlrev_b32_e32 v12, 16, v4
	v_and_b32_e32 v4, 0xffff0000, v4
	v_mul_f32_e32 v6, 0xbfb8aa3b, v12
	v_mul_f32_e32 v2, 0xbfb8aa3b, v4
	v_exp_f32_e32 v6, v6
	v_exp_f32_e32 v7, v2
	v_pk_mul_f32 v[8:9], v[10:11], v[8:9]
	v_pk_add_f32 v[6:7], v[6:7], 1.0 op_sel_hi:[1,0]
	s_nop 0
	s_nop 0
	v_rcp_f32_e32 v7, v7
	s_nop 0
	v_mul_f32_e32 v7, v4, v7
	s_nop 0
	v_rcp_f32_e32 v6, v6
	s_nop 0
	v_mul_f32_e32 v6, v12, v6
	v_pk_mul_f32 v[6:7], v[8:9], v[6:7]
	v_lshlrev_b32_e32 v10, 16, v5
	v_and_b32_e32 v11, 0xffff0000, v5
	v_cvt_pk_bf16_f32 v2, v6, v7
	v_mul_f32_e32 v4, 0xbfb8aa3b, v10
	v_lshlrev_b32_e32 v6, 16, v3
	v_and_b32_e32 v7, 0xffff0000, v3
	v_mul_f32_e32 v3, 0xbfb8aa3b, v11
	v_exp_f32_e32 v4, v4
	v_exp_f32_e32 v5, v3
	v_pk_add_f32 v[8:9], v[34:35], v[18:19] op_sel_hi:[0,1]
	v_pk_mul_f32 v[6:7], v[8:9], v[6:7]
	v_pk_add_f32 v[4:5], v[4:5], 1.0 op_sel_hi:[1,0]
	s_nop 0
	s_nop 0
	v_rcp_f32_e32 v5, v5
	s_nop 0
	v_mul_f32_e32 v5, v11, v5
	s_nop 0
	v_rcp_f32_e32 v4, v4
	s_nop 0
	v_mul_f32_e32 v4, v10, v4
	v_pk_mul_f32 v[4:5], v[6:7], v[4:5]
	v_pk_add_f32 v[10:11], v[34:35], v[20:21] op_sel_hi:[0,1]
	v_cvt_pk_bf16_f32 v3, v4, v5
	global_store_dwordx2 v[0:1], v[2:3], off
	v_or_b32_e32 v0, 0x50, v178
	v_mov_b32_e32 v1, v179
	v_lshl_add_u64 v[2:3], v[38:39], 0, v[0:1]
	v_lshl_add_u64 v[4:5], v[36:37], 0, v[0:1]
	global_load_dwordx2 v[2:3], v[2:3], off
	v_lshl_add_u64 v[0:1], v[32:33], 0, v[0:1]
	global_load_dwordx2 v[4:5], v[4:5], off
	s_waitcnt vmcnt(1)
	v_lshlrev_b32_e32 v8, 16, v2
	v_and_b32_e32 v9, 0xffff0000, v2
	s_waitcnt vmcnt(0)
	v_lshlrev_b32_e32 v12, 16, v4
	v_and_b32_e32 v4, 0xffff0000, v4
	v_mul_f32_e32 v6, 0xbfb8aa3b, v12
	v_mul_f32_e32 v2, 0xbfb8aa3b, v4
	v_exp_f32_e32 v6, v6
	v_exp_f32_e32 v7, v2
	v_pk_mul_f32 v[8:9], v[10:11], v[8:9]
	v_pk_add_f32 v[6:7], v[6:7], 1.0 op_sel_hi:[1,0]
	s_nop 0
	s_nop 0
	v_rcp_f32_e32 v7, v7
	s_nop 0
	v_mul_f32_e32 v7, v4, v7
	s_nop 0
	v_rcp_f32_e32 v6, v6
	s_nop 0
	v_mul_f32_e32 v6, v12, v6
	v_pk_mul_f32 v[6:7], v[8:9], v[6:7]
	v_lshlrev_b32_e32 v10, 16, v5
	v_and_b32_e32 v11, 0xffff0000, v5
	v_cvt_pk_bf16_f32 v2, v6, v7
	v_mul_f32_e32 v4, 0xbfb8aa3b, v10
	v_lshlrev_b32_e32 v6, 16, v3
	v_and_b32_e32 v7, 0xffff0000, v3
	v_mul_f32_e32 v3, 0xbfb8aa3b, v11
	v_exp_f32_e32 v4, v4
	v_exp_f32_e32 v5, v3
	v_pk_add_f32 v[8:9], v[34:35], v[22:23] op_sel_hi:[0,1]
	v_pk_mul_f32 v[6:7], v[8:9], v[6:7]
	v_pk_add_f32 v[4:5], v[4:5], 1.0 op_sel_hi:[1,0]
	s_nop 0
	s_nop 0
	v_rcp_f32_e32 v5, v5
	s_nop 0
	v_mul_f32_e32 v5, v11, v5
	s_nop 0
	v_rcp_f32_e32 v4, v4
	s_nop 0
	v_mul_f32_e32 v4, v10, v4
	v_pk_mul_f32 v[4:5], v[6:7], v[4:5]
	v_pk_add_f32 v[10:11], v[34:35], v[24:25] op_sel_hi:[0,1]
	v_cvt_pk_bf16_f32 v3, v4, v5
	global_store_dwordx2 v[0:1], v[2:3], off
	v_or_b32_e32 v0, 0x60, v178
	v_mov_b32_e32 v1, v179
	v_lshl_add_u64 v[2:3], v[38:39], 0, v[0:1]
	v_lshl_add_u64 v[4:5], v[36:37], 0, v[0:1]
	global_load_dwordx2 v[2:3], v[2:3], off
	v_lshl_add_u64 v[0:1], v[32:33], 0, v[0:1]
	global_load_dwordx2 v[4:5], v[4:5], off
	v_or_b32_e32 v178, 0x70, v178
	s_waitcnt vmcnt(1)
; DI float lo16(unsigned w) { return __uint_as_float(w << 16); }
; DI float hi16(unsigned w) { return __uint_as_float(w & 0xffff0000u); }
; DI float siluf_(float x) { return x / (1.f + __expf(-x)); }
; DI void pool_item(const Params& p, int l, int it, char* lds) {
;     ...
;   u32x4 cv[6];
; #pragma unroll
;   for (int i = 0; i < 6; ++i) {
;     const int c = tid + 256 * i, row = c >> 5, ch = c & 31; const int t = q0 - 16 + row;
;     cv[i] = u32x4{0u, 0u, 0u, 0u};
;     if (t >= 0) cv[i] = *(const u32x4*)(proj + ((size_t)b * S_ + t) * NP + C_CIN + ch * 8);
;   }
; DI void sgu_item(const Params& p, int l, int it, char* lds) {
;     ...
;   const size_t tok = (size_t)b * S_ + t0 + i;
;   const float bs = p.b_sp[(l * 4 + g) * 128 + i];
;   u16* y = (u16*)(ws_ + OFF_XB);
; #pragma unroll
;   for (int ct = 0; ct < 2; ++ct)
; #pragma unroll
;     for (int g4 = 0; g4 < 4; ++g4) {
;       const int col = g * 64 + ct * 32 + 8 * g4 + 4 * hi;
;       const u32x2 u = *(const u32x2*)(proj + tok * NP + C_DU + col), z = *(const u32x2*)(proj + tok * NP + C_DZ + col);
;       u32x2 v;
;       v[0] = pk2(lo16(u[0]) * (acc[ct][4 * g4] + bs) * siluf_(lo16(z[0])), hi16(u[0]) * (acc[ct][4 * g4 + 1] + bs) * siluf_(hi16(z[0])));
;       v[1] = pk2(lo16(u[1]) * (acc[ct][4 * g4 + 2] + bs) * siluf_(lo16(z[1])), hi16(u[1]) * (acc[ct][4 * g4 + 3] + bs) * siluf_(hi16(z[1])));
;       *(u32x2*)(y + tok * 1024 + 768 + col) = v;
;     }
	v_lshlrev_b32_e32 v8, 16, v2
	v_and_b32_e32 v9, 0xffff0000, v2
	s_waitcnt vmcnt(0)
	v_lshlrev_b32_e32 v12, 16, v4
	v_and_b32_e32 v4, 0xffff0000, v4
	v_mul_f32_e32 v6, 0xbfb8aa3b, v12
	v_mul_f32_e32 v2, 0xbfb8aa3b, v4
	v_exp_f32_e32 v6, v6
	v_exp_f32_e32 v7, v2
	v_pk_mul_f32 v[8:9], v[10:11], v[8:9]
	v_pk_add_f32 v[6:7], v[6:7], 1.0 op_sel_hi:[1,0]
	s_nop 0
	s_nop 0
	v_rcp_f32_e32 v7, v7
	s_nop 0
	v_mul_f32_e32 v7, v4, v7
	v_mov_b32_e32 v14, 0
	v_rcp_f32_e32 v6, v6
	s_nop 0
	v_mul_f32_e32 v6, v12, v6
	v_pk_mul_f32 v[6:7], v[8:9], v[6:7]
	v_lshlrev_b32_e32 v10, 16, v5
	v_and_b32_e32 v11, 0xffff0000, v5
	v_cvt_pk_bf16_f32 v2, v6, v7
	v_mul_f32_e32 v4, 0xbfb8aa3b, v10
	v_lshlrev_b32_e32 v6, 16, v3
	v_and_b32_e32 v7, 0xffff0000, v3
	v_mul_f32_e32 v3, 0xbfb8aa3b, v11
	v_exp_f32_e32 v4, v4
	v_exp_f32_e32 v5, v3
	v_pk_add_f32 v[8:9], v[34:35], v[26:27] op_sel_hi:[0,1]
	v_pk_mul_f32 v[6:7], v[8:9], v[6:7]
	v_pk_add_f32 v[4:5], v[4:5], 1.0 op_sel_hi:[1,0]
	s_nop 0
	s_nop 0
	v_rcp_f32_e32 v5, v5
	s_nop 0
	v_mul_f32_e32 v5, v11, v5
	v_mov_b32_e32 v13, 0
	v_rcp_f32_e32 v4, v4
	s_nop 0
	v_mul_f32_e32 v4, v10, v4
	v_pk_mul_f32 v[4:5], v[6:7], v[4:5]
	v_pk_add_f32 v[8:9], v[34:35], v[28:29] op_sel_hi:[0,1]
	v_cvt_pk_bf16_f32 v3, v4, v5
	global_store_dwordx2 v[0:1], v[2:3], off
	v_lshl_add_u64 v[0:1], v[38:39], 0, v[178:179]
	v_lshl_add_u64 v[2:3], v[36:37], 0, v[178:179]
	global_load_dwordx2 v[0:1], v[0:1], off
	s_nop 0
	global_load_dwordx2 v[2:3], v[2:3], off
	s_waitcnt vmcnt(1)
	v_lshlrev_b32_e32 v6, 16, v0
	v_and_b32_e32 v7, 0xffff0000, v0
	s_waitcnt vmcnt(0)
	v_lshlrev_b32_e32 v10, 16, v2
	v_and_b32_e32 v2, 0xffff0000, v2
	v_mul_f32_e32 v4, 0xbfb8aa3b, v10
	v_mul_f32_e32 v0, 0xbfb8aa3b, v2
	v_exp_f32_e32 v4, v4
	v_exp_f32_e32 v5, v0
	v_pk_mul_f32 v[6:7], v[8:9], v[6:7]
	v_pk_add_f32 v[4:5], v[4:5], 1.0 op_sel_hi:[1,0]
	s_nop 0
	s_nop 0
	v_rcp_f32_e32 v5, v5
	s_nop 0
	v_mul_f32_e32 v5, v2, v5
	v_mov_b32_e32 v12, 0
	v_rcp_f32_e32 v4, v4
	s_nop 0
	v_mul_f32_e32 v4, v10, v4
	v_pk_mul_f32 v[4:5], v[6:7], v[4:5]
	v_lshlrev_b32_e32 v8, 16, v3
	v_and_b32_e32 v9, 0xffff0000, v3
	v_cvt_pk_bf16_f32 v0, v4, v5
	v_mul_f32_e32 v2, 0xbfb8aa3b, v8
	v_lshlrev_b32_e32 v4, 16, v1
	v_and_b32_e32 v5, 0xffff0000, v1
	v_mul_f32_e32 v1, 0xbfb8aa3b, v9
	v_exp_f32_e32 v2, v2
	v_exp_f32_e32 v3, v1
	v_pk_add_f32 v[6:7], v[34:35], v[30:31] op_sel_hi:[0,1]
	v_pk_mul_f32 v[4:5], v[6:7], v[4:5]
	v_pk_add_f32 v[2:3], v[2:3], 1.0 op_sel_hi:[1,0]
	s_nop 0
	s_nop 0
	v_rcp_f32_e32 v3, v3
	s_nop 0
	v_mul_f32_e32 v3, v9, v3
	s_mov_b64 s[0:1], 0
	v_rcp_f32_e32 v2, v2
	s_nop 0
	v_mul_f32_e32 v2, v8, v2
	v_pk_mul_f32 v[2:3], v[4:5], v[2:3]
	v_mov_b32_e32 v8, 0
	v_cvt_pk_bf16_f32 v1, v2, v3
	v_lshl_add_u64 v[2:3], v[32:33], 0, v[178:179]
	global_store_dwordx2 v[2:3], v[0:1], off
	s_add_u32 s0, s90, s0
	s_addc_u32 s1, s91, s1
	v_add_u32_e32 v0, -16, v92
	v_lshlrev_b32_e32 v122, 3, v121
	v_ashrrev_i32_e32 v1, 5, v121
	s_add_u32 s2, s0, 0x4a50000
	v_and_b32_e32 v123, 0xf8, v122
	v_add_u32_e32 v1, v1, v0
	s_addc_u32 s3, s1, 0
	v_cmp_lt_i32_e32 vcc, -1, v1
	v_lshlrev_b32_e32 v178, 1, v123
	s_and_saveexec_b64 s[4:5], vcc
	s_cbranch_execz .LBB0_447
	v_add_u32_e32 v1, s80, v1
	v_mov_b64_e32 v[2:3], s[2:3]
	v_mad_u64_u32 v[2:3], s[8:9], v1, s33, v[2:3]
	v_lshl_add_u64 v[2:3], v[2:3], 0, v[178:179]
	global_load_dwordx4 v[12:15], v[2:3], off offset:3840

; #define MFMA(a, b, c) __builtin_amdgcn_mfma_f32_32x32x16_bf16((a), (b), (c), 0, 0, 0)
; DI float bf2f(u16 v) { return __uint_as_float((unsigned)v << 16); }
; DI u16 f2bf(float x) { return (u16)(pk2(x, 0.f) & 0xffffu); }
; DI float lo16(unsigned w) { return __uint_as_float(w << 16); }
; DI float hi16(unsigned w) { return __uint_as_float(w & 0xffff0000u); }
; DI float siluf_(float x) { return x / (1.f + __expf(-x)); }
; DI void pool_item(const Params& p, int l, int it, char* lds) {
;     ...
;     const int ch = tid, w = 2 << g;
;     float s = 0.f;
;     for (int r = 17 - w; r <= 16; ++r) s += bf2f(cin[r * 256 + ch]);
; #pragma unroll 4
;     for (int i = 0; i < 32; ++i) {
;       const int t = q0 + i; const int cnt = (t + 1 < w) ? t + 1 : w;
;       const float self = bf2f(cin[(i + 16) * 256 + ch]);
;       *(u16*)(pl + i * 528 + ch * 2) = f2bf(s / (float)cnt - self);
;       s += bf2f(cin[(i + 17) * 256 + ch]) - bf2f(cin[(i + 17 - w) * 256 + ch]);
;     }
;   }
;   __syncthreads();
;   f32x16 acc[2];
; #pragma unroll
;   for (int r = 0; r < 16; ++r) { acc[0][r] = 0.f; acc[1][r] = 0.f; }
; #pragma unroll
;   for (int s4 = 0; s4 < 4; ++s4) {
;     const bf16x8 bf = *(const bf16x8*)(pl + l31 * 528 + (g * 64 + 16 * s4 + 8 * hi) * 2);
; #pragma unroll
;     for (int dt = 0; dt < 2; ++dt) acc[dt] = MFMA(af[s4 * 2 + dt], bf, acc[dt]);
;   }
;   u16* y = (u16*)(ws_ + OFF_XB);
; #pragma unroll
;   for (int dt = 0; dt < 2; ++dt)
; #pragma unroll
;     for (int g4 = 0; g4 < 4; ++g4) {
;       const int col = g * 64 + dt * 32 + 8 * g4 + 4 * hi;
;       const f32x4 ps = psv[dt * 4 + g4];
;       const u32x2 z = zv[dt * 4 + g4];
;       u32x2 v;
;       v[0] = pk2(acc[dt][4 * g4] * ps[0] * siluf_(lo16(z[0])), acc[dt][4 * g4 + 1] * ps[1] * siluf_(hi16(z[0])));
;       v[1] = pk2(acc[dt][4 * g4 + 2] * ps[2] * siluf_(lo16(z[1])), acc[dt][4 * g4 + 3] * ps[3] * siluf_(hi16(z[1])));
;       *(u32x2*)(y + tok * 1024 + 512 + col) = v;
.LBB0_464:
	v_add_u32_e32 v15, s2, v118
	v_add_u32_e32 v16, 1, v15
	v_min_i32_e32 v16, v16, v9
	v_cvt_f32_i32_e32 v16, v16
	s_waitcnt lgkmcnt(0)
	v_lshlrev_b32_e32 v14, 16, v14
	s_add_i32 s2, s2, 4
	s_cmp_lg_u32 s2, 32
	s_nop 0
	v_rcp_f32_e32 v16, v16
	s_nop 0
	v_mul_f32_e32 v16, v12, v16
	v_sub_f32_e32 v14, v16, v14
	v_cvt_pk_bf16_f32 v14, v14, s0
	ds_write_b16 v11, v14
	v_add_u32_e32 v16, v13, v10
	ds_read_u16 v14, v16 offset:512
	ds_read_u16 v17, v13 offset:512
	s_waitcnt lgkmcnt(1)
	v_lshlrev_b32_e32 v14, 16, v14
	s_waitcnt lgkmcnt(0)
	v_lshlrev_b32_e32 v17, 16, v17
	v_sub_f32_e32 v14, v17, v14
	v_add_f32_e32 v12, v12, v14
	v_add_u32_e32 v14, 2, v15
	v_min_i32_e32 v14, v14, v9
	v_cvt_f32_i32_e32 v14, v14
	s_nop 0
	v_rcp_f32_e32 v14, v14
	s_nop 0
	v_mul_f32_e32 v14, v12, v14
	v_sub_f32_e32 v14, v14, v17
	v_cvt_pk_bf16_f32 v14, v14, s0
	ds_write_b16 v11, v14 offset:528
	ds_read_u16 v14, v16 offset:1024
	ds_read_u16 v17, v13 offset:1024
	s_waitcnt lgkmcnt(1)
	v_lshlrev_b32_e32 v14, 16, v14
	s_waitcnt lgkmcnt(0)
	v_lshlrev_b32_e32 v17, 16, v17
	v_sub_f32_e32 v14, v17, v14
	v_add_f32_e32 v12, v12, v14
	v_add_u32_e32 v14, 3, v15
	v_min_i32_e32 v14, v14, v9
	v_cvt_f32_i32_e32 v14, v14
	s_nop 0
	v_rcp_f32_e32 v14, v14
	s_nop 0
	v_mul_f32_e32 v14, v12, v14
	v_sub_f32_e32 v14, v14, v17
	v_cvt_pk_bf16_f32 v14, v14, s0
	ds_write_b16 v11, v14 offset:1056
	ds_read_u16 v14, v16 offset:1536
	ds_read_u16 v17, v13 offset:1536
	s_waitcnt lgkmcnt(1)
	v_lshlrev_b32_e32 v14, 16, v14
	s_waitcnt lgkmcnt(0)
	v_lshlrev_b32_e32 v17, 16, v17
	v_sub_f32_e32 v14, v17, v14
	v_add_f32_e32 v12, v12, v14
	v_add_u32_e32 v14, 4, v15
	v_min_i32_e32 v14, v14, v9
	v_cvt_f32_i32_e32 v14, v14
	s_nop 0
	v_rcp_f32_e32 v14, v14
	s_nop 0
	v_mul_f32_e32 v14, v12, v14
	v_sub_f32_e32 v14, v14, v17
	v_cvt_pk_bf16_f32 v14, v14, s0
	ds_write_b16 v11, v14 offset:1584
	v_add_u32_e32 v15, 0x800, v13
	ds_read_u16 v14, v13 offset:2048
	ds_read_u16 v13, v16 offset:2048
	v_add_u32_e32 v11, 0x840, v11
	s_waitcnt lgkmcnt(1)
	v_lshlrev_b32_e32 v16, 16, v14
	s_waitcnt lgkmcnt(0)
	v_lshlrev_b32_e32 v13, 16, v13
	v_sub_f32_e32 v13, v16, v13
	v_add_f32_e32 v12, v12, v13
	v_mov_b32_e32 v13, v15
	s_cbranch_scc1 .LBB0_464
	v_mul_u32_u24_e32 v9, 0x210, v120
	v_and_b32_e32 v8, 0xffffff80, v8
	v_add3_u32 v124, v9, v178, v8
	s_barrier
	ds_read_b128 v[8:11], v124 offset:24576
	ds_read_b128 v[120:123], v124 offset:24608
	s_waitcnt vmcnt(23) lgkmcnt(1)
	v_mfma_f32_32x32x16_bf16 v[16:31], v[0:3], v[8:11], 0
	v_mov_b32_e32 v183, v179
	s_mov_b64 s[2:3], 0xd390000
	v_mov_b32_e32 v185, v179
	s_mov_b64 s[4:5], 0x8000
	v_add_u32_e32 v118, 32, v118
	s_waitcnt vmcnt(22)
	v_mfma_f32_32x32x16_bf16 v[0:15], v[4:7], v[8:11], 0
	s_waitcnt vmcnt(21) lgkmcnt(0)
	v_mfma_f32_32x32x16_bf16 v[16:31], v[76:79], v[120:123], v[16:31]
	ds_read_b128 v[76:79], v124 offset:24640
	s_waitcnt vmcnt(19)
	v_mfma_f32_32x32x16_bf16 v[0:15], v[84:87], v[120:123], v[0:15]
	s_waitcnt lgkmcnt(0)
	v_mfma_f32_32x32x16_bf16 v[16:31], v[64:67], v[76:79], v[16:31]
	ds_read_b128 v[64:67], v124 offset:24672
	s_waitcnt vmcnt(18)
	v_mfma_f32_32x32x16_bf16 v[0:15], v[80:83], v[76:79], v[0:15]
	s_waitcnt vmcnt(17) lgkmcnt(0)
	v_mfma_f32_32x32x16_bf16 v[16:31], v[68:71], v[64:67], v[16:31]
	s_waitcnt vmcnt(11)
	v_lshlrev_b32_e32 v68, 16, v112
	v_and_b32_e32 v69, 0xffff0000, v112
	v_mfma_f32_32x32x16_bf16 v[0:15], v[72:75], v[64:67], v[0:15]
	v_mul_f32_e32 v66, 0xbfb8aa3b, v68
	s_nop 6
	v_mul_f32_e64 v16, v60, v16
	v_mul_f32_e64 v17, v61, v17
	v_mul_f32_e32 v60, 0xbfb8aa3b, v69
	v_exp_f32_e32 v66, v66
	v_exp_f32_e32 v67, v60
	v_lshlrev_b64 v[64:65], 11, v[114:115]
	v_lshl_add_u64 v[64:65], s[0:1], 0, v[64:65]
	s_mov_b64 s[0:1], 0x2a40400
	v_pk_add_f32 v[60:61], v[66:67], 1.0 op_sel_hi:[1,0]
	v_lshl_add_u64 v[64:65], v[64:65], 0, s[0:1]
	v_pk_mul_f32 v[18:19], v[62:63], v[18:19]
	v_pk_mul_f32 v[20:21], v[56:57], v[20:21]
	v_pk_mul_f32 v[22:23], v[58:59], v[22:23]
	v_rcp_f32_e32 v61, v61
	s_nop 0
	v_mul_f32_e32 v61, v69, v61
	s_waitcnt vmcnt(7)
	v_pk_mul_f32 v[0:1], v[44:45], v[0:1]
	v_pk_mul_f32 v[2:3], v[46:47], v[2:3]
	v_rcp_f32_e32 v60, v60
	s_nop 0
	v_mul_f32_e32 v60, v68, v60
	v_pk_mul_f32 v[16:17], v[60:61], v[16:17]
	v_lshlrev_b32_e32 v61, 16, v113
	v_and_b32_e32 v66, 0xffff0000, v113
	v_cvt_pk_bf16_f32 v60, v16, v17
	v_mul_f32_e32 v16, 0xbfb8aa3b, v61
	v_mul_f32_e32 v17, 0xbfb8aa3b, v66
	v_exp_f32_e32 v16, v16
	v_exp_f32_e32 v17, v17
	s_nop 0
	v_pk_add_f32 v[16:17], v[16:17], 1.0 op_sel_hi:[1,0]
	s_nop 0
	s_nop 0
	v_rcp_f32_e32 v17, v17
	s_nop 0
	v_mul_f32_e32 v17, v66, v17
	s_nop 0
	v_rcp_f32_e32 v16, v16
	s_nop 0
	v_mul_f32_e32 v16, v61, v16
	v_pk_mul_f32 v[16:17], v[16:17], v[18:19]
	s_nop 0
	v_cvt_pk_bf16_f32 v61, v16, v17
	v_lshl_add_u64 v[16:17], v[110:111], 1, v[64:65]
	global_store_dwordx2 v[16:17], v[60:61], off
	v_lshlrev_b32_e32 v60, 16, v108
	v_and_b32_e32 v61, 0xffff0000, v108
	v_mul_f32_e32 v18, 0xbfb8aa3b, v60
	v_mul_f32_e32 v19, 0xbfb8aa3b, v61
	v_exp_f32_e32 v18, v18
	v_exp_f32_e32 v19, v19
	s_nop 0
	v_pk_add_f32 v[18:19], v[18:19], 1.0 op_sel_hi:[1,0]
	s_nop 0
	s_nop 0
	v_rcp_f32_e32 v19, v19
	s_nop 0
	v_mul_f32_e32 v19, v61, v19
	s_nop 0
	v_rcp_f32_e32 v18, v18
	s_nop 0
	v_mul_f32_e32 v18, v60, v18
	v_pk_mul_f32 v[18:19], v[18:19], v[20:21]
	v_and_b32_e32 v56, 0xffff0000, v109
	v_cvt_pk_bf16_f32 v18, v18, v19
	v_lshlrev_b32_e32 v19, 16, v109
	v_mul_f32_e32 v20, 0xbfb8aa3b, v19
	v_mul_f32_e32 v21, 0xbfb8aa3b, v56
	v_exp_f32_e32 v20, v20
	v_exp_f32_e32 v21, v21
	s_nop 0
	v_pk_add_f32 v[20:21], v[20:21], 1.0 op_sel_hi:[1,0]
	s_nop 0
	s_nop 0
	v_rcp_f32_e32 v21, v21
	s_nop 0
	v_mul_f32_e32 v21, v56, v21
	s_nop 0
	v_rcp_f32_e32 v20, v20
; DI float lo16(unsigned w) { return __uint_as_float(w << 16); }
; DI float hi16(unsigned w) { return __uint_as_float(w & 0xffff0000u); }
; DI float sigmoidf_(float x) { return 1.f / (1.f + __expf(-x)); }
; DI float siluf_(float x) { return x / (1.f + __expf(-x)); }
; DI void pool_item(const Params& p, int l, int it, char* lds) {
;     ...
; #pragma unroll
;   for (int dt = 0; dt < 2; ++dt)
; #pragma unroll
;     for (int g4 = 0; g4 < 4; ++g4) {
;       const int col = g * 64 + dt * 32 + 8 * g4 + 4 * hi;
;       const f32x4 ps = psv[dt * 4 + g4];
;       const u32x2 z = zv[dt * 4 + g4];
;       u32x2 v;
;       v[0] = pk2(acc[dt][4 * g4] * ps[0] * siluf_(lo16(z[0])), acc[dt][4 * g4 + 1] * ps[1] * siluf_(hi16(z[0])));
;       v[1] = pk2(acc[dt][4 * g4 + 2] * ps[2] * siluf_(lo16(z[1])), acc[dt][4 * g4 + 3] * ps[3] * siluf_(hi16(z[1])));
;       *(u32x2*)(y + tok * 1024 + 512 + col) = v;
;     }
	s_nop 0
	v_mul_f32_e32 v20, v19, v20
	v_pk_mul_f32 v[20:21], v[20:21], v[22:23]
	v_lshlrev_b32_e32 v22, 16, v104
	v_cvt_pk_bf16_f32 v19, v20, v21
	v_lshl_add_u64 v[20:21], v[106:107], 1, v[64:65]
	v_and_b32_e32 v23, 0xffff0000, v104
	global_store_dwordx2 v[20:21], v[18:19], off
	v_mul_f32_e32 v18, 0xbfb8aa3b, v22
	v_mul_f32_e32 v19, 0xbfb8aa3b, v23
	v_exp_f32_e32 v18, v18
	v_exp_f32_e32 v19, v19
	v_pk_mul_f32 v[20:21], v[52:53], v[24:25]
	v_pk_add_f32 v[18:19], v[18:19], 1.0 op_sel_hi:[1,0]
	s_nop 0
	s_nop 0
	v_rcp_f32_e32 v19, v19
	s_nop 0
	v_mul_f32_e32 v19, v23, v19
	s_nop 0
	v_rcp_f32_e32 v18, v18
	s_nop 0
	v_mul_f32_e32 v18, v22, v18
	v_pk_mul_f32 v[18:19], v[18:19], v[20:21]
	v_and_b32_e32 v24, 0xffff0000, v105
	v_cvt_pk_bf16_f32 v18, v18, v19
	v_lshlrev_b32_e32 v19, 16, v105
	v_mul_f32_e32 v20, 0xbfb8aa3b, v19
	v_mul_f32_e32 v21, 0xbfb8aa3b, v24
	v_exp_f32_e32 v20, v20
	v_exp_f32_e32 v21, v21
	v_pk_mul_f32 v[22:23], v[54:55], v[26:27]
	v_pk_add_f32 v[20:21], v[20:21], 1.0 op_sel_hi:[1,0]
	s_nop 0
	s_nop 0
	v_rcp_f32_e32 v21, v21
	s_nop 0
	v_mul_f32_e32 v21, v24, v21
	s_nop 0
	v_rcp_f32_e32 v20, v20
	s_nop 0
	v_mul_f32_e32 v20, v19, v20
	v_pk_mul_f32 v[20:21], v[20:21], v[22:23]
	v_lshlrev_b32_e32 v22, 16, v100
	v_cvt_pk_bf16_f32 v19, v20, v21
	v_lshl_add_u64 v[20:21], v[102:103], 1, v[64:65]
	v_and_b32_e32 v23, 0xffff0000, v100
	global_store_dwordx2 v[20:21], v[18:19], off
	v_mul_f32_e32 v18, 0xbfb8aa3b, v22
	v_mul_f32_e32 v19, 0xbfb8aa3b, v23
	v_exp_f32_e32 v18, v18
	v_exp_f32_e32 v19, v19
	v_pk_mul_f32 v[20:21], v[48:49], v[28:29]
	v_pk_add_f32 v[18:19], v[18:19], 1.0 op_sel_hi:[1,0]
	s_nop 0
	s_nop 0
	v_rcp_f32_e32 v19, v19
	s_nop 0
	v_mul_f32_e32 v19, v23, v19
	s_nop 0
	v_rcp_f32_e32 v18, v18
	s_nop 0
	v_mul_f32_e32 v18, v22, v18
	v_pk_mul_f32 v[18:19], v[18:19], v[20:21]
	v_and_b32_e32 v24, 0xffff0000, v101
	v_cvt_pk_bf16_f32 v18, v18, v19
	v_lshlrev_b32_e32 v19, 16, v101
	v_mul_f32_e32 v20, 0xbfb8aa3b, v19
	v_mul_f32_e32 v21, 0xbfb8aa3b, v24
	v_exp_f32_e32 v20, v20
	v_exp_f32_e32 v21, v21
	v_pk_mul_f32 v[22:23], v[50:51], v[30:31]
	v_pk_add_f32 v[20:21], v[20:21], 1.0 op_sel_hi:[1,0]
	s_nop 0
	s_nop 0
	v_rcp_f32_e32 v21, v21
	s_nop 0
	v_mul_f32_e32 v21, v24, v21
	s_nop 0
	v_rcp_f32_e32 v20, v20
	s_nop 0
	v_mul_f32_e32 v20, v19, v20
	v_pk_mul_f32 v[20:21], v[20:21], v[22:23]
	s_nop 0
	v_cvt_pk_bf16_f32 v19, v20, v21
	v_lshl_add_u64 v[20:21], v[98:99], 1, v[64:65]
	global_store_dwordx2 v[20:21], v[18:19], off
	s_waitcnt vmcnt(7)
	v_lshlrev_b32_e32 v20, 16, v96
	v_and_b32_e32 v21, 0xffff0000, v96
	v_mul_f32_e32 v18, 0xbfb8aa3b, v20
	v_mul_f32_e32 v19, 0xbfb8aa3b, v21
	v_exp_f32_e32 v18, v18
	v_exp_f32_e32 v19, v19
	s_nop 0
	v_pk_add_f32 v[18:19], v[18:19], 1.0 op_sel_hi:[1,0]
	s_nop 0
	s_nop 0
	v_rcp_f32_e32 v19, v19
	s_nop 0
	v_mul_f32_e32 v19, v21, v19
	s_nop 0
	v_rcp_f32_e32 v18, v18
	s_nop 0
	v_mul_f32_e32 v18, v20, v18
	v_pk_mul_f32 v[0:1], v[18:19], v[0:1]
	v_and_b32_e32 v20, 0xffff0000, v97
	v_cvt_pk_bf16_f32 v0, v0, v1
	v_lshlrev_b32_e32 v1, 16, v97
	v_mul_f32_e32 v18, 0xbfb8aa3b, v1
	v_mul_f32_e32 v19, 0xbfb8aa3b, v20
	v_exp_f32_e32 v18, v18
	v_exp_f32_e32 v19, v19
	s_nop 0
	v_pk_add_f32 v[18:19], v[18:19], 1.0 op_sel_hi:[1,0]
	s_nop 0
	s_nop 0
	v_rcp_f32_e32 v19, v19
	s_nop 0
	v_mul_f32_e32 v19, v20, v19
	s_nop 0
	v_rcp_f32_e32 v18, v18
	s_nop 0
	v_mul_f32_e32 v18, v1, v18
	v_pk_mul_f32 v[2:3], v[18:19], v[2:3]
	s_waitcnt vmcnt(6)
	v_lshlrev_b32_e32 v18, 16, v92
	v_cvt_pk_bf16_f32 v1, v2, v3
	v_lshl_add_u64 v[2:3], v[94:95], 1, v[64:65]
	v_and_b32_e32 v19, 0xffff0000, v92
	global_store_dwordx2 v[2:3], v[0:1], off
	v_mul_f32_e32 v0, 0xbfb8aa3b, v18
	v_mul_f32_e32 v1, 0xbfb8aa3b, v19
	v_exp_f32_e32 v0, v0
	v_exp_f32_e32 v1, v1
	v_pk_mul_f32 v[2:3], v[40:41], v[4:5]
	v_pk_add_f32 v[0:1], v[0:1], 1.0 op_sel_hi:[1,0]
	s_nop 0
	s_nop 0
	v_rcp_f32_e32 v1, v1
	s_nop 0
	v_mul_f32_e32 v1, v19, v1
	s_nop 0
	v_rcp_f32_e32 v0, v0
	s_nop 0
	v_mul_f32_e32 v0, v18, v0
	v_pk_mul_f32 v[0:1], v[0:1], v[2:3]
	v_and_b32_e32 v18, 0xffff0000, v93
	v_cvt_pk_bf16_f32 v0, v0, v1
	v_lshlrev_b32_e32 v1, 16, v93
	v_mul_f32_e32 v2, 0xbfb8aa3b, v1
	v_mul_f32_e32 v3, 0xbfb8aa3b, v18
	v_exp_f32_e32 v2, v2
	v_exp_f32_e32 v3, v3
	v_pk_mul_f32 v[4:5], v[42:43], v[6:7]
	v_pk_add_f32 v[2:3], v[2:3], 1.0 op_sel_hi:[1,0]
	s_nop 0
	s_nop 0
	v_rcp_f32_e32 v3, v3
	s_nop 0
	v_mul_f32_e32 v3, v18, v3
	s_nop 0
	v_rcp_f32_e32 v2, v2
	s_nop 0
	v_mul_f32_e32 v2, v1, v2
	v_pk_mul_f32 v[2:3], v[2:3], v[4:5]
	s_waitcnt vmcnt(6)
	v_lshlrev_b32_e32 v4, 16, v90
	v_cvt_pk_bf16_f32 v1, v2, v3
	v_and_b32_e32 v5, 0xffff0000, v90
	global_store_dwordx2 v[16:17], v[0:1], off offset:80
	v_mul_f32_e32 v0, 0xbfb8aa3b, v4
	v_mul_f32_e32 v1, 0xbfb8aa3b, v5
	v_exp_f32_e32 v0, v0
	v_exp_f32_e32 v1, v1
	v_pk_mul_f32 v[2:3], v[36:37], v[8:9]
	v_pk_add_f32 v[0:1], v[0:1], 1.0 op_sel_hi:[1,0]
	s_nop 0
	s_nop 0
	v_rcp_f32_e32 v1, v1
	s_nop 0
	v_mul_f32_e32 v1, v5, v1
	s_nop 0
	v_rcp_f32_e32 v0, v0
	s_nop 0
	v_mul_f32_e32 v0, v4, v0
	v_pk_mul_f32 v[0:1], v[0:1], v[2:3]
	v_and_b32_e32 v6, 0xffff0000, v91
	v_cvt_pk_bf16_f32 v0, v0, v1
	v_lshlrev_b32_e32 v1, 16, v91
	v_mul_f32_e32 v2, 0xbfb8aa3b, v1
	v_mul_f32_e32 v3, 0xbfb8aa3b, v6
	v_exp_f32_e32 v2, v2
	v_exp_f32_e32 v3, v3
	v_pk_mul_f32 v[4:5], v[38:39], v[10:11]
	v_pk_add_f32 v[2:3], v[2:3], 1.0 op_sel_hi:[1,0]
	s_nop 0
	s_nop 0
	v_rcp_f32_e32 v3, v3
	s_nop 0
	v_mul_f32_e32 v3, v6, v3
	s_nop 0
	v_rcp_f32_e32 v2, v2
	s_nop 0
	v_mul_f32_e32 v2, v1, v2
	v_pk_mul_f32 v[2:3], v[2:3], v[4:5]
	s_waitcnt vmcnt(6)
; DI float lo16(unsigned w) { return __uint_as_float(w << 16); }
; DI float hi16(unsigned w) { return __uint_as_float(w & 0xffff0000u); }
; DI float siluf_(float x) { return x / (1.f + __expf(-x)); }
; DI void pool_item(const Params& p, int l, int it, char* lds) {
;     ...
;       v[0] = pk2(acc[dt][4 * g4] * ps[0] * siluf_(lo16(z[0])), acc[dt][4 * g4 + 1] * ps[1] * siluf_(hi16(z[0])));
;       v[1] = pk2(acc[dt][4 * g4 + 2] * ps[2] * siluf_(lo16(z[1])), acc[dt][4 * g4 + 3] * ps[3] * siluf_(hi16(z[1])));
;       *(u32x2*)(y + tok * 1024 + 512 + col) = v;
; DI void dilcomb_item(const Params& p, int it) {
;     ...
; #pragma unroll
;   for (int i = 0; i < 4; ++i) {
;     const int idx = it * 1024 + i * 256 + threadIdx.x;
;     const size_t tok = idx >> 5; const int c8 = idx & 31, h = c8 >> 3;
;     const float l0 = lse[((size_t)0 * T_ + tok) * 4 + h], l1 = lse[((size_t)1 * T_ + tok) * 4 + h], l2 = lse[((size_t)2 * T_ + tok) * 4 + h];
;     const float mx = fmaxf(l0, fmaxf(l1, l2));
;     float w0 = __expf(l0 - mx), w1 = __expf(l1 - mx), w2 = __expf(l2 - mx);
;     const float iw = 1.f / (w0 + w1 + w2); w0 *= iw; w1 *= iw; w2 *= iw;
;     const u32x4 a = *(const u32x4*)(od + ((size_t)0 * T_ + tok) * 256 + c8 * 8), bq = *(const u32x4*)(od + ((size_t)1 * T_ + tok) * 256 + c8 * 8), cq = *(const u32x4*)(od + ((size_t)2 * T_ + tok) * 256 + c8 * 8);
;     const u32x4 z = *(const u32x4*)(proj + tok * NP + C_BZ + c8 * 8);
	v_lshlrev_b32_e32 v4, 16, v88
	v_cvt_pk_bf16_f32 v1, v2, v3
	v_and_b32_e32 v5, 0xffff0000, v88
	global_store_dwordx2 v[16:17], v[0:1], off offset:96
	v_mul_f32_e32 v0, 0xbfb8aa3b, v4
	v_mul_f32_e32 v1, 0xbfb8aa3b, v5
	v_exp_f32_e32 v0, v0
	v_exp_f32_e32 v1, v1
	v_pk_mul_f32 v[2:3], v[32:33], v[12:13]
	v_pk_add_f32 v[0:1], v[0:1], 1.0 op_sel_hi:[1,0]
	s_nop 0
	s_nop 0
	v_rcp_f32_e32 v1, v1
	s_nop 0
	v_mul_f32_e32 v1, v5, v1
	s_nop 0
	v_rcp_f32_e32 v0, v0
	s_nop 0
	v_mul_f32_e32 v0, v4, v0
	v_pk_mul_f32 v[0:1], v[0:1], v[2:3]
	v_and_b32_e32 v6, 0xffff0000, v89
	v_cvt_pk_bf16_f32 v0, v0, v1
	v_lshlrev_b32_e32 v1, 16, v89
	v_mul_f32_e32 v2, 0xbfb8aa3b, v1
	v_mul_f32_e32 v3, 0xbfb8aa3b, v6
	v_exp_f32_e32 v2, v2
	v_exp_f32_e32 v3, v3
	v_pk_mul_f32 v[4:5], v[34:35], v[14:15]
	v_pk_add_f32 v[2:3], v[2:3], 1.0 op_sel_hi:[1,0]
	s_nop 0
	s_nop 0
	v_rcp_f32_e32 v3, v3
	s_nop 0
	v_mul_f32_e32 v3, v6, v3
	s_mov_b64 s[0:1], 0
	v_rcp_f32_e32 v2, v2
	s_nop 0
	v_mul_f32_e32 v2, v1, v2
	v_pk_mul_f32 v[2:3], v[2:3], v[4:5]
	s_nop 0
	v_cvt_pk_bf16_f32 v1, v2, v3
	global_store_dwordx2 v[16:17], v[0:1], off offset:112
	v_add_u32_e32 v0, s14, v119
	s_add_u32 s0, s90, s0
	s_addc_u32 s1, s91, s1
	v_lshl_or_b32 v31, v0, 10, v176
	v_lshl_add_u64 v[0:1], s[0:1], 0, v[182:183]
	v_ashrrev_i32_e32 v12, 5, v31
	v_lshl_add_u64 v[18:19], v[0:1], 0, s[2:3]
	v_lshl_add_u64 v[0:1], s[0:1], 0, v[184:185]
	v_ashrrev_i32_e32 v13, 31, v12
	v_lshl_add_u64 v[16:17], v[0:1], 0, s[94:95]
	v_lshl_add_u64 v[0:1], v[12:13], 4, v[18:19]
	v_lshl_add_u64 v[4:5], v[12:13], 0, s[96:97]
	global_load_dword v2, v[0:1], off
	v_lshl_add_u64 v[0:1], v[4:5], 4, v[18:19]
	v_lshl_add_u64 v[6:7], v[12:13], 0, s[4:5]
	global_load_dword v3, v[0:1], off
	v_lshl_add_u64 v[0:1], v[6:7], 4, v[18:19]
	global_load_dword v0, v[0:1], off
	v_mov_b64_e32 v[20:21], s[0:1]
	v_lshlrev_b64 v[4:5], 9, v[4:5]
	v_mad_i64_i32 v[22:23], s[0:1], v12, s33, v[20:21]
	v_lshl_add_u64 v[4:5], v[16:17], 0, v[4:5]
	v_lshl_add_u64 v[26:27], v[22:23], 0, v[184:185]
	s_add_i32 s6, s6, 1
	v_mov_b32_e32 v168, s93
	v_mov_b32_e32 v169, 0
	v_mov_b32_e32 v161, 0
	v_add_u32_e32 v160, 0x100, v31
	v_ashrrev_i32_e32 v160, 5, v160
	v_lshl_add_u64 v[162:163], v[160:161], 0, s[96:97]
	v_lshl_add_u64 v[164:165], v[160:161], 0, s[4:5]
	v_lshl_add_u64 v[166:167], v[160:161], 4, v[18:19]
	global_load_dword v150, v[166:167], off
	v_lshl_add_u64 v[166:167], v[162:163], 4, v[18:19]
	global_load_dword v151, v[166:167], off
	v_lshl_add_u64 v[166:167], v[164:165], 4, v[18:19]
	global_load_dword v152, v[166:167], off
	v_lshl_add_u64 v[162:163], v[160:161], 0, s[96:97]
	v_lshl_add_u64 v[164:165], v[160:161], 0, s[4:5]
	v_lshlrev_b64 v[166:167], 9, v[160:161]
	v_lshl_add_u64 v[166:167], v[16:17], 0, v[166:167]
	global_load_dwordx4 v[56:59], v[166:167], off
	v_lshlrev_b64 v[166:167], 9, v[162:163]
	v_lshl_add_u64 v[166:167], v[16:17], 0, v[166:167]
	global_load_dwordx4 v[60:63], v[166:167], off
	v_lshlrev_b64 v[166:167], 9, v[164:165]
	v_lshl_add_u64 v[166:167], v[16:17], 0, v[166:167]
	global_load_dwordx4 v[100:103], v[166:167], off
	v_mad_i64_i32 v[166:167], s[0:1], v160, s33, v[20:21]
	v_lshl_add_u64 v[166:167], v[166:167], 0, v[184:185]
	v_lshl_add_u64 v[166:167], v[166:167], 0, v[168:169]
	global_load_dwordx4 v[104:107], v[166:167], off offset:3328
	v_add_u32_e32 v160, 0x200, v31
	v_ashrrev_i32_e32 v160, 5, v160
	v_lshl_add_u64 v[162:163], v[160:161], 0, s[96:97]
	v_lshl_add_u64 v[164:165], v[160:161], 0, s[4:5]
	v_lshl_add_u64 v[166:167], v[160:161], 4, v[18:19]
	global_load_dword v153, v[166:167], off
	v_lshl_add_u64 v[166:167], v[162:163], 4, v[18:19]
	global_load_dword v154, v[166:167], off
	v_lshl_add_u64 v[166:167], v[164:165], 4, v[18:19]
	global_load_dword v155, v[166:167], off
	v_lshl_add_u64 v[162:163], v[160:161], 0, s[96:97]
	v_lshl_add_u64 v[164:165], v[160:161], 0, s[4:5]
	v_lshlrev_b64 v[166:167], 9, v[160:161]
	v_lshl_add_u64 v[166:167], v[16:17], 0, v[166:167]
	global_load_dwordx4 v[108:111], v[166:167], off
	v_lshlrev_b64 v[166:167], 9, v[162:163]
	v_lshl_add_u64 v[166:167], v[16:17], 0, v[166:167]
	global_load_dwordx4 v[112:115], v[166:167], off
	v_lshlrev_b64 v[166:167], 9, v[164:165]
	v_lshl_add_u64 v[166:167], v[16:17], 0, v[166:167]
	global_load_dwordx4 v[120:123], v[166:167], off
	v_mad_i64_i32 v[166:167], s[0:1], v160, s33, v[20:21]
	v_lshl_add_u64 v[166:167], v[166:167], 0, v[184:185]
	v_lshl_add_u64 v[166:167], v[166:167], 0, v[168:169]
	global_load_dwordx4 v[124:127], v[166:167], off offset:3328
	v_add_u32_e32 v160, 0x300, v31
	v_ashrrev_i32_e32 v160, 5, v160
	v_lshl_add_u64 v[162:163], v[160:161], 0, s[96:97]
	v_lshl_add_u64 v[164:165], v[160:161], 0, s[4:5]
	v_lshl_add_u64 v[166:167], v[160:161], 4, v[18:19]
	global_load_dword v156, v[166:167], off
	v_lshl_add_u64 v[166:167], v[162:163], 4, v[18:19]
	global_load_dword v157, v[166:167], off
	v_lshl_add_u64 v[166:167], v[164:165], 4, v[18:19]
	global_load_dword v158, v[166:167], off
	v_lshl_add_u64 v[162:163], v[160:161], 0, s[96:97]
	v_lshl_add_u64 v[164:165], v[160:161], 0, s[4:5]
	v_lshlrev_b64 v[166:167], 9, v[160:161]
	v_lshl_add_u64 v[166:167], v[16:17], 0, v[166:167]
	global_load_dwordx4 v[128:131], v[166:167], off
	v_lshlrev_b64 v[166:167], 9, v[162:163]
	v_lshl_add_u64 v[166:167], v[16:17], 0, v[166:167]
	global_load_dwordx4 v[132:135], v[166:167], off
	v_lshlrev_b64 v[166:167], 9, v[164:165]
	v_lshl_add_u64 v[166:167], v[16:17], 0, v[166:167]
	global_load_dwordx4 v[136:139], v[166:167], off
	v_mad_i64_i32 v[166:167], s[0:1], v160, s33, v[20:21]
	v_lshl_add_u64 v[166:167], v[166:167], 0, v[184:185]
	v_lshl_add_u64 v[166:167], v[166:167], 0, v[168:169]
	global_load_dwordx4 v[140:143], v[166:167], off offset:3328
	v_lshl_add_u64 v[162:163], v[12:13], 0, s[96:97]
	v_lshl_add_u64 v[164:165], v[12:13], 0, s[4:5]
	v_lshlrev_b64 v[166:167], 9, v[12:13]
	v_lshl_add_u64 v[166:167], v[16:17], 0, v[166:167]
	global_load_dwordx4 v[40:43], v[166:167], off
	v_lshlrev_b64 v[166:167], 9, v[162:163]
	v_lshl_add_u64 v[166:167], v[16:17], 0, v[166:167]
	global_load_dwordx4 v[44:47], v[166:167], off
	v_lshlrev_b64 v[166:167], 9, v[164:165]
	v_lshl_add_u64 v[166:167], v[16:17], 0, v[166:167]
	global_load_dwordx4 v[48:51], v[166:167], off
	v_mad_i64_i32 v[166:167], s[0:1], v12, s33, v[20:21]
	v_lshl_add_u64 v[166:167], v[166:167], 0, v[184:185]
	v_lshl_add_u64 v[166:167], v[166:167], 0, v[168:169]
	global_load_dwordx4 v[52:55], v[166:167], off offset:3328
	s_waitcnt vmcnt(0)
; DI float lo16(unsigned w) { return __uint_as_float(w << 16); }
; DI float hi16(unsigned w) { return __uint_as_float(w & 0xffff0000u); }
; DI float sigmoidf_(float x) { return 1.f / (1.f + __expf(-x)); }
; DI float siluf_(float x) { return x / (1.f + __expf(-x)); }
; DI void dilcomb_item(const Params& p, int it) {
;     ...
;     const int idx = it * 1024 + i * 256 + threadIdx.x;
;     const size_t tok = idx >> 5; const int c8 = idx & 31, h = c8 >> 3;
;     const float l0 = lse[((size_t)0 * T_ + tok) * 4 + h], l1 = lse[((size_t)1 * T_ + tok) * 4 + h], l2 = lse[((size_t)2 * T_ + tok) * 4 + h];
;     const float mx = fmaxf(l0, fmaxf(l1, l2));
;     float w0 = __expf(l0 - mx), w1 = __expf(l1 - mx), w2 = __expf(l2 - mx);
;     const float iw = 1.f / (w0 + w1 + w2); w0 *= iw; w1 *= iw; w2 *= iw;
;     const u32x4 a = *(const u32x4*)(od + ((size_t)0 * T_ + tok) * 256 + c8 * 8), bq = *(const u32x4*)(od + ((size_t)1 * T_ + tok) * 256 + c8 * 8), cq = *(const u32x4*)(od + ((size_t)2 * T_ + tok) * 256 + c8 * 8);
;     const u32x4 z = *(const u32x4*)(proj + tok * NP + C_BZ + c8 * 8);
;     u32x4 r;
; #pragma unroll
;     for (int e = 0; e < 4; ++e) {
;       const float v0 = (w0 * lo16(a[e]) + w1 * lo16(bq[e]) + w2 * lo16(cq[e])) * siluf_(lo16(z[e]));
;       const float v1 = (w0 * hi16(a[e]) + w1 * hi16(bq[e]) + w2 * hi16(cq[e])) * siluf_(hi16(z[e]));
;       r[e] = pk2(v0, v1);
;     }
;     *(u32x4*)(y + tok * 1024 + 256 + c8 * 8) = r;
	v_max3_f32 v1, v2, v3, v0
	v_sub_f32_e32 v2, v2, v1
	v_mul_f32_e32 v2, 0x3fb8aa3b, v2
	v_exp_f32_e32 v25, v2
	v_sub_f32_e32 v2, v3, v1
	v_mul_f32_e32 v2, 0x3fb8aa3b, v2
	v_sub_f32_e32 v0, v0, v1
	v_exp_f32_e32 v24, v2
	v_mul_f32_e32 v0, 0x3fb8aa3b, v0
	v_exp_f32_e32 v0, v0
	v_add_f32_e32 v1, v25, v24
	v_add_f32_e32 v1, v0, v1
	s_nop 0
	v_rcp_f32_e32 v30, v1
	s_nop 0
	v_mul_f32_e32 v14, v0, v30
	v_lshlrev_b64 v[0:1], 9, v[12:13]
	v_lshl_add_u64 v[0:1], v[16:17], 0, v[0:1]
	v_mov_b32_e32 v0, v40
	v_mov_b32_e32 v1, v41
	v_mov_b32_e32 v2, v42
	v_mov_b32_e32 v3, v43
	v_add_co_u32_e32 v26, vcc, s93, v26
	v_mov_b32_e32 v8, v44
	v_mov_b32_e32 v9, v45
	v_mov_b32_e32 v10, v46
	v_mov_b32_e32 v11, v47
	v_lshlrev_b64 v[4:5], 9, v[6:7]
	v_lshl_add_u64 v[4:5], v[16:17], 0, v[4:5]
	v_addc_co_u32_e32 v27, vcc, 0, v27, vcc
	v_mov_b32_e32 v4, v48
	v_mov_b32_e32 v5, v49
	v_mov_b32_e32 v6, v50
	v_mov_b32_e32 v7, v51
	v_pk_mul_f32 v[24:25], v[24:25], v[30:31] op_sel_hi:[1,0]
	v_mov_b32_e32 v26, v52
	v_mov_b32_e32 v27, v53
	v_mov_b32_e32 v28, v54
	v_mov_b32_e32 v29, v55
	v_and_b32_e32 v35, 0xffff0000, v0
	v_lshlrev_b32_e32 v36, 16, v0
	v_lshlrev_b32_e32 v34, 16, v8
	v_and_b32_e32 v37, 0xffff0000, v8
	v_pk_mul_f32 v[36:37], v[24:25], v[36:37] op_sel:[1,0] op_sel_hi:[0,1]
	v_pk_fma_f32 v[34:35], v[24:25], v[34:35], v[36:37]
	v_lshlrev_b32_e32 v38, 16, v4
	v_and_b32_e32 v39, 0xffff0000, v4
	v_lshlrev_b32_e32 v13, 16, v26
	v_and_b32_e32 v15, 0xffff0000, v26
	v_mul_f32_e32 v26, 0xbfb8aa3b, v13
	v_mul_f32_e32 v0, 0xbfb8aa3b, v15
	v_exp_f32_e32 v32, v26
	v_exp_f32_e32 v33, v0
	s_nop 0
	v_pk_add_f32 v[32:33], v[32:33], 1.0 op_sel_hi:[1,0]
	s_nop 0
	s_nop 0
	v_rcp_f32_e32 v33, v33
	s_nop 0
	v_mul_f32_e32 v33, v15, v33
	v_div_scale_f32 v0, s[0:1], v32, v32, v13
	v_rcp_f32_e32 v4, v0
	s_nop 0
	v_fma_f32 v8, -v0, v4, 1.0
	v_fmac_f32_e32 v4, v8, v4
	v_div_scale_f32 v8, vcc, v13, v32, v13
	v_mul_f32_e32 v15, v8, v4
	v_fma_f32 v26, -v0, v15, v8
	v_fmac_f32_e32 v15, v26, v4
	v_fma_f32 v0, -v0, v15, v8
	v_div_fmas_f32 v0, v0, v4, v15
	v_div_fixup_f32 v32, v0, v32, v13
	v_pk_fma_f32 v[34:35], v[14:15], v[38:39], v[34:35] op_sel_hi:[0,1,1]
	v_lshlrev_b32_e32 v13, 16, v27
	v_and_b32_e32 v15, 0xffff0000, v27
	v_pk_mul_f32 v[32:33], v[32:33], v[34:35]
	v_mul_f32_e32 v4, 0xbfb8aa3b, v13
	v_and_b32_e32 v27, 0xffff0000, v1
	v_lshlrev_b32_e32 v8, 16, v1
	v_mul_f32_e32 v1, 0xbfb8aa3b, v15
	v_cvt_pk_bf16_f32 v0, v32, v33
	v_exp_f32_e32 v4, v4
	v_lshlrev_b32_e32 v32, 16, v5
	v_and_b32_e32 v33, 0xffff0000, v5
	v_exp_f32_e32 v5, v1
	v_lshlrev_b32_e32 v26, 16, v9
	v_and_b32_e32 v9, 0xffff0000, v9
	v_pk_mul_f32 v[8:9], v[24:25], v[8:9] op_sel:[1,0] op_sel_hi:[0,1]
	v_pk_add_f32 v[4:5], v[4:5], 1.0 op_sel_hi:[1,0]
	v_pk_fma_f32 v[8:9], v[24:25], v[26:27], v[8:9]
	v_lshlrev_b32_e32 v26, 16, v2
	v_and_b32_e32 v27, 0xffff0000, v10
	v_pk_mul_f32 v[26:27], v[24:25], v[26:27] op_sel:[1,0] op_sel_hi:[0,1]
	v_rcp_f32_e32 v5, v5
	s_nop 0
	v_mul_f32_e32 v5, v15, v5
	v_div_scale_f32 v1, s[0:1], v4, v4, v13
	v_rcp_f32_e32 v15, v1
	s_nop 0
	v_fma_f32 v30, -v1, v15, 1.0
	v_fmac_f32_e32 v15, v30, v15
	v_div_scale_f32 v30, vcc, v13, v4, v13
	v_mul_f32_e32 v34, v30, v15
	v_fma_f32 v35, -v1, v34, v30
	v_fmac_f32_e32 v34, v35, v15
	v_fma_f32 v1, -v1, v34, v30
	v_div_fmas_f32 v1, v1, v15, v34
	v_div_fixup_f32 v4, v1, v4, v13
	v_pk_fma_f32 v[8:9], v[14:15], v[32:33], v[8:9] op_sel_hi:[0,1,1]
	v_pk_mul_f32 v[4:5], v[4:5], v[8:9]
	v_lshlrev_b32_e32 v13, 16, v28
	v_and_b32_e32 v15, 0xffff0000, v28
	v_cvt_pk_bf16_f32 v1, v4, v5
	v_mul_f32_e32 v4, 0xbfb8aa3b, v13
	v_and_b32_e32 v9, 0xffff0000, v2
	v_mul_f32_e32 v2, 0xbfb8aa3b, v15
	v_exp_f32_e32 v4, v4
	v_exp_f32_e32 v5, v2
	v_lshlrev_b32_e32 v32, 16, v6
	v_and_b32_e32 v33, 0xffff0000, v6
	v_lshlrev_b32_e32 v8, 16, v10
	v_pk_add_f32 v[4:5], v[4:5], 1.0 op_sel_hi:[1,0]
	v_pk_fma_f32 v[8:9], v[24:25], v[8:9], v[26:27]
	s_nop 0
	v_rcp_f32_e32 v5, v5
	s_nop 0
	v_mul_f32_e32 v5, v15, v5
	v_div_scale_f32 v2, s[0:1], v4, v4, v13
	v_rcp_f32_e32 v6, v2
	s_nop 0
	v_fma_f32 v10, -v2, v6, 1.0
	v_fmac_f32_e32 v6, v10, v6
	v_div_scale_f32 v10, vcc, v13, v4, v13
	v_mul_f32_e32 v15, v10, v6
	v_fma_f32 v28, -v2, v15, v10
	v_fmac_f32_e32 v15, v28, v6
	v_fma_f32 v2, -v2, v15, v10
	v_div_fmas_f32 v2, v2, v6, v15
	v_div_fixup_f32 v4, v2, v4, v13
	v_pk_fma_f32 v[8:9], v[14:15], v[32:33], v[8:9] op_sel_hi:[0,1,1]
	v_pk_mul_f32 v[4:5], v[4:5], v[8:9]
	v_lshlrev_b32_e32 v13, 16, v29
	v_and_b32_e32 v15, 0xffff0000, v29
	v_cvt_pk_bf16_f32 v2, v4, v5
	v_mul_f32_e32 v4, 0xbfb8aa3b, v13
	v_and_b32_e32 v9, 0xffff0000, v3
	v_lshlrev_b32_e32 v10, 16, v3
	v_mul_f32_e32 v3, 0xbfb8aa3b, v15
	v_exp_f32_e32 v4, v4
	v_exp_f32_e32 v5, v3
	v_lshlrev_b32_e32 v8, 16, v11
	v_and_b32_e32 v11, 0xffff0000, v11
	v_pk_mul_f32 v[10:11], v[24:25], v[10:11] op_sel:[1,0] op_sel_hi:[0,1]
	v_pk_add_f32 v[4:5], v[4:5], 1.0 op_sel_hi:[1,0]
	v_pk_fma_f32 v[8:9], v[24:25], v[8:9], v[10:11]
	v_lshlrev_b32_e32 v6, 16, v7
	v_and_b32_e32 v7, 0xffff0000, v7
	v_pk_fma_f32 v[6:7], v[14:15], v[6:7], v[8:9] op_sel_hi:[0,1,1]
	s_nop 0
	v_rcp_f32_e32 v5, v5
	s_nop 0
	v_mul_f32_e32 v5, v15, v5
	s_nop 0
	v_rcp_f32_e32 v4, v4
	s_nop 0
	v_mul_f32_e32 v4, v13, v4
	v_pk_mul_f32 v[4:5], v[4:5], v[6:7]
	s_nop 0
	v_cvt_pk_bf16_f32 v3, v4, v5
	v_mad_i64_i32 v[4:5], s[0:1], v12, s37, v[22:23]
	v_lshl_add_u64 v[4:5], v[4:5], 0, v[184:185]
	v_add_co_u32_e32 v4, vcc, s74, v4
	s_nop 1
	v_addc_co_u32_e32 v5, vcc, 0, v5, vcc
	global_store_dwordx4 v[4:5], v[0:3], off offset:512
	s_nop 1
	v_add_u32_e32 v0, 0x100, v31
	v_ashrrev_i32_e32 v22, 5, v0
	v_ashrrev_i32_e32 v23, 31, v22
	v_lshl_add_u64 v[0:1], v[22:23], 4, v[18:19]
	v_lshl_add_u64 v[4:5], v[22:23], 0, s[96:97]
; DI float lo16(unsigned w) { return __uint_as_float(w << 16); }
; DI float hi16(unsigned w) { return __uint_as_float(w & 0xffff0000u); }
; DI float sigmoidf_(float x) { return 1.f / (1.f + __expf(-x)); }
; DI float siluf_(float x) { return x / (1.f + __expf(-x)); }
; DI void dilcomb_item(const Params& p, int it) {
;     ...
;     const int idx = it * 1024 + i * 256 + threadIdx.x;
;     const size_t tok = idx >> 5; const int c8 = idx & 31, h = c8 >> 3;
;     const float l0 = lse[((size_t)0 * T_ + tok) * 4 + h], l1 = lse[((size_t)1 * T_ + tok) * 4 + h], l2 = lse[((size_t)2 * T_ + tok) * 4 + h];
;     const float mx = fmaxf(l0, fmaxf(l1, l2));
;     float w0 = __expf(l0 - mx), w1 = __expf(l1 - mx), w2 = __expf(l2 - mx);
;     const float iw = 1.f / (w0 + w1 + w2); w0 *= iw; w1 *= iw; w2 *= iw;
;     const u32x4 a = *(const u32x4*)(od + ((size_t)0 * T_ + tok) * 256 + c8 * 8), bq = *(const u32x4*)(od + ((size_t)1 * T_ + tok) * 256 + c8 * 8), cq = *(const u32x4*)(od + ((size_t)2 * T_ + tok) * 256 + c8 * 8);
;     const u32x4 z = *(const u32x4*)(proj + tok * NP + C_BZ + c8 * 8);
;     u32x4 r;
; #pragma unroll
;     for (int e = 0; e < 4; ++e) {
;       const float v0 = (w0 * lo16(a[e]) + w1 * lo16(bq[e]) + w2 * lo16(cq[e])) * siluf_(lo16(z[e]));
;       const float v1 = (w0 * hi16(a[e]) + w1 * hi16(bq[e]) + w2 * hi16(cq[e])) * siluf_(hi16(z[e]));
;       r[e] = pk2(v0, v1);
;     }
;     *(u32x4*)(y + tok * 1024 + 256 + c8 * 8) = r;
	v_mov_b32_e32 v2, v150
	v_lshl_add_u64 v[0:1], v[4:5], 4, v[18:19]
	v_lshl_add_u64 v[6:7], v[22:23], 0, s[4:5]
	v_mov_b32_e32 v3, v151
	v_lshl_add_u64 v[0:1], v[6:7], 4, v[18:19]
	v_mov_b32_e32 v0, v152
	v_lshlrev_b64 v[4:5], 9, v[4:5]
	v_mad_i64_i32 v[26:27], s[0:1], v22, s33, v[20:21]
	v_lshl_add_u64 v[4:5], v[16:17], 0, v[4:5]
	v_lshl_add_u64 v[12:13], v[26:27], 0, v[184:185]
	v_max3_f32 v1, v2, v3, v0
	v_sub_f32_e32 v2, v2, v1
	v_mul_f32_e32 v2, 0x3fb8aa3b, v2
	v_exp_f32_e32 v29, v2
	v_sub_f32_e32 v2, v3, v1
	v_mul_f32_e32 v2, 0x3fb8aa3b, v2
	v_sub_f32_e32 v0, v0, v1
	v_exp_f32_e32 v28, v2
	v_mul_f32_e32 v0, 0x3fb8aa3b, v0
	v_exp_f32_e32 v0, v0
	v_add_f32_e32 v1, v29, v28
	v_add_f32_e32 v1, v0, v1
	s_nop 0
	v_rcp_f32_e32 v30, v1
	s_nop 0
	v_mul_f32_e32 v24, v0, v30
	v_lshlrev_b64 v[0:1], 9, v[22:23]
	v_lshl_add_u64 v[0:1], v[16:17], 0, v[0:1]
	v_mov_b32_e32 v0, v56
	v_mov_b32_e32 v1, v57
	v_mov_b32_e32 v2, v58
	v_mov_b32_e32 v3, v59
	v_add_co_u32_e32 v12, vcc, s93, v12
	v_mov_b32_e32 v8, v60
	v_mov_b32_e32 v9, v61
	v_mov_b32_e32 v10, v62
	v_mov_b32_e32 v11, v63
	v_lshlrev_b64 v[4:5], 9, v[6:7]
	v_lshl_add_u64 v[4:5], v[16:17], 0, v[4:5]
	v_addc_co_u32_e32 v13, vcc, 0, v13, vcc
	v_mov_b32_e32 v4, v100
	v_mov_b32_e32 v5, v101
	v_mov_b32_e32 v6, v102
	v_mov_b32_e32 v7, v103
	v_pk_mul_f32 v[28:29], v[28:29], v[30:31] op_sel_hi:[1,0]
	v_mov_b32_e32 v12, v104
	v_mov_b32_e32 v13, v105
	v_mov_b32_e32 v14, v106
	v_mov_b32_e32 v15, v107
	v_and_b32_e32 v35, 0xffff0000, v0
	v_lshlrev_b32_e32 v36, 16, v0
	v_lshlrev_b32_e32 v34, 16, v8
	v_and_b32_e32 v37, 0xffff0000, v8
	v_pk_mul_f32 v[36:37], v[28:29], v[36:37] op_sel:[1,0] op_sel_hi:[0,1]
	v_pk_fma_f32 v[34:35], v[28:29], v[34:35], v[36:37]
	v_lshlrev_b32_e32 v38, 16, v4
	v_and_b32_e32 v39, 0xffff0000, v4
	v_lshlrev_b32_e32 v23, 16, v12
	v_and_b32_e32 v12, 0xffff0000, v12
	v_mul_f32_e32 v25, 0xbfb8aa3b, v23
	v_mul_f32_e32 v0, 0xbfb8aa3b, v12
	v_exp_f32_e32 v32, v25
	v_exp_f32_e32 v33, v0
	s_nop 0
	v_pk_add_f32 v[32:33], v[32:33], 1.0 op_sel_hi:[1,0]
	s_nop 0
	s_nop 0
	v_rcp_f32_e32 v33, v33
	s_nop 0
	v_mul_f32_e32 v33, v12, v33
	v_div_scale_f32 v0, s[0:1], v32, v32, v23
	v_rcp_f32_e32 v4, v0
	s_nop 0
	v_fma_f32 v8, -v0, v4, 1.0
	v_fmac_f32_e32 v4, v8, v4
	v_div_scale_f32 v8, vcc, v23, v32, v23
	v_mul_f32_e32 v12, v8, v4
	v_fma_f32 v25, -v0, v12, v8
	v_fmac_f32_e32 v12, v25, v4
	v_fma_f32 v0, -v0, v12, v8
	v_div_fmas_f32 v0, v0, v4, v12
	v_div_fixup_f32 v32, v0, v32, v23
	v_pk_fma_f32 v[34:35], v[24:25], v[38:39], v[34:35] op_sel_hi:[0,1,1]
	v_lshlrev_b32_e32 v23, 16, v13
	v_and_b32_e32 v25, 0xffff0000, v13
	v_pk_mul_f32 v[32:33], v[32:33], v[34:35]
	v_mul_f32_e32 v4, 0xbfb8aa3b, v23
	v_and_b32_e32 v13, 0xffff0000, v1
	v_lshlrev_b32_e32 v8, 16, v1
	v_mul_f32_e32 v1, 0xbfb8aa3b, v25
	v_cvt_pk_bf16_f32 v0, v32, v33
	v_exp_f32_e32 v4, v4
	v_lshlrev_b32_e32 v32, 16, v5
	v_and_b32_e32 v33, 0xffff0000, v5
	v_exp_f32_e32 v5, v1
	v_lshlrev_b32_e32 v12, 16, v9
	v_and_b32_e32 v9, 0xffff0000, v9
	v_pk_mul_f32 v[8:9], v[28:29], v[8:9] op_sel:[1,0] op_sel_hi:[0,1]
	v_pk_add_f32 v[4:5], v[4:5], 1.0 op_sel_hi:[1,0]
	v_pk_fma_f32 v[8:9], v[28:29], v[12:13], v[8:9]
	v_lshlrev_b32_e32 v12, 16, v2
	v_and_b32_e32 v13, 0xffff0000, v10
	v_pk_mul_f32 v[12:13], v[28:29], v[12:13] op_sel:[1,0] op_sel_hi:[0,1]
	v_rcp_f32_e32 v5, v5
	s_nop 0
	v_mul_f32_e32 v5, v25, v5
	v_div_scale_f32 v1, s[0:1], v4, v4, v23
	v_rcp_f32_e32 v25, v1
	s_nop 0
	v_fma_f32 v30, -v1, v25, 1.0
	v_fmac_f32_e32 v25, v30, v25
	v_div_scale_f32 v30, vcc, v23, v4, v23
	v_mul_f32_e32 v34, v30, v25
	v_fma_f32 v35, -v1, v34, v30
	v_fmac_f32_e32 v34, v35, v25
	v_fma_f32 v1, -v1, v34, v30
	v_div_fmas_f32 v1, v1, v25, v34
	v_div_fixup_f32 v4, v1, v4, v23
	v_pk_fma_f32 v[8:9], v[24:25], v[32:33], v[8:9] op_sel_hi:[0,1,1]
	v_pk_mul_f32 v[4:5], v[4:5], v[8:9]
	v_lshlrev_b32_e32 v23, 16, v14
	v_and_b32_e32 v14, 0xffff0000, v14
	v_cvt_pk_bf16_f32 v1, v4, v5
	v_mul_f32_e32 v4, 0xbfb8aa3b, v23
	v_and_b32_e32 v9, 0xffff0000, v2
	v_mul_f32_e32 v2, 0xbfb8aa3b, v14
	v_exp_f32_e32 v4, v4
	v_exp_f32_e32 v5, v2
	v_lshlrev_b32_e32 v32, 16, v6
	v_and_b32_e32 v33, 0xffff0000, v6
	v_lshlrev_b32_e32 v8, 16, v10
	v_pk_add_f32 v[4:5], v[4:5], 1.0 op_sel_hi:[1,0]
	v_pk_fma_f32 v[8:9], v[28:29], v[8:9], v[12:13]
	v_lshlrev_b32_e32 v12, 16, v15
	v_and_b32_e32 v13, 0xffff0000, v15
	v_rcp_f32_e32 v5, v5
	s_nop 0
	v_mul_f32_e32 v5, v14, v5
	v_div_scale_f32 v2, s[0:1], v4, v4, v23
	v_rcp_f32_e32 v6, v2
	s_nop 0
	v_fma_f32 v10, -v2, v6, 1.0
	v_fmac_f32_e32 v6, v10, v6
	v_div_scale_f32 v10, vcc, v23, v4, v23
	v_mul_f32_e32 v14, v10, v6
	v_fma_f32 v25, -v2, v14, v10
	v_fmac_f32_e32 v14, v25, v6
	v_fma_f32 v2, -v2, v14, v10
	v_div_fmas_f32 v2, v2, v6, v14
	v_div_fixup_f32 v4, v2, v4, v23
	v_pk_fma_f32 v[8:9], v[24:25], v[32:33], v[8:9] op_sel_hi:[0,1,1]
	v_pk_mul_f32 v[4:5], v[4:5], v[8:9]
	v_and_b32_e32 v9, 0xffff0000, v3
	v_cvt_pk_bf16_f32 v2, v4, v5
	v_mul_f32_e32 v4, 0xbfb8aa3b, v12
	v_lshlrev_b32_e32 v10, 16, v3
	v_mul_f32_e32 v3, 0xbfb8aa3b, v13
	v_exp_f32_e32 v4, v4
	v_exp_f32_e32 v5, v3
	v_lshlrev_b32_e32 v8, 16, v11
	v_and_b32_e32 v11, 0xffff0000, v11
	v_pk_mul_f32 v[10:11], v[28:29], v[10:11] op_sel:[1,0] op_sel_hi:[0,1]
	v_pk_add_f32 v[4:5], v[4:5], 1.0 op_sel_hi:[1,0]
	v_pk_fma_f32 v[8:9], v[28:29], v[8:9], v[10:11]
	v_lshlrev_b32_e32 v6, 16, v7
	v_and_b32_e32 v7, 0xffff0000, v7
	v_pk_fma_f32 v[6:7], v[24:25], v[6:7], v[8:9] op_sel_hi:[0,1,1]
	s_nop 0
	v_rcp_f32_e32 v5, v5
	s_nop 0
	v_mul_f32_e32 v5, v13, v5
	s_nop 0
	v_rcp_f32_e32 v4, v4
	s_nop 0
	v_mul_f32_e32 v4, v12, v4
	v_pk_mul_f32 v[4:5], v[4:5], v[6:7]
	s_nop 0
	v_cvt_pk_bf16_f32 v3, v4, v5
	v_mad_i64_i32 v[4:5], s[0:1], v22, s37, v[26:27]
; DI float lo16(unsigned w) { return __uint_as_float(w << 16); }
; DI float hi16(unsigned w) { return __uint_as_float(w & 0xffff0000u); }
; DI float sigmoidf_(float x) { return 1.f / (1.f + __expf(-x)); }
; DI float siluf_(float x) { return x / (1.f + __expf(-x)); }
; DI void dilcomb_item(const Params& p, int it) {
;     ...
;     const int idx = it * 1024 + i * 256 + threadIdx.x;
;     const size_t tok = idx >> 5; const int c8 = idx & 31, h = c8 >> 3;
;     const float l0 = lse[((size_t)0 * T_ + tok) * 4 + h], l1 = lse[((size_t)1 * T_ + tok) * 4 + h], l2 = lse[((size_t)2 * T_ + tok) * 4 + h];
;     const float mx = fmaxf(l0, fmaxf(l1, l2));
;     float w0 = __expf(l0 - mx), w1 = __expf(l1 - mx), w2 = __expf(l2 - mx);
;     const float iw = 1.f / (w0 + w1 + w2); w0 *= iw; w1 *= iw; w2 *= iw;
;     const u32x4 a = *(const u32x4*)(od + ((size_t)0 * T_ + tok) * 256 + c8 * 8), bq = *(const u32x4*)(od + ((size_t)1 * T_ + tok) * 256 + c8 * 8), cq = *(const u32x4*)(od + ((size_t)2 * T_ + tok) * 256 + c8 * 8);
;     const u32x4 z = *(const u32x4*)(proj + tok * NP + C_BZ + c8 * 8);
;     u32x4 r;
; #pragma unroll
;     for (int e = 0; e < 4; ++e) {
;       const float v0 = (w0 * lo16(a[e]) + w1 * lo16(bq[e]) + w2 * lo16(cq[e])) * siluf_(lo16(z[e]));
;       const float v1 = (w0 * hi16(a[e]) + w1 * hi16(bq[e]) + w2 * hi16(cq[e])) * siluf_(hi16(z[e]));
;       r[e] = pk2(v0, v1);
;     }
;     *(u32x4*)(y + tok * 1024 + 256 + c8 * 8) = r;
	v_lshl_add_u64 v[4:5], v[4:5], 0, v[184:185]
	v_add_co_u32_e32 v4, vcc, s74, v4
	s_nop 1
	v_addc_co_u32_e32 v5, vcc, 0, v5, vcc
	global_store_dwordx4 v[4:5], v[0:3], off offset:512
	s_nop 1
	v_add_u32_e32 v0, 0x200, v31
	v_ashrrev_i32_e32 v12, 5, v0
	v_ashrrev_i32_e32 v13, 31, v12
	v_lshl_add_u64 v[0:1], v[12:13], 4, v[18:19]
	v_lshl_add_u64 v[4:5], v[12:13], 0, s[96:97]
	v_mov_b32_e32 v2, v153
	v_lshl_add_u64 v[0:1], v[4:5], 4, v[18:19]
	v_lshl_add_u64 v[6:7], v[12:13], 0, s[4:5]
	v_mov_b32_e32 v3, v154
	v_lshl_add_u64 v[0:1], v[6:7], 4, v[18:19]
	v_mov_b32_e32 v0, v155
	v_lshlrev_b64 v[4:5], 9, v[4:5]
	v_mad_i64_i32 v[22:23], s[0:1], v12, s33, v[20:21]
	v_lshl_add_u64 v[4:5], v[16:17], 0, v[4:5]
	v_lshl_add_u64 v[24:25], v[22:23], 0, v[184:185]
	v_max3_f32 v1, v2, v3, v0
	v_sub_f32_e32 v2, v2, v1
	v_mul_f32_e32 v2, 0x3fb8aa3b, v2
	v_exp_f32_e32 v29, v2
	v_sub_f32_e32 v2, v3, v1
	v_mul_f32_e32 v2, 0x3fb8aa3b, v2
	v_sub_f32_e32 v0, v0, v1
	v_exp_f32_e32 v28, v2
	v_mul_f32_e32 v0, 0x3fb8aa3b, v0
	v_exp_f32_e32 v0, v0
	v_add_f32_e32 v1, v29, v28
	v_add_f32_e32 v1, v0, v1
	s_nop 0
	v_rcp_f32_e32 v30, v1
	s_nop 0
	v_mul_f32_e32 v14, v0, v30
	v_lshlrev_b64 v[0:1], 9, v[12:13]
	v_lshl_add_u64 v[0:1], v[16:17], 0, v[0:1]
	v_mov_b32_e32 v0, v108
	v_mov_b32_e32 v1, v109
	v_mov_b32_e32 v2, v110
	v_mov_b32_e32 v3, v111
	v_add_co_u32_e32 v24, vcc, s93, v24
	v_mov_b32_e32 v8, v112
	v_mov_b32_e32 v9, v113
	v_mov_b32_e32 v10, v114
	v_mov_b32_e32 v11, v115
	v_lshlrev_b64 v[4:5], 9, v[6:7]
	v_lshl_add_u64 v[4:5], v[16:17], 0, v[4:5]
	v_addc_co_u32_e32 v25, vcc, 0, v25, vcc
	v_mov_b32_e32 v4, v120
	v_mov_b32_e32 v5, v121
	v_mov_b32_e32 v6, v122
	v_mov_b32_e32 v7, v123
	v_pk_mul_f32 v[28:29], v[28:29], v[30:31] op_sel_hi:[1,0]
	v_mov_b32_e32 v24, v124
	v_mov_b32_e32 v25, v125
	v_mov_b32_e32 v26, v126
	v_mov_b32_e32 v27, v127
	v_and_b32_e32 v35, 0xffff0000, v0
	v_lshlrev_b32_e32 v36, 16, v0
	v_lshlrev_b32_e32 v34, 16, v8
	v_and_b32_e32 v37, 0xffff0000, v8
	v_pk_mul_f32 v[36:37], v[28:29], v[36:37] op_sel:[1,0] op_sel_hi:[0,1]
	v_pk_fma_f32 v[34:35], v[28:29], v[34:35], v[36:37]
	v_lshlrev_b32_e32 v38, 16, v4
	v_and_b32_e32 v39, 0xffff0000, v4
	v_lshlrev_b32_e32 v13, 16, v24
	v_and_b32_e32 v15, 0xffff0000, v24
	v_mul_f32_e32 v24, 0xbfb8aa3b, v13
	v_mul_f32_e32 v0, 0xbfb8aa3b, v15
	v_exp_f32_e32 v32, v24
	v_exp_f32_e32 v33, v0
	s_nop 0
	v_pk_add_f32 v[32:33], v[32:33], 1.0 op_sel_hi:[1,0]
	s_nop 0
	s_nop 0
	v_rcp_f32_e32 v33, v33
	s_nop 0
	v_mul_f32_e32 v33, v15, v33
	v_div_scale_f32 v0, s[0:1], v32, v32, v13
	v_rcp_f32_e32 v4, v0
	s_nop 0
	v_fma_f32 v8, -v0, v4, 1.0
	v_fmac_f32_e32 v4, v8, v4
	v_div_scale_f32 v8, vcc, v13, v32, v13
	v_mul_f32_e32 v15, v8, v4
	v_fma_f32 v24, -v0, v15, v8
	v_fmac_f32_e32 v15, v24, v4
	v_fma_f32 v0, -v0, v15, v8
	v_div_fmas_f32 v0, v0, v4, v15
	v_div_fixup_f32 v32, v0, v32, v13
	v_pk_fma_f32 v[34:35], v[14:15], v[38:39], v[34:35] op_sel_hi:[0,1,1]
	v_lshlrev_b32_e32 v13, 16, v25
	v_and_b32_e32 v15, 0xffff0000, v25
	v_pk_mul_f32 v[32:33], v[32:33], v[34:35]
	v_mul_f32_e32 v4, 0xbfb8aa3b, v13
	v_and_b32_e32 v25, 0xffff0000, v1
	v_lshlrev_b32_e32 v8, 16, v1
	v_mul_f32_e32 v1, 0xbfb8aa3b, v15
	v_cvt_pk_bf16_f32 v0, v32, v33
	v_exp_f32_e32 v4, v4
	v_lshlrev_b32_e32 v32, 16, v5
	v_and_b32_e32 v33, 0xffff0000, v5
	v_exp_f32_e32 v5, v1
	v_lshlrev_b32_e32 v24, 16, v9
	v_and_b32_e32 v9, 0xffff0000, v9
	v_pk_mul_f32 v[8:9], v[28:29], v[8:9] op_sel:[1,0] op_sel_hi:[0,1]
	v_pk_add_f32 v[4:5], v[4:5], 1.0 op_sel_hi:[1,0]
	v_pk_fma_f32 v[8:9], v[28:29], v[24:25], v[8:9]
	v_lshlrev_b32_e32 v24, 16, v2
	v_and_b32_e32 v25, 0xffff0000, v10
	v_pk_mul_f32 v[24:25], v[28:29], v[24:25] op_sel:[1,0] op_sel_hi:[0,1]
	v_rcp_f32_e32 v5, v5
	s_nop 0
	v_mul_f32_e32 v5, v15, v5
	v_div_scale_f32 v1, s[0:1], v4, v4, v13
	v_rcp_f32_e32 v15, v1
	s_nop 0
	v_fma_f32 v30, -v1, v15, 1.0
	v_fmac_f32_e32 v15, v30, v15
	v_div_scale_f32 v30, vcc, v13, v4, v13
	v_mul_f32_e32 v34, v30, v15
	v_fma_f32 v35, -v1, v34, v30
	v_fmac_f32_e32 v34, v35, v15
	v_fma_f32 v1, -v1, v34, v30
	v_div_fmas_f32 v1, v1, v15, v34
	v_div_fixup_f32 v4, v1, v4, v13
	v_pk_fma_f32 v[8:9], v[14:15], v[32:33], v[8:9] op_sel_hi:[0,1,1]
	v_pk_mul_f32 v[4:5], v[4:5], v[8:9]
	v_lshlrev_b32_e32 v13, 16, v26
	v_and_b32_e32 v15, 0xffff0000, v26
	v_cvt_pk_bf16_f32 v1, v4, v5
	v_mul_f32_e32 v4, 0xbfb8aa3b, v13
	v_and_b32_e32 v9, 0xffff0000, v2
	v_mul_f32_e32 v2, 0xbfb8aa3b, v15
	v_exp_f32_e32 v4, v4
	v_exp_f32_e32 v5, v2
	v_lshlrev_b32_e32 v32, 16, v6
	v_and_b32_e32 v33, 0xffff0000, v6
	v_lshlrev_b32_e32 v8, 16, v10
	v_pk_add_f32 v[4:5], v[4:5], 1.0 op_sel_hi:[1,0]
	v_pk_fma_f32 v[8:9], v[28:29], v[8:9], v[24:25]
	s_nop 0
	v_rcp_f32_e32 v5, v5
	s_nop 0
	v_mul_f32_e32 v5, v15, v5
	v_div_scale_f32 v2, s[0:1], v4, v4, v13
	v_rcp_f32_e32 v6, v2
	s_nop 0
	v_fma_f32 v10, -v2, v6, 1.0
	v_fmac_f32_e32 v6, v10, v6
	v_div_scale_f32 v10, vcc, v13, v4, v13
	v_mul_f32_e32 v15, v10, v6
	v_fma_f32 v26, -v2, v15, v10
	v_fmac_f32_e32 v15, v26, v6
	v_fma_f32 v2, -v2, v15, v10
	v_div_fmas_f32 v2, v2, v6, v15
	v_div_fixup_f32 v4, v2, v4, v13
	v_pk_fma_f32 v[8:9], v[14:15], v[32:33], v[8:9] op_sel_hi:[0,1,1]
	v_pk_mul_f32 v[4:5], v[4:5], v[8:9]
	v_lshlrev_b32_e32 v13, 16, v27
	v_and_b32_e32 v15, 0xffff0000, v27
	v_cvt_pk_bf16_f32 v2, v4, v5
	v_mul_f32_e32 v4, 0xbfb8aa3b, v13
	v_and_b32_e32 v9, 0xffff0000, v3
	v_lshlrev_b32_e32 v10, 16, v3
	v_mul_f32_e32 v3, 0xbfb8aa3b, v15
	v_exp_f32_e32 v4, v4
	v_exp_f32_e32 v5, v3
	v_lshlrev_b32_e32 v8, 16, v11
	v_and_b32_e32 v11, 0xffff0000, v11
	v_pk_mul_f32 v[10:11], v[28:29], v[10:11] op_sel:[1,0] op_sel_hi:[0,1]
	v_pk_add_f32 v[4:5], v[4:5], 1.0 op_sel_hi:[1,0]
; DI float lo16(unsigned w) { return __uint_as_float(w << 16); }
; DI float hi16(unsigned w) { return __uint_as_float(w & 0xffff0000u); }
; DI float siluf_(float x) { return x / (1.f + __expf(-x)); }
; DI void dilcomb_item(const Params& p, int it) {
;     ...
;     const int idx = it * 1024 + i * 256 + threadIdx.x;
;     const size_t tok = idx >> 5; const int c8 = idx & 31, h = c8 >> 3;
;     const float l0 = lse[((size_t)0 * T_ + tok) * 4 + h], l1 = lse[((size_t)1 * T_ + tok) * 4 + h], l2 = lse[((size_t)2 * T_ + tok) * 4 + h];
;     const float mx = fmaxf(l0, fmaxf(l1, l2));
;     float w0 = __expf(l0 - mx), w1 = __expf(l1 - mx), w2 = __expf(l2 - mx);
;     const float iw = 1.f / (w0 + w1 + w2); w0 *= iw; w1 *= iw; w2 *= iw;
;     const u32x4 a = *(const u32x4*)(od + ((size_t)0 * T_ + tok) * 256 + c8 * 8), bq = *(const u32x4*)(od + ((size_t)1 * T_ + tok) * 256 + c8 * 8), cq = *(const u32x4*)(od + ((size_t)2 * T_ + tok) * 256 + c8 * 8);
;     const u32x4 z = *(const u32x4*)(proj + tok * NP + C_BZ + c8 * 8);
;     u32x4 r;
; #pragma unroll
;     for (int e = 0; e < 4; ++e) {
;       const float v0 = (w0 * lo16(a[e]) + w1 * lo16(bq[e]) + w2 * lo16(cq[e])) * siluf_(lo16(z[e]));
;       const float v1 = (w0 * hi16(a[e]) + w1 * hi16(bq[e]) + w2 * hi16(cq[e])) * siluf_(hi16(z[e]));
;       r[e] = pk2(v0, v1);
;     }
;     *(u32x4*)(y + tok * 1024 + 256 + c8 * 8) = r;
;   }
	v_pk_fma_f32 v[8:9], v[28:29], v[8:9], v[10:11]
	v_lshlrev_b32_e32 v6, 16, v7
	v_and_b32_e32 v7, 0xffff0000, v7
	v_pk_fma_f32 v[6:7], v[14:15], v[6:7], v[8:9] op_sel_hi:[0,1,1]
	s_nop 0
	v_rcp_f32_e32 v5, v5
	s_nop 0
	v_mul_f32_e32 v5, v15, v5
	s_nop 0
	v_rcp_f32_e32 v4, v4
	s_nop 0
	v_mul_f32_e32 v4, v13, v4
	v_pk_mul_f32 v[4:5], v[4:5], v[6:7]
	s_nop 0
	v_cvt_pk_bf16_f32 v3, v4, v5
	v_mad_i64_i32 v[4:5], s[0:1], v12, s37, v[22:23]
	v_lshl_add_u64 v[4:5], v[4:5], 0, v[184:185]
	v_add_co_u32_e32 v4, vcc, s74, v4
	s_nop 1
	v_addc_co_u32_e32 v5, vcc, 0, v5, vcc
	global_store_dwordx4 v[4:5], v[0:3], off offset:512
	s_nop 1
	v_add_u32_e32 v0, 0x300, v31
	v_ashrrev_i32_e32 v22, 5, v0
	v_ashrrev_i32_e32 v23, 31, v22
	v_lshl_add_u64 v[0:1], v[22:23], 4, v[18:19]
	v_lshl_add_u64 v[4:5], v[22:23], 0, s[96:97]
	v_mov_b32_e32 v2, v156
	v_lshl_add_u64 v[0:1], v[4:5], 4, v[18:19]
	v_lshl_add_u64 v[6:7], v[22:23], 0, s[4:5]
	v_mov_b32_e32 v3, v157
	v_lshl_add_u64 v[0:1], v[6:7], 4, v[18:19]
	v_mov_b32_e32 v0, v158
	v_lshlrev_b64 v[4:5], 9, v[4:5]
	v_lshl_add_u64 v[4:5], v[16:17], 0, v[4:5]
	v_max3_f32 v1, v2, v3, v0
	v_sub_f32_e32 v2, v2, v1
	v_mul_f32_e32 v2, 0x3fb8aa3b, v2
	v_exp_f32_e32 v25, v2
	v_sub_f32_e32 v2, v3, v1
	v_mul_f32_e32 v2, 0x3fb8aa3b, v2
	v_sub_f32_e32 v0, v0, v1
	v_exp_f32_e32 v24, v2
	v_mul_f32_e32 v0, 0x3fb8aa3b, v0
	v_exp_f32_e32 v0, v0
	v_add_f32_e32 v1, v25, v24
	v_add_f32_e32 v1, v0, v1
	s_nop 0
	v_rcp_f32_e32 v26, v1
	s_nop 0
	v_mul_f32_e32 v18, v0, v26
	v_lshlrev_b64 v[0:1], 9, v[22:23]
	v_lshl_add_u64 v[0:1], v[16:17], 0, v[0:1]
	v_mov_b32_e32 v0, v128
	v_mov_b32_e32 v1, v129
	v_mov_b32_e32 v2, v130
	v_mov_b32_e32 v3, v131
	s_nop 0
	v_mov_b32_e32 v8, v132
	v_mov_b32_e32 v9, v133
	v_mov_b32_e32 v10, v134
	v_mov_b32_e32 v11, v135
	v_lshlrev_b64 v[4:5], 9, v[6:7]
	v_lshl_add_u64 v[4:5], v[16:17], 0, v[4:5]
	v_mad_i64_i32 v[16:17], s[0:1], v22, s33, v[20:21]
	v_lshl_add_u64 v[12:13], v[16:17], 0, v[184:185]
	v_add_co_u32_e32 v12, vcc, s93, v12
	v_mov_b32_e32 v4, v136
	v_mov_b32_e32 v5, v137
	v_mov_b32_e32 v6, v138
	v_mov_b32_e32 v7, v139
	s_nop 0
	v_addc_co_u32_e32 v13, vcc, 0, v13, vcc
	v_mov_b32_e32 v12, v140
	v_mov_b32_e32 v13, v141
	v_mov_b32_e32 v14, v142
	v_mov_b32_e32 v15, v143
	v_pk_mul_f32 v[20:21], v[24:25], v[26:27] op_sel_hi:[1,0]
	v_and_b32_e32 v27, 0xffff0000, v0
	v_lshlrev_b32_e32 v28, 16, v0
	v_lshlrev_b32_e32 v26, 16, v8
	v_and_b32_e32 v29, 0xffff0000, v8
	v_pk_mul_f32 v[28:29], v[20:21], v[28:29] op_sel:[1,0] op_sel_hi:[0,1]
	v_pk_fma_f32 v[26:27], v[20:21], v[26:27], v[28:29]
	v_lshlrev_b32_e32 v30, 16, v4
	v_and_b32_e32 v31, 0xffff0000, v4
	v_lshlrev_b32_e32 v19, 16, v12
	v_and_b32_e32 v12, 0xffff0000, v12
	v_mul_f32_e32 v23, 0xbfb8aa3b, v19
	v_mul_f32_e32 v0, 0xbfb8aa3b, v12
	v_exp_f32_e32 v24, v23
	v_exp_f32_e32 v25, v0
	v_pk_fma_f32 v[26:27], v[18:19], v[30:31], v[26:27] op_sel_hi:[0,1,1]
	v_pk_add_f32 v[24:25], v[24:25], 1.0 op_sel_hi:[1,0]
	s_nop 0
	s_nop 0
	v_rcp_f32_e32 v25, v25
	s_nop 0
	v_mul_f32_e32 v25, v12, v25
	s_nop 0
	v_rcp_f32_e32 v24, v24
	s_nop 0
	v_mul_f32_e32 v24, v19, v24
	v_lshlrev_b32_e32 v19, 16, v13
	v_and_b32_e32 v23, 0xffff0000, v13
	v_pk_mul_f32 v[24:25], v[24:25], v[26:27]
	v_mul_f32_e32 v4, 0xbfb8aa3b, v19
	v_and_b32_e32 v13, 0xffff0000, v1
	v_lshlrev_b32_e32 v8, 16, v1
	v_mul_f32_e32 v1, 0xbfb8aa3b, v23
	v_cvt_pk_bf16_f32 v0, v24, v25
	v_exp_f32_e32 v4, v4
	v_lshlrev_b32_e32 v24, 16, v5
	v_and_b32_e32 v25, 0xffff0000, v5
	v_exp_f32_e32 v5, v1
	v_lshlrev_b32_e32 v12, 16, v9
	v_and_b32_e32 v9, 0xffff0000, v9
	v_pk_mul_f32 v[8:9], v[20:21], v[8:9] op_sel:[1,0] op_sel_hi:[0,1]
	v_pk_add_f32 v[4:5], v[4:5], 1.0 op_sel_hi:[1,0]
	v_pk_fma_f32 v[8:9], v[20:21], v[12:13], v[8:9]
	v_pk_fma_f32 v[8:9], v[18:19], v[24:25], v[8:9] op_sel_hi:[0,1,1]
	v_lshlrev_b32_e32 v12, 16, v2
	v_lshlrev_b32_e32 v24, 16, v6
	v_rcp_f32_e32 v5, v5
	s_nop 0
	v_mul_f32_e32 v5, v23, v5
	v_and_b32_e32 v25, 0xffff0000, v6
	v_and_b32_e32 v13, 0xffff0000, v10
	v_pk_mul_f32 v[12:13], v[20:21], v[12:13] op_sel:[1,0] op_sel_hi:[0,1]
	v_rcp_f32_e32 v4, v4
	s_nop 0
	v_mul_f32_e32 v4, v19, v4
	v_pk_mul_f32 v[4:5], v[4:5], v[8:9]
	v_lshlrev_b32_e32 v19, 16, v14
	v_and_b32_e32 v14, 0xffff0000, v14
	v_cvt_pk_bf16_f32 v1, v4, v5
	v_mul_f32_e32 v4, 0xbfb8aa3b, v19
	v_and_b32_e32 v9, 0xffff0000, v2
	v_mul_f32_e32 v2, 0xbfb8aa3b, v14
	v_exp_f32_e32 v4, v4
	v_exp_f32_e32 v5, v2
	v_lshlrev_b32_e32 v8, 16, v10
	v_pk_fma_f32 v[8:9], v[20:21], v[8:9], v[12:13]
	v_lshlrev_b32_e32 v12, 16, v15
	v_pk_add_f32 v[4:5], v[4:5], 1.0 op_sel_hi:[1,0]
	v_pk_fma_f32 v[8:9], v[18:19], v[24:25], v[8:9] op_sel_hi:[0,1,1]
	v_and_b32_e32 v13, 0xffff0000, v15
	v_rcp_f32_e32 v5, v5
	s_nop 0
	v_mul_f32_e32 v5, v14, v5
	s_nop 0
	v_rcp_f32_e32 v4, v4
	s_nop 0
	v_mul_f32_e32 v4, v19, v4
	v_pk_mul_f32 v[4:5], v[4:5], v[8:9]
	v_and_b32_e32 v9, 0xffff0000, v3
	v_cvt_pk_bf16_f32 v2, v4, v5
	v_mul_f32_e32 v4, 0xbfb8aa3b, v12
	v_lshlrev_b32_e32 v10, 16, v3
	v_mul_f32_e32 v3, 0xbfb8aa3b, v13
	v_exp_f32_e32 v4, v4
	v_exp_f32_e32 v5, v3
	v_lshlrev_b32_e32 v8, 16, v11
	v_and_b32_e32 v11, 0xffff0000, v11
	v_pk_mul_f32 v[10:11], v[20:21], v[10:11] op_sel:[1,0] op_sel_hi:[0,1]
	v_pk_add_f32 v[4:5], v[4:5], 1.0 op_sel_hi:[1,0]
	v_pk_fma_f32 v[8:9], v[20:21], v[8:9], v[10:11]
	v_lshlrev_b32_e32 v6, 16, v7
	v_and_b32_e32 v7, 0xffff0000, v7
	v_pk_fma_f32 v[6:7], v[18:19], v[6:7], v[8:9] op_sel_hi:[0,1,1]
	s_nop 0
	v_rcp_f32_e32 v5, v5
	s_nop 0
	v_mul_f32_e32 v5, v13, v5
	s_nop 0
	v_rcp_f32_e32 v4, v4
	s_nop 0
	v_mul_f32_e32 v4, v12, v4
	v_pk_mul_f32 v[4:5], v[4:5], v[6:7]
	s_nop 0
	v_cvt_pk_bf16_f32 v3, v4, v5
	v_mad_i64_i32 v[4:5], s[0:1], v22, s37, v[16:17]
	v_lshl_add_u64 v[4:5], v[4:5], 0, v[184:185]
	v_add_co_u32_e32 v4, vcc, 0x2a40000, v4
	s_nop 1
	v_addc_co_u32_e32 v5, vcc, 0, v5, vcc
	v_cmp_eq_u32_e32 vcc, s6, v116
	global_store_dwordx4 v[4:5], v[0:3], off offset:512
	s_cbranch_vccz .LBB0_411
	s_branch .LBB0_345
